# non-temporal cache policy on the hgrn chunk-state stream (stage 1 stores, stage 2 loads and stores, stage 3 f32 loads)
# baseline (speedup 1.0000x reference)
.LBB0_431:
	s_ashr_i32 s21, s20, 31
	s_lshl_b64 s[0:1], s[20:21], 9
	v_readlane_b32 s4, v254, 46
	v_readlane_b32 s5, v254, 47
	s_add_u32 s0, s4, s0
	s_addc_u32 s1, s5, s1
	s_lshl_b32 s3, s33, 5
	s_and_b32 s3, s3, 0xc0
	s_lshl_b32 s4, s3, 1
	s_add_u32 s0, s0, s4
	s_addc_u32 s1, s1, 0
	v_ashrrev_i32_e32 v35, 31, v34
	s_ashr_i32 s37, s36, 31
	v_lshl_add_u64 v[30:31], v[34:35], 1, s[0:1]
	s_lshl_b64 s[0:1], s[36:37], 9
	v_lshl_add_u64 v[2:3], v[30:31], 0, s[0:1]
	global_load_ushort v100, v[30:31], off
	s_lshl_b32 s0, s36, 1
	global_load_ushort v101, v[2:3], off
	s_ashr_i32 s1, s0, 31
	s_mul_i32 s90, s36, 15
	v_writelane_b32 v255, s0, 0
	s_ashr_i32 s91, s90, 31
	s_mul_i32 s12, s36, 21
	v_writelane_b32 v255, s1, 1
	s_lshl_b64 s[0:1], s[0:1], 9
	v_lshl_add_u64 v[4:5], v[30:31], 0, s[0:1]
	s_mul_i32 s0, s36, 3
	s_ashr_i32 s1, s0, 31
	v_writelane_b32 v255, s0, 2
	s_ashr_i32 s13, s12, 31
	s_mul_i32 s34, s36, 22
	v_writelane_b32 v255, s1, 3
	s_lshl_b64 s[0:1], s[0:1], 9
	s_ashr_i32 s35, s34, 31
	s_mul_i32 s28, s36, 23
	s_ashr_i32 s29, s28, 31
	s_mul_i32 s14, s36, 24
	s_ashr_i32 s15, s14, 31
	s_mul_i32 s96, s36, 25
	s_ashr_i32 s97, s96, 31
	s_mul_i32 s52, s36, 26
	s_ashr_i32 s53, s52, 31
	s_mul_i32 s16, s36, 27
	s_ashr_i32 s17, s16, 31
	s_mul_i32 s4, s36, 28
	s_ashr_i32 s5, s4, 31
	s_mul_i32 s92, s36, 29
	s_ashr_i32 s93, s92, 31
	s_mul_i32 s38, s36, 30
	s_ashr_i32 s39, s38, 31
	s_mul_i32 s18, s36, 31
	s_ashr_i32 s19, s18, 31
	s_lshl_b32 s22, s36, 5
	s_ashr_i32 s23, s22, 31
	s_mul_i32 s24, s36, 33
	s_ashr_i32 s25, s24, 31
	s_mul_i32 s30, s36, 34
	s_ashr_i32 s31, s30, 31
	s_mul_i32 s6, s36, 35
	s_ashr_i32 s7, s6, 31
	s_mul_i32 s72, s36, 36
	s_ashr_i32 s73, s72, 31
	s_mul_i32 s74, s36, 37
	s_ashr_i32 s75, s74, 31
	s_mul_i32 s26, s36, 38
	s_ashr_i32 s27, s26, 31
	s_mul_i32 s84, s36, 39
	s_ashr_i32 s85, s84, 31
	s_mul_i32 s8, s36, 40
	s_ashr_i32 s9, s8, 31
	s_mul_i32 s94, s36, 41
	s_ashr_i32 s95, s94, 31
	s_mul_i32 s82, s36, 42
	s_ashr_i32 s83, s82, 31
	s_mul_i32 s86, s36, 43
	s_ashr_i32 s87, s86, 31
	s_mul_i32 s78, s36, 44
	s_ashr_i32 s79, s78, 31
	s_mul_i32 s80, s36, 45
	s_ashr_i32 s81, s80, 31
	s_mul_i32 s42, s36, 47
	s_ashr_i32 s43, s42, 31
	s_lshl_b64 s[20:21], s[20:21], 10
	v_and_b32_e32 v46, 31, v34
	v_bfe_u32 v79, v34, 4, 1
	v_and_b32_e32 v48, 15, v34
	v_or_b32_e32 v67, 32, v46
	v_lshrrev_b32_e32 v80, 4, v67
	global_load_ushort v102, v[4:5], off
	v_lshl_add_u64 v[4:5], v[30:31], 0, s[0:1]
	global_load_ushort v103, v[4:5], off
	s_lshl_b32 s0, s36, 2
	s_ashr_i32 s1, s0, 31
	v_writelane_b32 v255, s0, 4
	v_writelane_b32 v255, s1, 5
	s_lshl_b64 s[0:1], s[0:1], 9
	v_lshl_add_u64 v[4:5], v[30:31], 0, s[0:1]
	s_mul_i32 s0, s36, 5
	s_ashr_i32 s1, s0, 31
	v_writelane_b32 v255, s0, 6
	global_load_ushort v104, v[4:5], off
	s_nop 0
	v_writelane_b32 v255, s1, 7
	s_lshl_b64 s[0:1], s[0:1], 9
	v_lshl_add_u64 v[4:5], v[30:31], 0, s[0:1]
	global_load_ushort v105, v[4:5], off
	s_mul_i32 s0, s36, 6
	s_ashr_i32 s1, s0, 31
	v_writelane_b32 v255, s0, 8
	v_writelane_b32 v255, s1, 9
	s_lshl_b64 s[0:1], s[0:1], 9
	v_lshl_add_u64 v[6:7], v[30:31], 0, s[0:1]
	s_mul_i32 s0, s36, 7
	s_ashr_i32 s1, s0, 31
	v_writelane_b32 v255, s0, 10
	global_load_ushort v106, v[6:7], off
	s_nop 0
	v_writelane_b32 v255, s1, 11
	s_lshl_b64 s[0:1], s[0:1], 9
	v_lshl_add_u64 v[6:7], v[30:31], 0, s[0:1]
	global_load_ushort v107, v[6:7], off
	s_lshl_b32 s0, s36, 3
	s_ashr_i32 s1, s0, 31
	v_writelane_b32 v255, s0, 12
	v_writelane_b32 v255, s1, 13
	s_lshl_b64 s[0:1], s[0:1], 9
	v_lshl_add_u64 v[6:7], v[30:31], 0, s[0:1]
	s_mul_i32 s0, s36, 9
	s_ashr_i32 s1, s0, 31
	v_writelane_b32 v255, s0, 14
	global_load_ushort v108, v[6:7], off
	s_nop 0
	v_writelane_b32 v255, s1, 15
	s_lshl_b64 s[0:1], s[0:1], 9
	v_lshl_add_u64 v[6:7], v[30:31], 0, s[0:1]
	global_load_ushort v109, v[6:7], off
	s_mul_i32 s0, s36, 10
	s_ashr_i32 s1, s0, 31
	v_writelane_b32 v255, s0, 16
	v_writelane_b32 v255, s1, 17
	s_lshl_b64 s[0:1], s[0:1], 9
	v_lshl_add_u64 v[8:9], v[30:31], 0, s[0:1]
	s_mul_i32 s0, s36, 11
	s_ashr_i32 s1, s0, 31
	v_writelane_b32 v255, s0, 18
	global_load_ushort v110, v[8:9], off
	s_nop 0
	v_writelane_b32 v255, s1, 19
	s_lshl_b64 s[0:1], s[0:1], 9
	v_lshl_add_u64 v[8:9], v[30:31], 0, s[0:1]
	global_load_ushort v111, v[8:9], off
	s_mul_i32 s0, s36, 12
	s_ashr_i32 s1, s0, 31
	v_writelane_b32 v255, s0, 20
	v_writelane_b32 v255, s1, 21
	s_lshl_b64 s[0:1], s[0:1], 9
	v_lshl_add_u64 v[8:9], v[30:31], 0, s[0:1]
	s_mul_i32 s0, s36, 13
	s_ashr_i32 s1, s0, 31
	v_writelane_b32 v255, s0, 22
	global_load_ushort v112, v[8:9], off
	s_nop 0
	v_writelane_b32 v255, s1, 23
	s_lshl_b64 s[0:1], s[0:1], 9
	v_lshl_add_u64 v[8:9], v[30:31], 0, s[0:1]
	global_load_ushort v113, v[8:9], off
	s_mul_i32 s0, s36, 14
	s_ashr_i32 s1, s0, 31
	v_writelane_b32 v255, s0, 24
	v_writelane_b32 v255, s1, 25
	s_lshl_b64 s[0:1], s[0:1], 9
	v_lshl_add_u64 v[10:11], v[30:31], 0, s[0:1]
	s_lshl_b64 s[0:1], s[90:91], 9
	global_load_ushort v114, v[10:11], off
	v_lshl_add_u64 v[10:11], v[30:31], 0, s[0:1]
	global_load_ushort v115, v[10:11], off
	s_lshl_b32 s0, s36, 4
	s_ashr_i32 s1, s0, 31
	v_writelane_b32 v255, s0, 26
	v_writelane_b32 v255, s1, 27
	s_lshl_b64 s[0:1], s[0:1], 9
	v_lshl_add_u64 v[10:11], v[30:31], 0, s[0:1]
	s_mul_i32 s0, s36, 17
	s_ashr_i32 s1, s0, 31
	v_writelane_b32 v255, s0, 28
	global_load_ushort v116, v[10:11], off
	s_nop 0
	v_writelane_b32 v255, s1, 29
	s_lshl_b64 s[0:1], s[0:1], 9
	v_lshl_add_u64 v[10:11], v[30:31], 0, s[0:1]
	global_load_ushort v117, v[10:11], off
	s_mul_i32 s0, s36, 18
	s_ashr_i32 s1, s0, 31
	v_writelane_b32 v255, s0, 30
	v_writelane_b32 v255, s1, 31
	s_lshl_b64 s[0:1], s[0:1], 9
	v_lshl_add_u64 v[12:13], v[30:31], 0, s[0:1]
	s_mul_i32 s0, s36, 19
	s_ashr_i32 s1, s0, 31
	v_writelane_b32 v255, s0, 32
	global_load_ushort v118, v[12:13], off
	s_nop 0
	v_writelane_b32 v255, s1, 33
	s_lshl_b64 s[0:1], s[0:1], 9
	v_lshl_add_u64 v[12:13], v[30:31], 0, s[0:1]
	global_load_ushort v119, v[12:13], off
	s_mul_i32 s0, s36, 20
	s_ashr_i32 s1, s0, 31
	v_writelane_b32 v255, s0, 34
	v_writelane_b32 v255, s1, 35
	s_lshl_b64 s[0:1], s[0:1], 9
	v_lshl_add_u64 v[12:13], v[30:31], 0, s[0:1]
	s_lshl_b64 s[0:1], s[12:13], 9
	global_load_ushort v120, v[12:13], off
	v_lshl_add_u64 v[12:13], v[30:31], 0, s[0:1]
	global_load_ushort v121, v[12:13], off
	s_lshl_b64 s[0:1], s[34:35], 9
	v_lshl_add_u64 v[14:15], v[30:31], 0, s[0:1]
	s_lshl_b64 s[0:1], s[28:29], 9
	global_load_ushort v122, v[14:15], off
	v_lshl_add_u64 v[14:15], v[30:31], 0, s[0:1]
	global_load_ushort v123, v[14:15], off
	s_lshl_b64 s[0:1], s[14:15], 9
	v_lshl_add_u64 v[14:15], v[30:31], 0, s[0:1]
	s_lshl_b64 s[0:1], s[96:97], 9
	global_load_ushort v124, v[14:15], off
	v_lshl_add_u64 v[14:15], v[30:31], 0, s[0:1]
	global_load_ushort v125, v[14:15], off
	s_lshl_b64 s[0:1], s[52:53], 9
	v_lshl_add_u64 v[16:17], v[30:31], 0, s[0:1]
	s_lshl_b64 s[0:1], s[16:17], 9
	global_load_ushort v126, v[16:17], off
	v_lshl_add_u64 v[16:17], v[30:31], 0, s[0:1]
	global_load_ushort v127, v[16:17], off
	s_lshl_b64 s[0:1], s[4:5], 9
	v_lshl_add_u64 v[16:17], v[30:31], 0, s[0:1]
	s_lshl_b64 s[0:1], s[92:93], 9
	global_load_ushort v128, v[16:17], off
	v_lshl_add_u64 v[16:17], v[30:31], 0, s[0:1]
	global_load_ushort v129, v[16:17], off
	s_lshl_b64 s[0:1], s[38:39], 9
	v_lshl_add_u64 v[18:19], v[30:31], 0, s[0:1]
	s_lshl_b64 s[0:1], s[18:19], 9
	global_load_ushort v130, v[18:19], off
	v_lshl_add_u64 v[18:19], v[30:31], 0, s[0:1]
	global_load_ushort v131, v[18:19], off
	s_lshl_b64 s[0:1], s[22:23], 9
	v_lshl_add_u64 v[18:19], v[30:31], 0, s[0:1]
	s_lshl_b64 s[0:1], s[24:25], 9
	global_load_ushort v132, v[18:19], off
	v_lshl_add_u64 v[18:19], v[30:31], 0, s[0:1]
	global_load_ushort v133, v[18:19], off
	s_lshl_b64 s[0:1], s[30:31], 9
	v_lshl_add_u64 v[20:21], v[30:31], 0, s[0:1]
	s_lshl_b64 s[0:1], s[6:7], 9
	global_load_ushort v134, v[20:21], off
	v_lshl_add_u64 v[20:21], v[30:31], 0, s[0:1]
	global_load_ushort v135, v[20:21], off
	s_lshl_b64 s[0:1], s[72:73], 9
	v_lshl_add_u64 v[20:21], v[30:31], 0, s[0:1]
	s_lshl_b64 s[0:1], s[74:75], 9
	global_load_ushort v136, v[20:21], off
	v_lshl_add_u64 v[20:21], v[30:31], 0, s[0:1]
	global_load_ushort v137, v[20:21], off
	s_lshl_b64 s[0:1], s[26:27], 9
	v_lshl_add_u64 v[22:23], v[30:31], 0, s[0:1]
	s_lshl_b64 s[0:1], s[84:85], 9
	global_load_ushort v138, v[22:23], off
	v_lshl_add_u64 v[22:23], v[30:31], 0, s[0:1]
	global_load_ushort v139, v[22:23], off
	s_lshl_b64 s[0:1], s[8:9], 9
	v_lshl_add_u64 v[22:23], v[30:31], 0, s[0:1]
	s_lshl_b64 s[0:1], s[94:95], 9
	global_load_ushort v140, v[22:23], off
	v_lshl_add_u64 v[22:23], v[30:31], 0, s[0:1]
	global_load_ushort v141, v[22:23], off
	s_lshl_b64 s[0:1], s[82:83], 9
	v_lshl_add_u64 v[24:25], v[30:31], 0, s[0:1]
	s_lshl_b64 s[0:1], s[86:87], 9
	global_load_ushort v142, v[24:25], off
	v_lshl_add_u64 v[24:25], v[30:31], 0, s[0:1]
	global_load_ushort v143, v[24:25], off
	s_lshl_b64 s[0:1], s[78:79], 9
	v_lshl_add_u64 v[24:25], v[30:31], 0, s[0:1]
	s_lshl_b64 s[0:1], s[80:81], 9
	global_load_ushort v144, v[24:25], off
	v_lshl_add_u64 v[24:25], v[30:31], 0, s[0:1]
	global_load_ushort v145, v[24:25], off
	s_mul_i32 s0, s36, 46
	s_ashr_i32 s1, s0, 31
	s_lshl_b64 s[10:11], s[0:1], 9
	v_lshl_add_u64 v[26:27], v[30:31], 0, s[10:11]
	s_lshl_b64 s[10:11], s[42:43], 9
	global_load_ushort v146, v[26:27], off
	v_lshl_add_u64 v[26:27], v[30:31], 0, s[10:11]
	global_load_ushort v147, v[26:27], off
	s_mul_i32 s10, s36, 48
	s_ashr_i32 s11, s10, 31
	s_lshl_b64 s[40:41], s[10:11], 9
	v_lshl_add_u64 v[26:27], v[30:31], 0, s[40:41]
	s_mul_i32 s40, s36, 49
	s_ashr_i32 s41, s40, 31
	s_lshl_b64 s[44:45], s[40:41], 9
	global_load_ushort v148, v[26:27], off
	v_lshl_add_u64 v[26:27], v[30:31], 0, s[44:45]
	global_load_ushort v149, v[26:27], off
	s_mul_i32 s44, s36, 50
	s_ashr_i32 s45, s44, 31
	s_lshl_b64 s[46:47], s[44:45], 9
	v_lshl_add_u64 v[28:29], v[30:31], 0, s[46:47]
	s_mul_i32 s46, s36, 51
	s_ashr_i32 s47, s46, 31
	s_lshl_b64 s[48:49], s[46:47], 9
	global_load_ushort v150, v[28:29], off
	v_lshl_add_u64 v[28:29], v[30:31], 0, s[48:49]
	global_load_ushort v151, v[28:29], off
	s_mul_i32 s48, s36, 52
	s_ashr_i32 s49, s48, 31
	s_lshl_b64 s[50:51], s[48:49], 9
	v_lshl_add_u64 v[28:29], v[30:31], 0, s[50:51]
	s_mul_i32 s50, s36, 53
	s_ashr_i32 s51, s50, 31
	s_lshl_b64 s[54:55], s[50:51], 9
	global_load_ushort v152, v[28:29], off
	v_lshl_add_u64 v[28:29], v[30:31], 0, s[54:55]
	global_load_ushort v153, v[28:29], off
	s_mul_i32 s54, s36, 54
	s_ashr_i32 s55, s54, 31
	s_lshl_b64 s[56:57], s[54:55], 9
	v_lshl_add_u64 v[32:33], v[30:31], 0, s[56:57]
	s_mul_i32 s56, s36, 55
	s_ashr_i32 s57, s56, 31
	s_lshl_b64 s[58:59], s[56:57], 9
	global_load_ushort v154, v[32:33], off
	v_lshl_add_u64 v[32:33], v[30:31], 0, s[58:59]
	global_load_ushort v155, v[32:33], off
	s_mul_i32 s58, s36, 56
	s_ashr_i32 s59, s58, 31
	s_lshl_b64 s[60:61], s[58:59], 9
	v_lshl_add_u64 v[32:33], v[30:31], 0, s[60:61]
	s_mul_i32 s60, s36, 57
	s_ashr_i32 s61, s60, 31
	s_lshl_b64 s[62:63], s[60:61], 9
	global_load_ushort v156, v[32:33], off
	v_lshl_add_u64 v[32:33], v[30:31], 0, s[62:63]
	global_load_ushort v157, v[32:33], off
	s_mul_i32 s62, s36, 58
	s_ashr_i32 s63, s62, 31
	s_lshl_b64 s[64:65], s[62:63], 9
	v_lshl_add_u64 v[32:33], v[30:31], 0, s[64:65]
	s_mul_i32 s64, s36, 59
	s_ashr_i32 s65, s64, 31
	s_lshl_b64 s[66:67], s[64:65], 9
	global_load_ushort v158, v[32:33], off
	v_lshl_add_u64 v[32:33], v[30:31], 0, s[66:67]
	global_load_ushort v159, v[32:33], off
	s_mul_i32 s66, s36, 60
	s_ashr_i32 s67, s66, 31
	s_lshl_b64 s[68:69], s[66:67], 9
	v_lshl_add_u64 v[32:33], v[30:31], 0, s[68:69]
	s_mul_i32 s68, s36, 61
	s_ashr_i32 s69, s68, 31
	s_lshl_b64 s[70:71], s[68:69], 9
	global_load_ushort v160, v[32:33], off
	v_lshl_add_u64 v[32:33], v[30:31], 0, s[70:71]
	global_load_ushort v161, v[32:33], off
	s_mul_i32 s70, s36, 62
	s_ashr_i32 s71, s70, 31
	s_lshl_b64 s[76:77], s[70:71], 9
	v_lshl_add_u64 v[32:33], v[30:31], 0, s[76:77]
	s_mul_i32 s76, s36, 63
	s_ashr_i32 s77, s76, 31
	s_lshl_b64 vcc, s[76:77], 9
	v_lshl_add_u64 v[30:31], v[30:31], 0, vcc
	global_load_ushort v162, v[32:33], off
	s_movk_i32 vcc_lo, 0x90
	global_load_ushort v163, v[30:31], off
	s_add_u32 s20, s88, s20
	s_addc_u32 s21, s89, s21
	s_lshl_b32 s3, s3, 2
	s_add_u32 s20, s20, s3
	s_addc_u32 s21, s21, 0
	s_lshl_b64 s[6:7], s[6:7], 10
	s_lshl_b64 s[0:1], s[0:1], 10
	s_ashr_i32 s3, s2, 31
	s_waitcnt vmcnt(0)
	v_lshl_or_b32 v2, v101, 16, v100
	v_lshl_or_b32 v3, v103, 16, v102
	v_lshl_or_b32 v4, v105, 16, v104
	v_lshl_or_b32 v5, v107, 16, v106
	v_lshl_or_b32 v6, v109, 16, v108
	v_lshl_or_b32 v7, v111, 16, v110
	v_lshl_or_b32 v8, v113, 16, v112
	v_lshl_or_b32 v9, v115, 16, v114
	v_lshl_or_b32 v10, v117, 16, v116
	v_lshl_or_b32 v11, v119, 16, v118
	v_lshl_or_b32 v12, v121, 16, v120
	v_lshl_or_b32 v13, v123, 16, v122
	v_lshl_or_b32 v14, v125, 16, v124
	v_lshl_or_b32 v15, v127, 16, v126
	v_lshl_or_b32 v16, v129, 16, v128
	v_lshl_or_b32 v17, v131, 16, v130
	v_lshl_or_b32 v18, v133, 16, v132
	v_lshl_or_b32 v19, v135, 16, v134
	v_lshl_or_b32 v20, v137, 16, v136
	v_lshl_or_b32 v21, v139, 16, v138
	v_lshl_or_b32 v22, v141, 16, v140
	v_lshl_or_b32 v23, v143, 16, v142
	v_lshl_or_b32 v24, v145, 16, v144
	v_lshl_or_b32 v25, v147, 16, v146
	v_lshl_or_b32 v26, v149, 16, v148
	v_lshl_or_b32 v27, v151, 16, v150
	v_lshl_or_b32 v28, v153, 16, v152
	v_lshl_or_b32 v29, v155, 16, v154
	v_lshl_or_b32 v36, v157, 16, v156
	v_lshl_or_b32 v37, v159, 16, v158
	v_lshl_or_b32 v38, v161, 16, v160
	v_lshl_or_b32 v39, v163, 16, v162
	v_mul_lo_u32 v0, v34, vcc_lo
	v_readlane_b32 vcc_lo, v254, 58
	s_nop 1
	v_add_u32_e32 v0, vcc_lo, v0
	ds_write_b128 v0, v[2:5] offset:9216
	ds_write_b128 v0, v[6:9] offset:9232
	ds_write_b128 v0, v[10:13] offset:9248
	ds_write_b128 v0, v[14:17] offset:9264
	ds_write_b128 v0, v[18:21] offset:9280
	ds_write_b128 v0, v[22:25] offset:9296
	ds_write_b128 v0, v[26:29] offset:9312
	ds_write_b128 v0, v[36:39] offset:9328
	v_lshlrev_b64 v[2:3], 2, v[34:35]
	v_lshl_add_u64 v[6:7], s[20:21], 0, v[2:3]
	s_lshl_b64 s[20:21], s[22:23], 10
	v_lshl_add_u64 v[4:5], v[6:7], 0, s[20:21]
	s_lshl_b64 s[20:21], s[24:25], 10
	v_lshl_add_u64 v[8:9], v[6:7], 0, s[20:21]
	s_lshl_b64 s[20:21], s[30:31], 10
	global_load_dword v4, v[4:5], off
	v_lshl_add_u64 v[10:11], v[6:7], 0, s[6:7]
	global_load_dword v5, v[8:9], off
	v_lshl_add_u64 v[8:9], v[6:7], 0, s[20:21]
	s_lshl_b64 s[6:7], s[72:73], 10
	global_load_dword v8, v[8:9], off
	s_mov_b32 s72, 0xa000
	global_load_dword v9, v[10:11], off
	v_lshl_add_u64 v[10:11], v[6:7], 0, s[6:7]
	s_lshl_b64 s[6:7], s[74:75], 10
	v_lshl_add_u64 v[12:13], v[6:7], 0, s[6:7]
	s_lshl_b64 s[6:7], s[26:27], 10
	global_load_dword v10, v[10:11], off
	s_mov_b32 s73, 0x1e000
	global_load_dword v11, v[12:13], off
	v_lshl_add_u64 v[12:13], v[6:7], 0, s[6:7]
	s_lshl_b64 s[6:7], s[84:85], 10
	v_lshl_add_u64 v[14:15], v[6:7], 0, s[6:7]
	s_lshl_b64 s[6:7], s[8:9], 10
	global_load_dword v12, v[12:13], off
	v_readlane_b32 s84, v253, 61
	global_load_dword v13, v[14:15], off
	v_lshl_add_u64 v[14:15], v[6:7], 0, s[6:7]
	s_lshl_b64 s[6:7], s[94:95], 10
	v_lshl_add_u64 v[16:17], v[6:7], 0, s[6:7]
	s_lshl_b64 s[6:7], s[82:83], 10
	global_load_dword v14, v[14:15], off
	v_readlane_b32 s82, v253, 58
	global_load_dword v15, v[16:17], off
	v_lshl_add_u64 v[16:17], v[6:7], 0, s[6:7]
	s_lshl_b64 s[6:7], s[86:87], 10
	v_lshl_add_u64 v[18:19], v[6:7], 0, s[6:7]
	s_lshl_b64 s[6:7], s[78:79], 10
	global_load_dword v16, v[16:17], off
	v_readlane_b32 s78, v253, 55
	global_load_dword v17, v[18:19], off
	v_lshl_add_u64 v[18:19], v[6:7], 0, s[6:7]
	s_lshl_b64 s[6:7], s[80:81], 10
	v_lshl_add_u64 v[20:21], v[6:7], 0, s[6:7]
	global_load_dword v18, v[18:19], off
	v_readlane_b32 s7, v254, 54
	global_load_dword v19, v[20:21], off
	v_lshl_add_u64 v[20:21], v[6:7], 0, s[0:1]
	s_lshl_b64 s[0:1], s[42:43], 10
	v_lshl_add_u64 v[22:23], v[6:7], 0, s[0:1]
	s_lshl_b64 s[0:1], s[10:11], 10
	global_load_dword v20, v[20:21], off
	v_readlane_b32 s80, v253, 56
	global_load_dword v21, v[22:23], off
	v_lshl_add_u64 v[22:23], v[6:7], 0, s[0:1]
	s_lshl_b64 s[0:1], s[40:41], 10
	v_lshl_add_u64 v[24:25], v[6:7], 0, s[0:1]
	s_lshl_b64 s[0:1], s[44:45], 10
	global_load_dword v22, v[22:23], off
	v_readlane_b32 s81, v253, 57
	global_load_dword v23, v[24:25], off
	v_lshl_add_u64 v[24:25], v[6:7], 0, s[0:1]
	s_lshl_b64 s[0:1], s[46:47], 10
	v_lshl_add_u64 v[26:27], v[6:7], 0, s[0:1]
	s_lshl_b64 s[0:1], s[48:49], 10
	global_load_dword v24, v[24:25], off
	v_readlane_b32 s42, v254, 31
	global_load_dword v25, v[26:27], off
	v_lshl_add_u64 v[26:27], v[6:7], 0, s[0:1]
	s_lshl_b64 s[0:1], s[50:51], 10
	v_lshl_add_u64 v[28:29], v[6:7], 0, s[0:1]
	s_lshl_b64 s[0:1], s[54:55], 10
	global_load_dword v26, v[26:27], off
	v_readlane_b32 s54, v254, 12
	global_load_dword v27, v[28:29], off
	v_lshl_add_u64 v[28:29], v[6:7], 0, s[0:1]
	s_lshl_b64 s[0:1], s[56:57], 10
	v_lshl_add_u64 v[30:31], v[6:7], 0, s[0:1]
	s_lshl_b64 s[0:1], s[58:59], 10
	global_load_dword v28, v[28:29], off
	v_readlane_b32 s83, v253, 59
	global_load_dword v29, v[30:31], off
	v_lshl_add_u64 v[30:31], v[6:7], 0, s[0:1]
	s_lshl_b64 s[0:1], s[60:61], 10
	v_lshl_add_u64 v[32:33], v[6:7], 0, s[0:1]
	s_lshl_b64 s[0:1], s[62:63], 10
	global_load_dword v30, v[30:31], off
	v_readlane_b32 s79, v253, 60
	global_load_dword v31, v[32:33], off
	v_lshl_add_u64 v[32:33], v[6:7], 0, s[0:1]
	s_lshl_b64 s[0:1], s[64:65], 10
	v_lshl_add_u64 v[36:37], v[6:7], 0, s[0:1]
	s_lshl_b64 s[0:1], s[66:67], 10
	global_load_dword v32, v[32:33], off
	v_readlane_b32 s85, v253, 62
	global_load_dword v33, v[36:37], off
	v_lshl_add_u64 v[36:37], v[6:7], 0, s[0:1]
	s_lshl_b64 s[0:1], s[68:69], 10
	v_lshl_add_u64 v[38:39], v[6:7], 0, s[0:1]
	s_lshl_b64 s[0:1], s[70:71], 10
	global_load_dword v36, v[36:37], off
	v_readlane_b32 s86, v253, 63
	global_load_dword v37, v[38:39], off
	v_lshl_add_u64 v[38:39], v[6:7], 0, s[0:1]
	s_lshl_b64 s[0:1], s[76:77], 10
	global_load_dword v35, v[38:39], off
	v_lshl_add_u64 v[38:39], v[6:7], 0, s[0:1]
	global_load_dword v38, v[38:39], off
	s_lshl_b64 s[0:1], s[36:37], 10
	v_readlane_b32 s36, v254, 56
	v_readlane_b32 s37, v254, 57
	s_movk_i32 s81, 0x4000
	s_movk_i32 s87, 0x3000
	s_mov_b32 s94, 0x10000
	s_movk_i32 s95, 0x6000
	s_mov_b32 s74, 0xc000
	s_mov_b32 s75, 0xe000
	s_mov_b32 s10, 0xca01000
	s_mov_b32 s11, 0xeb01000
	s_mov_b32 s77, 0x42000
	s_mov_b32 s20, 0x4a000
	s_mov_b32 s21, 0x52000
	s_mov_b32 s76, 0x5a000
	s_mov_b32 s24, 0x63000
	s_mov_b32 s31, 0xa5000
	s_movk_i32 s46, 0xffd0
	s_movk_i32 s50, 0xffc0
	s_mov_b32 s51, 0x41000000
	s_mov_b64 s[48:49], 0xca00100
	v_readlane_b32 s43, v254, 32
	v_readlane_b32 s55, v254, 13
	s_waitcnt vmcnt(2)
	v_pk_add_f32 v[40:41], v[36:37], 1.0 op_sel_hi:[1,0] neg_lo:[1,0] neg_hi:[1,0]
	s_waitcnt vmcnt(1)
	v_sub_f32_e32 v39, 1.0, v35
	s_waitcnt vmcnt(0)
	v_mul_f32_e32 v45, v38, v39
	v_mul_f32_e32 v39, v35, v38
	v_sub_f32_e32 v44, 1.0, v38
	v_mul_f32_e32 v38, v37, v39
	v_mul_f32_e32 v37, v36, v38
	v_mul_f32_e32 v36, v33, v37
	v_pk_mul_f32 v[40:41], v[40:41], v[38:39]
	v_pk_add_f32 v[38:39], v[32:33], 1.0 op_sel_hi:[1,0] neg_lo:[1,0] neg_hi:[1,0]
	v_mul_f32_e32 v33, v32, v36
	v_mul_f32_e32 v32, v31, v33
	v_pk_mul_f32 v[38:39], v[38:39], v[36:37]
	v_pk_add_f32 v[36:37], v[30:31], 1.0 op_sel_hi:[1,0] neg_lo:[1,0] neg_hi:[1,0]
	v_mul_f32_e32 v31, v30, v32
	v_mul_f32_e32 v30, v29, v31
	v_pk_mul_f32 v[36:37], v[36:37], v[32:33]
	v_pk_add_f32 v[32:33], v[28:29], 1.0 op_sel_hi:[1,0] neg_lo:[1,0] neg_hi:[1,0]
	v_mul_f32_e32 v29, v28, v30
	v_mul_f32_e32 v28, v27, v29
	v_pk_mul_f32 v[32:33], v[32:33], v[30:31]
	v_pk_add_f32 v[30:31], v[26:27], 1.0 op_sel_hi:[1,0] neg_lo:[1,0] neg_hi:[1,0]
	v_mul_f32_e32 v27, v26, v28
	v_mul_f32_e32 v26, v25, v27
	v_pk_mul_f32 v[30:31], v[30:31], v[28:29]
	v_pk_add_f32 v[28:29], v[24:25], 1.0 op_sel_hi:[1,0] neg_lo:[1,0] neg_hi:[1,0]
	v_mul_f32_e32 v25, v24, v26
	v_mul_f32_e32 v24, v23, v25
	v_pk_mul_f32 v[28:29], v[28:29], v[26:27]
	v_pk_add_f32 v[26:27], v[22:23], 1.0 op_sel_hi:[1,0] neg_lo:[1,0] neg_hi:[1,0]
	v_mul_f32_e32 v23, v22, v24
	v_mul_f32_e32 v22, v21, v23
	v_pk_mul_f32 v[26:27], v[26:27], v[24:25]
	v_pk_add_f32 v[24:25], v[20:21], 1.0 op_sel_hi:[1,0] neg_lo:[1,0] neg_hi:[1,0]
	v_mul_f32_e32 v21, v20, v22
	v_mul_f32_e32 v20, v19, v21
	v_pk_mul_f32 v[24:25], v[24:25], v[22:23]
	v_pk_add_f32 v[22:23], v[18:19], 1.0 op_sel_hi:[1,0] neg_lo:[1,0] neg_hi:[1,0]
	v_mul_f32_e32 v19, v18, v20
	v_mul_f32_e32 v18, v17, v19
	v_pk_mul_f32 v[22:23], v[22:23], v[20:21]
	v_pk_add_f32 v[20:21], v[16:17], 1.0 op_sel_hi:[1,0] neg_lo:[1,0] neg_hi:[1,0]
	v_mul_f32_e32 v17, v16, v18
	v_mul_f32_e32 v16, v15, v17
	v_pk_mul_f32 v[20:21], v[20:21], v[18:19]
	v_pk_add_f32 v[18:19], v[14:15], 1.0 op_sel_hi:[1,0] neg_lo:[1,0] neg_hi:[1,0]
	v_mul_f32_e32 v15, v14, v16
	v_mul_f32_e32 v14, v13, v15
	v_pk_mul_f32 v[18:19], v[18:19], v[16:17]
	v_pk_add_f32 v[16:17], v[12:13], 1.0 op_sel_hi:[1,0] neg_lo:[1,0] neg_hi:[1,0]
	v_mul_f32_e32 v13, v12, v14
	v_mul_f32_e32 v12, v11, v13
	v_pk_mul_f32 v[42:43], v[16:17], v[14:15]
	v_pk_add_f32 v[14:15], v[10:11], 1.0 op_sel_hi:[1,0] neg_lo:[1,0] neg_hi:[1,0]
	v_mul_f32_e32 v11, v10, v12
	v_mul_f32_e32 v10, v9, v11
	v_mul_f32_e32 v17, v8, v10
	v_pk_mul_f32 v[14:15], v[14:15], v[12:13]
	v_pk_add_f32 v[12:13], v[8:9], 1.0 op_sel_hi:[1,0] neg_lo:[1,0] neg_hi:[1,0]
	v_mul_f32_e32 v16, v5, v17
	v_pk_add_f32 v[8:9], v[4:5], 1.0 op_sel_hi:[1,0] neg_lo:[1,0] neg_hi:[1,0]
	v_pk_mul_f32 v[12:13], v[12:13], v[10:11]
	v_pk_mul_f32 v[8:9], v[8:9], v[16:17]
	v_cvt_pk_bf16_f32 v10, v14, v15
	v_cvt_pk_bf16_f32 v8, v8, v9
	v_cvt_pk_bf16_f32 v9, v12, v13
	v_cvt_pk_bf16_f32 v11, v42, v43
	ds_write_b128 v0, v[8:11] offset:64
	v_cvt_pk_bf16_f32 v8, v18, v19
	v_cvt_pk_bf16_f32 v9, v20, v21
	v_cvt_pk_bf16_f32 v10, v22, v23
	v_cvt_pk_bf16_f32 v11, v24, v25
	ds_write_b128 v0, v[8:11] offset:80
	v_cvt_pk_bf16_f32 v8, v26, v27
	v_cvt_pk_bf16_f32 v9, v28, v29
	v_cvt_pk_bf16_f32 v10, v30, v31
	v_cvt_pk_bf16_f32 v11, v32, v33
	ds_write_b128 v0, v[8:11] offset:96
	v_cvt_pk_bf16_f32 v8, v36, v37
	v_cvt_pk_bf16_f32 v9, v38, v39
	v_cvt_pk_bf16_f32 v10, v40, v41
	v_cvt_pk_bf16_f32 v11, v45, v44
	ds_write_b128 v0, v[8:11] offset:112
	v_lshl_add_u64 v[10:11], v[6:7], 0, s[0:1]
	v_readlane_b32 s0, v255, 0
	v_readlane_b32 s1, v255, 1
	s_lshl_b64 s[0:1], s[0:1], 10
	global_load_dword v8, v[6:7], off
	global_load_dword v9, v[10:11], off
	v_lshl_add_u64 v[10:11], v[6:7], 0, s[0:1]
	v_readlane_b32 s0, v255, 2
	v_readlane_b32 s1, v255, 3
	s_lshl_b64 s[0:1], s[0:1], 10
	global_load_dword v10, v[10:11], off
	v_lshl_add_u64 v[12:13], v[6:7], 0, s[0:1]
	v_readlane_b32 s0, v255, 4
	v_readlane_b32 s1, v255, 5
	s_lshl_b64 s[0:1], s[0:1], 10
	global_load_dword v11, v[12:13], off
	v_lshl_add_u64 v[12:13], v[6:7], 0, s[0:1]
	v_readlane_b32 s0, v255, 6
	v_readlane_b32 s1, v255, 7
	s_lshl_b64 s[0:1], s[0:1], 10
	global_load_dword v12, v[12:13], off
	v_lshl_add_u64 v[14:15], v[6:7], 0, s[0:1]
	v_readlane_b32 s0, v255, 8
	v_readlane_b32 s1, v255, 9
	s_lshl_b64 s[0:1], s[0:1], 10
	global_load_dword v13, v[14:15], off
	v_lshl_add_u64 v[14:15], v[6:7], 0, s[0:1]
	v_readlane_b32 s0, v255, 10
	v_readlane_b32 s1, v255, 11
	s_lshl_b64 s[0:1], s[0:1], 10
	global_load_dword v14, v[14:15], off
	v_lshl_add_u64 v[18:19], v[6:7], 0, s[0:1]
	v_readlane_b32 s0, v255, 12
	v_readlane_b32 s1, v255, 13
	s_lshl_b64 s[0:1], s[0:1], 10
	global_load_dword v15, v[18:19], off
	v_lshl_add_u64 v[18:19], v[6:7], 0, s[0:1]
	v_readlane_b32 s0, v255, 14
	v_readlane_b32 s1, v255, 15
	s_lshl_b64 s[0:1], s[0:1], 10
	global_load_dword v18, v[18:19], off
	v_lshl_add_u64 v[20:21], v[6:7], 0, s[0:1]
	v_readlane_b32 s0, v255, 16
	v_readlane_b32 s1, v255, 17
	s_lshl_b64 s[0:1], s[0:1], 10
	global_load_dword v19, v[20:21], off
	v_lshl_add_u64 v[20:21], v[6:7], 0, s[0:1]
	v_readlane_b32 s0, v255, 18
	v_readlane_b32 s1, v255, 19
	s_lshl_b64 s[0:1], s[0:1], 10
	global_load_dword v20, v[20:21], off
	v_lshl_add_u64 v[22:23], v[6:7], 0, s[0:1]
	v_readlane_b32 s0, v255, 20
	v_readlane_b32 s1, v255, 21
	s_lshl_b64 s[0:1], s[0:1], 10
	global_load_dword v21, v[22:23], off
	v_lshl_add_u64 v[22:23], v[6:7], 0, s[0:1]
	v_readlane_b32 s0, v255, 22
	v_readlane_b32 s1, v255, 23
	s_lshl_b64 s[0:1], s[0:1], 10
	global_load_dword v22, v[22:23], off
	v_lshl_add_u64 v[24:25], v[6:7], 0, s[0:1]
	v_readlane_b32 s0, v255, 24
	v_readlane_b32 s1, v255, 25
	s_lshl_b64 s[0:1], s[0:1], 10
	global_load_dword v23, v[24:25], off
	v_lshl_add_u64 v[24:25], v[6:7], 0, s[0:1]
	s_lshl_b64 s[0:1], s[90:91], 10
	v_lshl_add_u64 v[26:27], v[6:7], 0, s[0:1]
	v_readlane_b32 s0, v255, 26
	v_readlane_b32 s1, v255, 27
	s_lshl_b64 s[0:1], s[0:1], 10
	global_load_dword v24, v[24:25], off
	v_mul_f32_e32 v5, v4, v16
	global_load_dword v25, v[26:27], off
	v_lshl_add_u64 v[26:27], v[6:7], 0, s[0:1]
	v_readlane_b32 s0, v255, 28
	v_readlane_b32 s1, v255, 29
	s_lshl_b64 s[0:1], s[0:1], 10
	global_load_dword v26, v[26:27], off
	v_lshl_add_u64 v[28:29], v[6:7], 0, s[0:1]
	v_readlane_b32 s0, v255, 30
	v_readlane_b32 s1, v255, 31
	s_lshl_b64 s[0:1], s[0:1], 10
	global_load_dword v27, v[28:29], off
	v_lshl_add_u64 v[28:29], v[6:7], 0, s[0:1]
	v_readlane_b32 s0, v255, 32
	v_readlane_b32 s1, v255, 33
	s_lshl_b64 s[0:1], s[0:1], 10
	global_load_dword v28, v[28:29], off
	v_lshl_add_u64 v[30:31], v[6:7], 0, s[0:1]
	v_readlane_b32 s0, v255, 34
	v_readlane_b32 s1, v255, 35
	s_lshl_b64 s[0:1], s[0:1], 10
	global_load_dword v29, v[30:31], off
	v_lshl_add_u64 v[30:31], v[6:7], 0, s[0:1]
	s_lshl_b64 s[0:1], s[12:13], 10
	v_lshl_add_u64 v[32:33], v[6:7], 0, s[0:1]
	s_lshl_b64 s[0:1], s[34:35], 10
	global_load_dword v30, v[30:31], off
	s_movk_i32 s90, 0x1800
	global_load_dword v31, v[32:33], off
	v_lshl_add_u64 v[32:33], v[6:7], 0, s[0:1]
	s_lshl_b64 s[0:1], s[28:29], 10
	v_lshl_add_u64 v[36:37], v[6:7], 0, s[0:1]
	s_lshl_b64 s[0:1], s[14:15], 10
	global_load_dword v32, v[32:33], off
	s_movk_i32 s14, 0x90
	global_load_dword v33, v[36:37], off
	v_lshl_add_u64 v[36:37], v[6:7], 0, s[0:1]
	s_lshl_b64 s[0:1], s[96:97], 10
	v_lshl_add_u64 v[38:39], v[6:7], 0, s[0:1]
	s_lshl_b64 s[0:1], s[52:53], 10
	global_load_dword v36, v[36:37], off
	s_mov_b32 s91, 0x12000
	global_load_dword v37, v[38:39], off
	v_lshl_add_u64 v[38:39], v[6:7], 0, s[0:1]
	s_lshl_b64 s[0:1], s[16:17], 10
	v_lshl_add_u64 v[40:41], v[6:7], 0, s[0:1]
	s_lshl_b64 s[0:1], s[4:5], 10
	global_load_dword v38, v[38:39], off
	v_readlane_b32 s4, v254, 63
	global_load_dword v39, v[40:41], off
	v_lshl_add_u64 v[40:41], v[6:7], 0, s[0:1]
	s_lshl_b64 s[0:1], s[92:93], 10
	v_lshl_add_u64 v[42:43], v[6:7], 0, s[0:1]
	s_lshl_b64 s[0:1], s[38:39], 10
	global_load_dword v40, v[40:41], off
	s_movk_i32 s92, 0x5000
	global_load_dword v41, v[42:43], off
	v_lshl_add_u64 v[42:43], v[6:7], 0, s[0:1]
	s_lshl_b64 s[0:1], s[18:19], 10
	v_lshl_add_u64 v[6:7], v[6:7], 0, s[0:1]
	global_load_dword v42, v[42:43], off
	s_lshl_b64 s[0:1], s[2:3], 8
	global_load_dword v43, v[6:7], off
	v_readlane_b32 s3, v254, 59
	s_add_u32 s0, s3, s0
	v_readlane_b32 s3, v254, 60
	s_addc_u32 s1, s3, s1
	v_lshl_add_u64 v[2:3], s[0:1], 0, v[2:3]
	v_readlane_b32 s0, v254, 52
	s_ashr_i32 s3, s0, 31
	s_mul_hi_i32 s1, s33, 0x2100
	s_add_u32 s0, s4, s0
	s_addc_u32 s1, s1, s3
	s_lshl_b64 s[0:1], s[0:1], 8
	s_add_u32 s0, s36, s0
	s_addc_u32 s1, s37, s1
	s_movk_i32 s93, 0x2000
	s_mov_b32 s96, 0x18000
	s_mov_b32 s97, 0x8000
	s_movk_i32 s15, 0x1000
	s_mov_b32 s16, 0x21000
	s_mov_b32 s17, 0x29000
	s_mov_b32 s18, 0x31000
	s_mov_b32 s19, 0x39000
	s_mov_b32 s33, 0xad000
	s_mov_b32 s34, 0xb5000
	s_mov_b32 s35, 0xbd000
	s_mov_b32 s38, 0xc6000
	s_mov_b32 s39, 0xce000
	s_mov_b32 s52, 0xd6000
	s_mov_b32 s53, 0xde000
	s_waitcnt vmcnt(0)
	v_mul_f32_e32 v4, v5, v43
	v_pk_add_f32 v[6:7], v[42:43], 1.0 op_sel_hi:[1,0] neg_lo:[1,0] neg_hi:[1,0]
	s_nop 0
	v_pk_mul_f32 v[16:17], v[6:7], v[4:5]
	v_mul_f32_e32 v5, v42, v4
	v_mul_f32_e32 v4, v41, v5
	v_pk_add_f32 v[6:7], v[40:41], 1.0 op_sel_hi:[1,0] neg_lo:[1,0] neg_hi:[1,0]
	s_nop 0
	v_pk_mul_f32 v[42:43], v[6:7], v[4:5]
	v_mul_f32_e32 v5, v40, v4
	v_mul_f32_e32 v4, v39, v5
	v_pk_add_f32 v[6:7], v[38:39], 1.0 op_sel_hi:[1,0] neg_lo:[1,0] neg_hi:[1,0]
	s_nop 0
	v_pk_mul_f32 v[40:41], v[6:7], v[4:5]
	v_mul_f32_e32 v5, v38, v4
	v_mul_f32_e32 v4, v37, v5
	v_pk_add_f32 v[6:7], v[36:37], 1.0 op_sel_hi:[1,0] neg_lo:[1,0] neg_hi:[1,0]
	s_nop 0
	v_pk_mul_f32 v[38:39], v[6:7], v[4:5]
	v_mul_f32_e32 v5, v36, v4
	v_mul_f32_e32 v4, v33, v5
	v_pk_add_f32 v[6:7], v[32:33], 1.0 op_sel_hi:[1,0] neg_lo:[1,0] neg_hi:[1,0]
	s_nop 0
	v_pk_mul_f32 v[36:37], v[6:7], v[4:5]
	v_mul_f32_e32 v5, v32, v4
	v_mul_f32_e32 v4, v31, v5
	v_pk_add_f32 v[6:7], v[30:31], 1.0 op_sel_hi:[1,0] neg_lo:[1,0] neg_hi:[1,0]
	s_nop 0
	v_pk_mul_f32 v[32:33], v[6:7], v[4:5]
	v_mul_f32_e32 v5, v30, v4
	v_mul_f32_e32 v4, v29, v5
	v_pk_add_f32 v[6:7], v[28:29], 1.0 op_sel_hi:[1,0] neg_lo:[1,0] neg_hi:[1,0]
	s_nop 0
	v_pk_mul_f32 v[30:31], v[6:7], v[4:5]
	v_mul_f32_e32 v5, v28, v4
	v_mul_f32_e32 v4, v27, v5
	v_pk_add_f32 v[6:7], v[26:27], 1.0 op_sel_hi:[1,0] neg_lo:[1,0] neg_hi:[1,0]
	s_nop 0
	v_pk_mul_f32 v[28:29], v[6:7], v[4:5]
	v_mul_f32_e32 v5, v26, v4
	v_mul_f32_e32 v4, v25, v5
	v_pk_add_f32 v[6:7], v[24:25], 1.0 op_sel_hi:[1,0] neg_lo:[1,0] neg_hi:[1,0]
	s_nop 0
	v_pk_mul_f32 v[26:27], v[6:7], v[4:5]
	v_mul_f32_e32 v5, v24, v4
	v_mul_f32_e32 v4, v23, v5
	v_pk_add_f32 v[6:7], v[22:23], 1.0 op_sel_hi:[1,0] neg_lo:[1,0] neg_hi:[1,0]
	s_nop 0
	v_pk_mul_f32 v[24:25], v[6:7], v[4:5]
	v_mul_f32_e32 v5, v22, v4
	v_mul_f32_e32 v4, v21, v5
	v_pk_add_f32 v[6:7], v[20:21], 1.0 op_sel_hi:[1,0] neg_lo:[1,0] neg_hi:[1,0]
	s_nop 0
	v_pk_mul_f32 v[22:23], v[6:7], v[4:5]
	v_mul_f32_e32 v5, v20, v4
	v_mul_f32_e32 v4, v19, v5
	v_pk_add_f32 v[6:7], v[18:19], 1.0 op_sel_hi:[1,0] neg_lo:[1,0] neg_hi:[1,0]
	s_nop 0
	v_pk_mul_f32 v[20:21], v[6:7], v[4:5]
	v_mul_f32_e32 v5, v18, v4
	v_mul_f32_e32 v4, v15, v5
	v_pk_add_f32 v[6:7], v[14:15], 1.0 op_sel_hi:[1,0] neg_lo:[1,0] neg_hi:[1,0]
	s_nop 0
	v_pk_mul_f32 v[18:19], v[6:7], v[4:5]
	v_mul_f32_e32 v5, v14, v4
	v_mul_f32_e32 v4, v13, v5
	v_pk_add_f32 v[6:7], v[12:13], 1.0 op_sel_hi:[1,0] neg_lo:[1,0] neg_hi:[1,0]
	s_nop 0
	v_pk_mul_f32 v[6:7], v[6:7], v[4:5]
	v_mul_f32_e32 v5, v12, v4
	v_mul_f32_e32 v4, v11, v5
	v_pk_add_f32 v[12:13], v[10:11], 1.0 op_sel_hi:[1,0] neg_lo:[1,0] neg_hi:[1,0]
	v_mul_f32_e32 v11, v10, v4
	v_pk_mul_f32 v[12:13], v[12:13], v[4:5]
	v_mul_f32_e32 v10, v9, v11
	v_pk_add_f32 v[4:5], v[8:9], 1.0 op_sel_hi:[1,0] neg_lo:[1,0] neg_hi:[1,0]
	v_cvt_pk_bf16_f32 v6, v6, v7
	v_pk_mul_f32 v[4:5], v[4:5], v[10:11]
	v_cvt_pk_bf16_f32 v7, v18, v19
	v_cvt_pk_bf16_f32 v4, v4, v5
	v_cvt_pk_bf16_f32 v5, v12, v13
	ds_write_b128 v0, v[4:7]
	v_cvt_pk_bf16_f32 v4, v20, v21
	v_cvt_pk_bf16_f32 v5, v22, v23
	v_cvt_pk_bf16_f32 v6, v24, v25
	v_cvt_pk_bf16_f32 v7, v26, v27
	ds_write_b128 v0, v[4:7] offset:16
	v_cvt_pk_bf16_f32 v4, v28, v29
	v_cvt_pk_bf16_f32 v5, v30, v31
	v_cvt_pk_bf16_f32 v6, v32, v33
	v_cvt_pk_bf16_f32 v7, v36, v37
	ds_write_b128 v0, v[4:7] offset:32
	v_cvt_pk_bf16_f32 v4, v38, v39
	v_cvt_pk_bf16_f32 v5, v40, v41
	v_cvt_pk_bf16_f32 v6, v42, v43
	v_cvt_pk_bf16_f32 v7, v16, v17
	ds_write_b128 v0, v[4:7] offset:48
	v_mul_f32_e32 v0, v8, v10
	v_ashrrev_i32_e32 v4, 5, v34
	global_store_dword v[2:3], v0, off nt
	v_lshlrev_b32_e32 v0, 4, v4
	v_add_u32_e32 v47, vcc_lo, v0
	v_mad_u32_u24 v18, v46, s14, v47
	ds_read_b128 v[22:25], v18 offset:9216
	ds_read_b128 v[42:45], v18
	ds_read_b128 v[38:41], v18 offset:32
	v_lshlrev_b32_e32 v78, 2, v4
	s_waitcnt lgkmcnt(1)
	v_mfma_f32_32x32x16_bf16 v[2:17], v[42:45], v[22:25], 0
	ds_read_b128 v[26:29], v18 offset:9248
	ds_read_b128 v[54:57], v18 offset:64
	ds_read_b128 v[30:33], v18 offset:9280
	ds_read_b128 v[50:53], v18 offset:96
	ds_read_b128 v[18:21], v18 offset:9312
	v_and_b32_e32 v66, 48, v0
	v_or_b32_e32 v0, v66, v79
	v_mul_u32_u24_e32 v0, 0x2100, v0
	v_and_b32_e32 v34, -16, v78
	s_waitcnt lgkmcnt(4)
	v_mfma_f32_32x32x16_bf16 v[2:17], v[38:41], v[26:29], v[2:17]
	v_ashrrev_i32_e32 v35, 31, v34
	v_lshlrev_b32_e32 v0, 2, v0
	v_lshl_add_u64 v[36:37], s[0:1], 0, v[0:1]
	v_lshlrev_b64 v[72:73], 2, v[34:35]
	v_lshl_add_u64 v[34:35], v[36:37], 0, v[72:73]
	v_lshlrev_b32_e32 v0, 2, v48
	v_lshl_add_u64 v[58:59], v[34:35], 0, v[0:1]
	s_waitcnt lgkmcnt(2)
	v_mfma_f32_32x32x16_bf16 v[2:17], v[54:57], v[30:33], v[2:17]
	v_or_b32_e32 v68, 4, v66
	v_mov_b32_e32 v35, v1
	v_or_b32_e32 v70, 8, v66
	v_or_b32_e32 v81, 12, v66
	v_mad_u32_u24 v90, v67, s14, v47
	s_waitcnt lgkmcnt(0)
	v_mfma_f32_32x32x16_bf16 v[2:17], v[50:53], v[18:21], v[2:17]
	s_nop 11
	global_store_dword v[58:59], v2, off nt
	v_or_b32_e32 v2, v68, v79
	v_mul_u32_u24_e32 v2, 0x2100, v2
	v_lshlrev_b32_e32 v34, 2, v2
	v_lshl_add_u64 v[34:35], s[0:1], 0, v[34:35]
	v_lshl_add_u64 v[34:35], v[34:35], 0, v[72:73]
	v_or_b32_e32 v2, v70, v79
	v_lshl_add_u64 v[60:61], v[34:35], 0, v[0:1]
	v_mul_u32_u24_e32 v2, 0x2100, v2
	global_store_dword v[60:61], v3, off nt
	v_lshlrev_b32_e32 v2, 2, v2
	v_mov_b32_e32 v3, v1
	v_lshl_add_u64 v[2:3], s[0:1], 0, v[2:3]
	v_lshl_add_u64 v[2:3], v[2:3], 0, v[72:73]
	v_lshl_add_u64 v[62:63], v[2:3], 0, v[0:1]
	v_or_b32_e32 v2, v81, v79
	v_mul_u32_u24_e32 v2, 0x2100, v2
	v_lshlrev_b32_e32 v2, 2, v2
	v_mov_b32_e32 v3, v1
	v_lshl_add_u64 v[2:3], s[0:1], 0, v[2:3]
	v_lshl_add_u64 v[2:3], v[2:3], 0, v[72:73]
	v_lshl_add_u64 v[64:65], v[2:3], 0, v[0:1]
	v_add_u32_e32 v2, 8, v78
	v_lshlrev_b32_e32 v3, 2, v2
	v_and_b32_e32 v82, 48, v3
	v_or_b32_e32 v3, v82, v79
	global_store_dword v[62:63], v4, off nt
	v_mul_u32_u24_e32 v4, 0x2100, v3
	v_and_b32_e32 v2, -16, v2
	global_store_dword v[64:65], v5, off nt
	v_ashrrev_i32_e32 v3, 31, v2
	v_lshlrev_b32_e32 v4, 2, v4
	v_mov_b32_e32 v5, v1
	v_lshl_add_u64 v[4:5], s[0:1], 0, v[4:5]
	v_lshlrev_b64 v[74:75], 2, v[2:3]
	v_lshl_add_u64 v[2:3], v[4:5], 0, v[74:75]
	v_lshl_add_u64 v[2:3], v[2:3], 0, v[0:1]
	v_or_b32_e32 v83, 4, v82
	global_store_dword v[2:3], v6, off nt
	v_or_b32_e32 v2, v83, v79
	v_mul_u32_u24_e32 v2, 0x2100, v2
	v_lshlrev_b32_e32 v2, 2, v2
	v_mov_b32_e32 v3, v1
	v_lshl_add_u64 v[2:3], s[0:1], 0, v[2:3]
	v_lshl_add_u64 v[2:3], v[2:3], 0, v[74:75]
	v_lshl_add_u64 v[2:3], v[2:3], 0, v[0:1]
	v_or_b32_e32 v84, 8, v82
	global_store_dword v[2:3], v7, off nt
	v_or_b32_e32 v2, v84, v79
	v_mul_u32_u24_e32 v2, 0x2100, v2
	v_lshlrev_b32_e32 v2, 2, v2
	v_mov_b32_e32 v3, v1
	v_lshl_add_u64 v[2:3], s[0:1], 0, v[2:3]
	v_lshl_add_u64 v[2:3], v[2:3], 0, v[74:75]
	v_lshl_add_u64 v[2:3], v[2:3], 0, v[0:1]
	v_or_b32_e32 v85, 12, v82
	global_store_dword v[2:3], v8, off nt
	v_or_b32_e32 v2, v85, v79
	v_mul_u32_u24_e32 v2, 0x2100, v2
	v_lshlrev_b32_e32 v2, 2, v2
	v_mov_b32_e32 v3, v1
	v_lshl_add_u64 v[2:3], s[0:1], 0, v[2:3]
	v_lshl_add_u64 v[2:3], v[2:3], 0, v[74:75]
	v_lshl_add_u64 v[2:3], v[2:3], 0, v[0:1]
	global_store_dword v[2:3], v9, off nt
	global_store_dword v[58:59], v10, off offset:64 nt
	global_store_dword v[60:61], v11, off offset:64 nt
	global_store_dword v[62:63], v12, off offset:64 nt
	global_store_dword v[64:65], v13, off offset:64 nt
	v_add_u32_e32 v2, 24, v78
	v_lshlrev_b32_e32 v3, 2, v2
	v_and_b32_e32 v86, 48, v3
	v_or_b32_e32 v3, v86, v79
	v_mul_u32_u24_e32 v4, 0x2100, v3
	v_and_b32_e32 v2, -16, v2
	v_ashrrev_i32_e32 v3, 31, v2
	v_lshlrev_b32_e32 v4, 2, v4
	v_mov_b32_e32 v5, v1
	v_lshl_add_u64 v[4:5], s[0:1], 0, v[4:5]
	v_lshlrev_b64 v[76:77], 2, v[2:3]
	v_lshl_add_u64 v[2:3], v[4:5], 0, v[76:77]
	v_lshl_add_u64 v[2:3], v[2:3], 0, v[0:1]
	v_or_b32_e32 v87, 4, v86
	global_store_dword v[2:3], v14, off nt
	v_or_b32_e32 v2, v87, v79
	v_mul_u32_u24_e32 v2, 0x2100, v2
	v_lshlrev_b32_e32 v2, 2, v2
	v_mov_b32_e32 v3, v1
	v_lshl_add_u64 v[2:3], s[0:1], 0, v[2:3]
	v_lshl_add_u64 v[2:3], v[2:3], 0, v[76:77]
	v_lshl_add_u64 v[2:3], v[2:3], 0, v[0:1]
	v_or_b32_e32 v88, 8, v86
	global_store_dword v[2:3], v15, off nt
	v_or_b32_e32 v2, v88, v79
	v_mul_u32_u24_e32 v2, 0x2100, v2
	v_lshlrev_b32_e32 v2, 2, v2
	v_mov_b32_e32 v3, v1
	v_lshl_add_u64 v[2:3], s[0:1], 0, v[2:3]
	v_lshl_add_u64 v[2:3], v[2:3], 0, v[76:77]
	v_lshl_add_u64 v[2:3], v[2:3], 0, v[0:1]
	v_or_b32_e32 v89, 12, v86
	global_store_dword v[2:3], v16, off nt
	v_or_b32_e32 v2, v89, v79
	v_mul_u32_u24_e32 v2, 0x2100, v2
	v_lshlrev_b32_e32 v2, 2, v2
	v_mov_b32_e32 v3, v1
	v_lshl_add_u64 v[2:3], s[0:1], 0, v[2:3]
	v_lshl_add_u64 v[2:3], v[2:3], 0, v[76:77]
	v_lshl_add_u64 v[2:3], v[2:3], 0, v[0:1]
	global_store_dword v[2:3], v17, off nt
	ds_read_b128 v[46:49], v90 offset:9216
	ds_read_b128 v[34:37], v90 offset:9248
	s_waitcnt lgkmcnt(1)
	v_mfma_f32_32x32x16_bf16 v[2:17], v[42:45], v[46:49], 0
	ds_read_b128 v[42:45], v90 offset:9280
	s_waitcnt lgkmcnt(1)
	v_mfma_f32_32x32x16_bf16 v[2:17], v[38:41], v[34:37], v[2:17]
	ds_read_b128 v[38:41], v90 offset:9312
	s_waitcnt lgkmcnt(1)
	v_mfma_f32_32x32x16_bf16 v[2:17], v[54:57], v[42:45], v[2:17]
	s_waitcnt lgkmcnt(0)
	v_mfma_f32_32x32x16_bf16 v[2:17], v[50:53], v[38:41], v[2:17]
	v_or_b32_e32 v50, v66, v80
	v_mul_u32_u24_e32 v50, 0x2100, v50
	v_lshlrev_b32_e32 v50, 2, v50
	v_mov_b32_e32 v51, v1
	v_lshl_add_u64 v[50:51], s[0:1], 0, v[50:51]
	v_lshl_add_u64 v[50:51], v[50:51], 0, v[72:73]
	v_lshl_add_u64 v[66:67], v[50:51], 0, v[0:1]
	s_nop 4
	global_store_dword v[66:67], v2, off nt
	v_or_b32_e32 v2, v68, v80
	v_mul_u32_u24_e32 v2, 0x2100, v2
	v_lshlrev_b32_e32 v50, 2, v2
	v_mov_b32_e32 v51, v1
	v_lshl_add_u64 v[50:51], s[0:1], 0, v[50:51]
	v_lshl_add_u64 v[50:51], v[50:51], 0, v[72:73]
	v_or_b32_e32 v2, v70, v80
	v_lshl_add_u64 v[68:69], v[50:51], 0, v[0:1]
	v_mul_u32_u24_e32 v2, 0x2100, v2
	global_store_dword v[68:69], v3, off nt
	v_lshlrev_b32_e32 v2, 2, v2
	v_mov_b32_e32 v3, v1
	v_lshl_add_u64 v[2:3], s[0:1], 0, v[2:3]
	v_lshl_add_u64 v[2:3], v[2:3], 0, v[72:73]
	v_lshl_add_u64 v[70:71], v[2:3], 0, v[0:1]
	v_or_b32_e32 v2, v81, v80
	v_mul_u32_u24_e32 v2, 0x2100, v2
	v_lshlrev_b32_e32 v2, 2, v2
	v_mov_b32_e32 v3, v1
	v_lshl_add_u64 v[2:3], s[0:1], 0, v[2:3]
	v_lshl_add_u64 v[2:3], v[2:3], 0, v[72:73]
	v_lshl_add_u64 v[72:73], v[2:3], 0, v[0:1]
	v_or_b32_e32 v2, v82, v80
	v_mul_u32_u24_e32 v2, 0x2100, v2
	v_lshlrev_b32_e32 v2, 2, v2
	v_mov_b32_e32 v3, v1
	v_lshl_add_u64 v[2:3], s[0:1], 0, v[2:3]
	v_lshl_add_u64 v[2:3], v[2:3], 0, v[74:75]
	v_lshl_add_u64 v[2:3], v[2:3], 0, v[0:1]
	global_store_dword v[70:71], v4, off nt
	global_store_dword v[72:73], v5, off nt
	global_store_dword v[2:3], v6, off nt
	v_or_b32_e32 v2, v83, v80
	v_mul_u32_u24_e32 v2, 0x2100, v2
	v_lshlrev_b32_e32 v2, 2, v2
	v_mov_b32_e32 v3, v1
	v_lshl_add_u64 v[2:3], s[0:1], 0, v[2:3]
	v_lshl_add_u64 v[2:3], v[2:3], 0, v[74:75]
	v_lshl_add_u64 v[2:3], v[2:3], 0, v[0:1]
	global_store_dword v[2:3], v7, off nt
	v_or_b32_e32 v2, v84, v80
	v_mul_u32_u24_e32 v2, 0x2100, v2
	v_lshlrev_b32_e32 v2, 2, v2
	v_mov_b32_e32 v3, v1
	v_lshl_add_u64 v[2:3], s[0:1], 0, v[2:3]
	v_lshl_add_u64 v[2:3], v[2:3], 0, v[74:75]
	v_lshl_add_u64 v[2:3], v[2:3], 0, v[0:1]
	global_store_dword v[2:3], v8, off nt
	v_or_b32_e32 v2, v85, v80
	v_mul_u32_u24_e32 v2, 0x2100, v2
	v_lshlrev_b32_e32 v2, 2, v2
	v_mov_b32_e32 v3, v1
	v_lshl_add_u64 v[2:3], s[0:1], 0, v[2:3]
	v_lshl_add_u64 v[2:3], v[2:3], 0, v[74:75]
	v_lshl_add_u64 v[2:3], v[2:3], 0, v[0:1]
	global_store_dword v[2:3], v9, off nt
	global_store_dword v[66:67], v10, off offset:64 nt
	global_store_dword v[68:69], v11, off offset:64 nt
	global_store_dword v[70:71], v12, off offset:64 nt
	global_store_dword v[72:73], v13, off offset:64 nt
	v_or_b32_e32 v2, v86, v80
	v_mul_u32_u24_e32 v2, 0x2100, v2
	v_lshlrev_b32_e32 v2, 2, v2
	v_mov_b32_e32 v3, v1
	v_lshl_add_u64 v[2:3], s[0:1], 0, v[2:3]
	v_lshl_add_u64 v[2:3], v[2:3], 0, v[76:77]
	v_lshl_add_u64 v[2:3], v[2:3], 0, v[0:1]
	global_store_dword v[2:3], v14, off nt
	v_or_b32_e32 v2, v87, v80
	v_mul_u32_u24_e32 v2, 0x2100, v2
	v_lshlrev_b32_e32 v2, 2, v2
	v_mov_b32_e32 v3, v1
	v_lshl_add_u64 v[2:3], s[0:1], 0, v[2:3]
	v_lshl_add_u64 v[2:3], v[2:3], 0, v[76:77]
	v_lshl_add_u64 v[2:3], v[2:3], 0, v[0:1]
	global_store_dword v[2:3], v15, off nt
	v_or_b32_e32 v2, v88, v80
	v_mul_u32_u24_e32 v2, 0x2100, v2
	v_lshlrev_b32_e32 v2, 2, v2
	v_mov_b32_e32 v3, v1
	v_lshl_add_u64 v[2:3], s[0:1], 0, v[2:3]
	v_lshl_add_u64 v[2:3], v[2:3], 0, v[76:77]
	v_lshl_add_u64 v[2:3], v[2:3], 0, v[0:1]
	global_store_dword v[2:3], v16, off nt
	v_or_b32_e32 v2, v89, v80
	v_mul_u32_u24_e32 v2, 0x2100, v2
	v_lshlrev_b32_e32 v2, 2, v2
	v_mov_b32_e32 v3, v1
	v_lshl_add_u64 v[2:3], s[0:1], 0, v[2:3]
	v_lshl_add_u64 v[2:3], v[2:3], 0, v[76:77]
	v_lshl_add_u64 v[2:3], v[2:3], 0, v[0:1]
	global_store_dword v[2:3], v17, off nt
	ds_read_b128 v[54:57], v90
	ds_read_b128 v[50:53], v90 offset:32
	s_waitcnt lgkmcnt(1)
	v_mfma_f32_32x32x16_bf16 v[2:17], v[54:57], v[22:25], 0
	ds_read_b128 v[22:25], v90 offset:64
	s_waitcnt lgkmcnt(1)
	v_mfma_f32_32x32x16_bf16 v[2:17], v[50:53], v[26:29], v[2:17]
	ds_read_b128 v[26:29], v90 offset:96
	s_waitcnt lgkmcnt(1)
	v_mfma_f32_32x32x16_bf16 v[2:17], v[22:25], v[30:33], v[2:17]
	s_waitcnt lgkmcnt(0)
	v_mfma_f32_32x32x16_bf16 v[2:17], v[26:29], v[18:21], v[2:17]
	s_nop 11
	global_store_dword v[58:59], v2, off offset:128 nt
	global_store_dword v[60:61], v3, off offset:128 nt
	global_store_dword v[62:63], v4, off offset:128 nt
	global_store_dword v[64:65], v5, off offset:128 nt
	v_add_u32_e32 v2, 40, v78
	v_lshlrev_b32_e32 v3, 2, v2
	v_and_b32_e32 v30, 48, v3
	v_or_b32_e32 v3, v30, v79
	v_mul_u32_u24_e32 v4, 0x2100, v3
	v_and_b32_e32 v2, -16, v2
	v_ashrrev_i32_e32 v3, 31, v2
	v_lshlrev_b32_e32 v4, 2, v4
	v_mov_b32_e32 v5, v1
	v_lshl_add_u64 v[4:5], s[0:1], 0, v[4:5]
	v_lshlrev_b64 v[18:19], 2, v[2:3]
	v_lshl_add_u64 v[2:3], v[4:5], 0, v[18:19]
	v_lshl_add_u64 v[2:3], v[2:3], 0, v[0:1]
	v_or_b32_e32 v31, 4, v30
	global_store_dword v[2:3], v6, off nt
	v_or_b32_e32 v2, v31, v79
	v_mul_u32_u24_e32 v2, 0x2100, v2
	v_lshlrev_b32_e32 v2, 2, v2
	v_mov_b32_e32 v3, v1
	v_lshl_add_u64 v[2:3], s[0:1], 0, v[2:3]
	v_lshl_add_u64 v[2:3], v[2:3], 0, v[18:19]
	v_lshl_add_u64 v[2:3], v[2:3], 0, v[0:1]
	v_or_b32_e32 v32, 8, v30
	global_store_dword v[2:3], v7, off nt
	v_or_b32_e32 v2, v32, v79
	v_mul_u32_u24_e32 v2, 0x2100, v2
	v_lshlrev_b32_e32 v2, 2, v2
	v_mov_b32_e32 v3, v1
	v_lshl_add_u64 v[2:3], s[0:1], 0, v[2:3]
	v_lshl_add_u64 v[2:3], v[2:3], 0, v[18:19]
	v_lshl_add_u64 v[2:3], v[2:3], 0, v[0:1]
	v_or_b32_e32 v33, 12, v30
	global_store_dword v[2:3], v8, off nt
	v_or_b32_e32 v2, v33, v79
	v_mul_u32_u24_e32 v2, 0x2100, v2
	v_lshlrev_b32_e32 v2, 2, v2
	v_mov_b32_e32 v3, v1
	v_lshl_add_u64 v[2:3], s[0:1], 0, v[2:3]
	v_lshl_add_u64 v[2:3], v[2:3], 0, v[18:19]
	v_lshl_add_u64 v[2:3], v[2:3], 0, v[0:1]
	global_store_dword v[2:3], v9, off nt
	global_store_dword v[58:59], v10, off offset:192 nt
	global_store_dword v[60:61], v11, off offset:192 nt
	global_store_dword v[62:63], v12, off offset:192 nt
	global_store_dword v[64:65], v13, off offset:192 nt
	v_add_u32_e32 v2, 56, v78
	v_lshlrev_b32_e32 v3, 2, v2
	v_and_b32_e32 v58, 48, v3
	v_or_b32_e32 v3, v58, v79
	v_mul_u32_u24_e32 v4, 0x2100, v3
	v_and_b32_e32 v2, -16, v2
	v_ashrrev_i32_e32 v3, 31, v2
	v_lshlrev_b32_e32 v4, 2, v4
	v_mov_b32_e32 v5, v1
	v_lshl_add_u64 v[4:5], s[0:1], 0, v[4:5]
	v_lshlrev_b64 v[20:21], 2, v[2:3]
	v_lshl_add_u64 v[2:3], v[4:5], 0, v[20:21]
	v_lshl_add_u64 v[2:3], v[2:3], 0, v[0:1]
	v_or_b32_e32 v59, 4, v58
	global_store_dword v[2:3], v14, off nt
	v_or_b32_e32 v2, v59, v79
	v_mul_u32_u24_e32 v2, 0x2100, v2
	v_lshlrev_b32_e32 v2, 2, v2
	v_mov_b32_e32 v3, v1
	v_lshl_add_u64 v[2:3], s[0:1], 0, v[2:3]
	v_lshl_add_u64 v[2:3], v[2:3], 0, v[20:21]
	v_lshl_add_u64 v[2:3], v[2:3], 0, v[0:1]
	v_or_b32_e32 v60, 8, v58
	global_store_dword v[2:3], v15, off nt
	v_or_b32_e32 v2, v60, v79
	v_mul_u32_u24_e32 v2, 0x2100, v2
	v_lshlrev_b32_e32 v2, 2, v2
	v_mov_b32_e32 v3, v1
	v_lshl_add_u64 v[2:3], s[0:1], 0, v[2:3]
	v_lshl_add_u64 v[2:3], v[2:3], 0, v[20:21]
	v_lshl_add_u64 v[2:3], v[2:3], 0, v[0:1]
	v_or_b32_e32 v61, 12, v58
	global_store_dword v[2:3], v16, off nt
	v_or_b32_e32 v2, v61, v79
	v_mul_u32_u24_e32 v2, 0x2100, v2
	v_lshlrev_b32_e32 v2, 2, v2
	v_mov_b32_e32 v3, v1
	v_lshl_add_u64 v[2:3], s[0:1], 0, v[2:3]
	v_lshl_add_u64 v[2:3], v[2:3], 0, v[20:21]
	v_lshl_add_u64 v[2:3], v[2:3], 0, v[0:1]
	global_store_dword v[2:3], v17, off nt
	v_mfma_f32_32x32x16_bf16 v[2:17], v[54:57], v[46:49], 0
	v_mfma_f32_32x32x16_bf16 v[2:17], v[50:53], v[34:37], v[2:17]
	v_mfma_f32_32x32x16_bf16 v[2:17], v[22:25], v[42:45], v[2:17]
	v_mfma_f32_32x32x16_bf16 v[2:17], v[26:29], v[38:41], v[2:17]
	s_nop 11
	global_store_dword v[66:67], v2, off offset:128 nt
	global_store_dword v[68:69], v3, off offset:128 nt
	global_store_dword v[70:71], v4, off offset:128 nt
	global_store_dword v[72:73], v5, off offset:128 nt
	v_or_b32_e32 v2, v30, v80
	v_mul_u32_u24_e32 v2, 0x2100, v2
	v_lshlrev_b32_e32 v2, 2, v2
	v_mov_b32_e32 v3, v1
	v_lshl_add_u64 v[2:3], s[0:1], 0, v[2:3]
	v_lshl_add_u64 v[2:3], v[2:3], 0, v[18:19]
	v_lshl_add_u64 v[2:3], v[2:3], 0, v[0:1]
	global_store_dword v[2:3], v6, off nt
	v_or_b32_e32 v2, v31, v80
	v_mul_u32_u24_e32 v2, 0x2100, v2
	v_lshlrev_b32_e32 v2, 2, v2
	v_mov_b32_e32 v3, v1
	v_lshl_add_u64 v[2:3], s[0:1], 0, v[2:3]
	v_lshl_add_u64 v[2:3], v[2:3], 0, v[18:19]
	v_lshl_add_u64 v[2:3], v[2:3], 0, v[0:1]
	global_store_dword v[2:3], v7, off nt
	v_or_b32_e32 v2, v32, v80
	v_mul_u32_u24_e32 v2, 0x2100, v2
	v_lshlrev_b32_e32 v2, 2, v2
	v_mov_b32_e32 v3, v1
	v_lshl_add_u64 v[2:3], s[0:1], 0, v[2:3]
	v_lshl_add_u64 v[2:3], v[2:3], 0, v[18:19]
	v_lshl_add_u64 v[2:3], v[2:3], 0, v[0:1]
	global_store_dword v[2:3], v8, off nt
	v_or_b32_e32 v2, v33, v80
	v_mul_u32_u24_e32 v2, 0x2100, v2
	v_lshlrev_b32_e32 v2, 2, v2
	v_mov_b32_e32 v3, v1
	v_lshl_add_u64 v[2:3], s[0:1], 0, v[2:3]
	v_lshl_add_u64 v[2:3], v[2:3], 0, v[18:19]
	v_lshl_add_u64 v[2:3], v[2:3], 0, v[0:1]
	global_store_dword v[2:3], v9, off nt
	global_store_dword v[66:67], v10, off offset:192 nt
	global_store_dword v[68:69], v11, off offset:192 nt
	global_store_dword v[70:71], v12, off offset:192 nt
	global_store_dword v[72:73], v13, off offset:192 nt
	v_or_b32_e32 v2, v58, v80
	v_mul_u32_u24_e32 v2, 0x2100, v2
	v_lshlrev_b32_e32 v2, 2, v2
	v_mov_b32_e32 v3, v1
	v_lshl_add_u64 v[2:3], s[0:1], 0, v[2:3]
	v_lshl_add_u64 v[2:3], v[2:3], 0, v[20:21]
	v_lshl_add_u64 v[2:3], v[2:3], 0, v[0:1]
	global_store_dword v[2:3], v14, off nt
	v_or_b32_e32 v2, v59, v80
	v_mul_u32_u24_e32 v2, 0x2100, v2
	v_lshlrev_b32_e32 v2, 2, v2
	v_mov_b32_e32 v3, v1
	v_lshl_add_u64 v[2:3], s[0:1], 0, v[2:3]
	v_lshl_add_u64 v[2:3], v[2:3], 0, v[20:21]
	v_lshl_add_u64 v[2:3], v[2:3], 0, v[0:1]
	global_store_dword v[2:3], v15, off nt
	v_or_b32_e32 v2, v60, v80
	v_mul_u32_u24_e32 v2, 0x2100, v2
	v_lshlrev_b32_e32 v2, 2, v2
	v_mov_b32_e32 v3, v1
	v_lshl_add_u64 v[2:3], s[0:1], 0, v[2:3]
	v_lshl_add_u64 v[2:3], v[2:3], 0, v[20:21]
	v_lshl_add_u64 v[2:3], v[2:3], 0, v[0:1]
	global_store_dword v[2:3], v16, off nt
	v_or_b32_e32 v2, v61, v80
	v_mul_u32_u24_e32 v2, 0x2100, v2
	v_lshlrev_b32_e32 v2, 2, v2
	v_mov_b32_e32 v3, v1
	v_lshl_add_u64 v[2:3], s[0:1], 0, v[2:3]
	v_lshl_add_u64 v[2:3], v[2:3], 0, v[20:21]
	v_lshl_add_u64 v[2:3], v[2:3], 0, v[0:1]
	global_store_dword v[2:3], v17, off nt
	v_readlane_b32 s0, v252, 22
	s_waitcnt lgkmcnt(0)
	s_add_i32 s2, s2, s0
	v_readlane_b32 s0, v254, 61
	s_sub_i32 s7, s7, s0
	v_readlane_b32 s1, v254, 62
	s_cmp_ge_i32 s2, s1
	s_cbranch_scc1 .LBB0_443

.LBB0_466:
	v_readlane_b32 s56, v254, 8
	v_readlane_b32 s58, v254, 10
	v_readlane_b32 s59, v254, 11
	s_mov_b64 s[22:23], s[58:59]
	v_lshl_add_u64 v[10:11], s[22:23], 0, v[6:7]
	v_add_co_u32_e32 v106, vcc, 0xca00000, v10
	v_lshl_add_u64 v[14:15], s[22:23], 0, v[2:3]
	s_nop 0
	v_addc_co_u32_e32 v107, vcc, 0, v11, vcc
	v_add_co_u32_e32 v16, vcc, 0xeb00000, v14
	v_lshl_add_u64 v[12:13], s[22:23], 0, v[8:9]
	s_nop 0
	v_addc_co_u32_e32 v17, vcc, 0, v15, vcc
	v_add_co_u32_e32 v18, vcc, 0xca00000, v12
	v_lshl_add_u64 v[20:21], s[22:23], 0, v[4:5]
	s_nop 0
	v_addc_co_u32_e32 v19, vcc, 0, v13, vcc
	v_add_co_u32_e32 v22, vcc, 0xeb00000, v20
	v_readlane_b32 s57, v254, 9
	s_nop 0
	v_addc_co_u32_e32 v23, vcc, 0, v21, vcc
	global_load_dword v95, v[106:107], off nt
	global_load_dword v92, v[106:107], off offset:256 nt
	global_load_dword v88, v[106:107], off offset:512 nt
	global_load_dword v83, v[106:107], off offset:768 nt
	global_load_dword v77, v[106:107], off offset:1024 nt
	global_load_dword v72, v[106:107], off offset:1280 nt
	global_load_dword v66, v[106:107], off offset:1536 nt
	global_load_dword v62, v[106:107], off offset:1792 nt
	global_load_dword v104, v[16:17], off nt
	global_load_dword v101, v[16:17], off offset:256 nt
	global_load_dword v98, v[16:17], off offset:512 nt
	global_load_dword v94, v[16:17], off offset:768 nt
	global_load_dword v90, v[16:17], off offset:1024 nt
	global_load_dword v85, v[16:17], off offset:1280 nt
	global_load_dword v79, v[16:17], off offset:1536 nt
	global_load_dword v71, v[16:17], off offset:1792 nt
	global_load_dword v102, v[18:19], off nt
	global_load_dword v99, v[18:19], off offset:256 nt
	global_load_dword v96, v[18:19], off offset:512 nt
	global_load_dword v91, v[18:19], off offset:768 nt
	global_load_dword v86, v[18:19], off offset:1024 nt
	global_load_dword v80, v[18:19], off offset:1280 nt
	global_load_dword v73, v[18:19], off offset:1536 nt
	global_load_dword v67, v[18:19], off offset:1792 nt
	global_load_dword v105, v[22:23], off nt
	global_load_dword v103, v[22:23], off offset:256 nt
	global_load_dword v100, v[22:23], off offset:512 nt
	global_load_dword v97, v[22:23], off offset:768 nt
	global_load_dword v93, v[22:23], off offset:1024 nt
	global_load_dword v89, v[22:23], off offset:1280 nt
	global_load_dword v84, v[22:23], off offset:1536 nt
	global_load_dword v76, v[22:23], off offset:1792 nt
	global_load_dword v64, v[106:107], off offset:2048 nt
	global_load_dword v60, v[106:107], off offset:2304 nt
	global_load_dword v55, v[106:107], off offset:2560 nt
	global_load_dword v51, v[106:107], off offset:2816 nt
	global_load_dword v47, v[106:107], off offset:3072 nt
	global_load_dword v44, v[106:107], off offset:3328 nt
	global_load_dword v41, v[106:107], off offset:3584 nt
	global_load_dword v40, v[106:107], off offset:3840 nt
	global_load_dword v82, v[16:17], off offset:2048 nt
	global_load_dword v75, v[16:17], off offset:2304 nt
	global_load_dword v69, v[16:17], off offset:2560 nt
	global_load_dword v63, v[16:17], off offset:2816 nt
	global_load_dword v58, v[16:17], off offset:3072 nt
	global_load_dword v53, v[16:17], off offset:3328 nt
	global_load_dword v48, v[16:17], off offset:3584 nt
	global_load_dword v43, v[16:17], off offset:3840 nt
	global_load_dword v78, v[18:19], off offset:2048 nt
	global_load_dword v70, v[18:19], off offset:2304 nt
	global_load_dword v65, v[18:19], off offset:2560 nt
	global_load_dword v59, v[18:19], off offset:2816 nt
	global_load_dword v54, v[18:19], off offset:3072 nt
	global_load_dword v50, v[18:19], off offset:3328 nt
	global_load_dword v45, v[18:19], off offset:3584 nt
	global_load_dword v42, v[18:19], off offset:3840 nt
	global_load_dword v87, v[22:23], off offset:2048 nt
	global_load_dword v81, v[22:23], off offset:2304 nt
	global_load_dword v74, v[22:23], off offset:2560 nt
	global_load_dword v68, v[22:23], off offset:2816 nt
	global_load_dword v61, v[22:23], off offset:3072 nt
	global_load_dword v57, v[22:23], off offset:3328 nt
	global_load_dword v52, v[22:23], off offset:3584 nt
	global_load_dword v46, v[22:23], off offset:3840 nt
	v_add_co_u32_e32 v16, vcc, s10, v10
	s_nop 1
	v_addc_co_u32_e32 v17, vcc, 0, v11, vcc
	v_add_co_u32_e32 v108, vcc, s11, v14
	s_nop 1
	v_addc_co_u32_e32 v109, vcc, 0, v15, vcc
	v_add_co_u32_e32 v110, vcc, s10, v12
	s_nop 1
	v_addc_co_u32_e32 v111, vcc, 0, v13, vcc
	v_add_co_u32_e32 v112, vcc, s11, v20
	s_nop 1
	v_addc_co_u32_e32 v113, vcc, 0, v21, vcc
	global_load_dword v34, v[16:17], off nt
	global_load_dword v49, v[108:109], off nt
	global_load_dword v30, v[16:17], off offset:256 nt
	global_load_dword v32, v[108:109], off offset:256 nt
	global_load_dword v26, v[16:17], off offset:512 nt
	global_load_dword v22, v[16:17], off offset:768 nt
	global_load_dword v18, v[16:17], off offset:1024 nt
	global_load_dword v14, v[16:17], off offset:1280 nt
	global_load_dword v35, v[110:111], off nt
	global_load_dword v31, v[110:111], off offset:256 nt
	global_load_dword v28, v[108:109], off offset:512 nt
	global_load_dword v27, v[110:111], off offset:512 nt
	global_load_dword v24, v[108:109], off offset:768 nt
	global_load_dword v23, v[110:111], off offset:768 nt
	global_load_dword v20, v[108:109], off offset:1024 nt
	global_load_dword v16, v[108:109], off offset:1280 nt
	global_load_dword v56, v[112:113], off nt
	global_load_dword v33, v[112:113], off offset:256 nt
	global_load_dword v29, v[112:113], off offset:512 nt
	global_load_dword v25, v[112:113], off offset:768 nt
	global_load_dword v19, v[110:111], off offset:1024 nt
	global_load_dword v21, v[112:113], off offset:1024 nt
	global_load_dword v17, v[112:113], off offset:1280 nt
	global_load_dword v15, v[110:111], off offset:1280 nt
	s_nop 0
	global_store_dword v[106:107], v36, off nt
	s_and_saveexec_b64 s[4:5], s[40:41]
	s_cbranch_execz .LBB0_468
	s_mov_b64 s[8:9], 0xca00000
	v_lshl_add_u64 v[106:107], v[12:13], 0, s[8:9]
	global_store_dword v[106:107], v37, off nt
.LBB0_468:
	s_or_b64 exec, exec, s[4:5]
	v_lshl_add_u64 v[106:107], v[10:11], 0, s[48:49]
	s_waitcnt vmcnt(62)
	v_fmac_f32_e32 v95, v36, v104
	v_fmac_f32_e32 v102, v37, v105
	global_store_dword v[106:107], v95, off nt
	s_and_saveexec_b64 s[4:5], s[40:41]
	s_cbranch_execz .LBB0_470
	v_lshl_add_u64 v[36:37], v[12:13], 0, s[48:49]
	global_store_dword v[36:37], v102, off nt
.LBB0_470:
	s_or_b64 exec, exec, s[4:5]
	s_mov_b64 s[4:5], 0xca00200
	v_lshl_add_u64 v[36:37], v[10:11], 0, s[4:5]
	v_fmac_f32_e32 v92, v95, v101
	v_fmac_f32_e32 v99, v102, v103
	global_store_dword v[36:37], v92, off nt
	s_and_saveexec_b64 s[4:5], s[40:41]
	s_cbranch_execz .LBB0_472
	s_mov_b64 s[8:9], 0xca00200
	v_lshl_add_u64 v[36:37], v[12:13], 0, s[8:9]
	global_store_dword v[36:37], v99, off nt
.LBB0_472:
	s_or_b64 exec, exec, s[4:5]
	s_mov_b64 s[4:5], 0xca00300
	v_lshl_add_u64 v[36:37], v[10:11], 0, s[4:5]
	v_fmac_f32_e32 v88, v92, v98
	v_fmac_f32_e32 v96, v99, v100
	global_store_dword v[36:37], v88, off nt
	s_and_saveexec_b64 s[4:5], s[40:41]
	s_cbranch_execz .LBB0_474
	s_mov_b64 s[8:9], 0xca00300
	v_lshl_add_u64 v[36:37], v[12:13], 0, s[8:9]
	global_store_dword v[36:37], v96, off nt
.LBB0_474:
	s_or_b64 exec, exec, s[4:5]
	s_mov_b64 s[4:5], 0xca00400
	v_lshl_add_u64 v[36:37], v[10:11], 0, s[4:5]
	v_fmac_f32_e32 v83, v88, v94
	s_waitcnt vmcnt(62)
	v_fmac_f32_e32 v91, v96, v97
	global_store_dword v[36:37], v83, off nt
	s_and_saveexec_b64 s[4:5], s[40:41]
	s_cbranch_execz .LBB0_476
	s_mov_b64 s[8:9], 0xca00400
	v_lshl_add_u64 v[36:37], v[12:13], 0, s[8:9]
	global_store_dword v[36:37], v91, off nt
.LBB0_476:
	s_or_b64 exec, exec, s[4:5]
	s_mov_b64 s[4:5], 0xca00500
	v_lshl_add_u64 v[36:37], v[10:11], 0, s[4:5]
	v_fmac_f32_e32 v77, v83, v90
	v_fmac_f32_e32 v86, v91, v93
	global_store_dword v[36:37], v77, off nt
	s_and_saveexec_b64 s[4:5], s[40:41]
	s_cbranch_execz .LBB0_478
	s_mov_b64 s[8:9], 0xca00500
	v_lshl_add_u64 v[36:37], v[12:13], 0, s[8:9]
	global_store_dword v[36:37], v86, off nt
.LBB0_478:
	s_or_b64 exec, exec, s[4:5]
	s_mov_b64 s[4:5], 0xca00600
	v_lshl_add_u64 v[36:37], v[10:11], 0, s[4:5]
	v_fmac_f32_e32 v72, v77, v85
	v_fmac_f32_e32 v80, v86, v89
	global_store_dword v[36:37], v72, off nt
	s_and_saveexec_b64 s[4:5], s[40:41]
	s_cbranch_execz .LBB0_480
	s_mov_b64 s[8:9], 0xca00600
	v_lshl_add_u64 v[36:37], v[12:13], 0, s[8:9]
	global_store_dword v[36:37], v80, off nt
.LBB0_480:
	s_or_b64 exec, exec, s[4:5]
	s_mov_b64 s[4:5], 0xca00700
	v_lshl_add_u64 v[36:37], v[10:11], 0, s[4:5]
	v_fmac_f32_e32 v66, v72, v79
	s_waitcnt vmcnt(62)
	v_fmac_f32_e32 v73, v80, v84
	global_store_dword v[36:37], v66, off nt
	s_and_saveexec_b64 s[4:5], s[40:41]
	s_cbranch_execz .LBB0_482
	s_mov_b64 s[8:9], 0xca00700
	v_lshl_add_u64 v[36:37], v[12:13], 0, s[8:9]
	global_store_dword v[36:37], v73, off nt
.LBB0_482:
	s_or_b64 exec, exec, s[4:5]
	s_mov_b64 s[4:5], 0xca00800
	v_lshl_add_u64 v[36:37], v[10:11], 0, s[4:5]
	v_fmac_f32_e32 v62, v66, v71
	v_fmac_f32_e32 v67, v73, v76
	global_store_dword v[36:37], v62, off nt
	s_and_saveexec_b64 s[4:5], s[40:41]
	s_cbranch_execz .LBB0_484
	s_mov_b64 s[8:9], 0xca00800
	v_lshl_add_u64 v[36:37], v[12:13], 0, s[8:9]
	global_store_dword v[36:37], v67, off nt
.LBB0_484:
	s_or_b64 exec, exec, s[4:5]
	s_mov_b64 s[4:5], 0xca00900
	v_lshl_add_u64 v[36:37], v[10:11], 0, s[4:5]
	s_waitcnt vmcnt(56)
	v_fmac_f32_e32 v64, v62, v82
	s_waitcnt vmcnt(40)
	v_fmac_f32_e32 v78, v67, v87
	global_store_dword v[36:37], v64, off nt
	s_and_saveexec_b64 s[4:5], s[40:41]
	s_cbranch_execz .LBB0_486
	s_mov_b64 s[8:9], 0xca00900
	v_lshl_add_u64 v[36:37], v[12:13], 0, s[8:9]
	global_store_dword v[36:37], v78, off nt
.LBB0_486:
	s_or_b64 exec, exec, s[4:5]
	s_mov_b64 s[4:5], 0xca00a00
	v_lshl_add_u64 v[36:37], v[10:11], 0, s[4:5]
	v_fmac_f32_e32 v60, v64, v75
	s_waitcnt vmcnt(40)
	v_fmac_f32_e32 v70, v78, v81
	global_store_dword v[36:37], v60, off nt
	s_and_saveexec_b64 s[4:5], s[40:41]
	s_cbranch_execz .LBB0_488
	s_mov_b64 s[8:9], 0xca00a00
	v_lshl_add_u64 v[36:37], v[12:13], 0, s[8:9]
	global_store_dword v[36:37], v70, off nt
.LBB0_488:
	s_or_b64 exec, exec, s[4:5]
	s_mov_b64 s[4:5], 0xca00b00
	v_lshl_add_u64 v[36:37], v[10:11], 0, s[4:5]
	v_fmac_f32_e32 v55, v60, v69
	s_waitcnt vmcnt(40)
	v_fmac_f32_e32 v65, v70, v74
	global_store_dword v[36:37], v55, off nt
	s_and_saveexec_b64 s[4:5], s[40:41]
	s_cbranch_execz .LBB0_490
	s_mov_b64 s[8:9], 0xca00b00
	v_lshl_add_u64 v[36:37], v[12:13], 0, s[8:9]
	global_store_dword v[36:37], v65, off nt
.LBB0_490:
	s_or_b64 exec, exec, s[4:5]
	s_mov_b64 s[4:5], 0xca00c00
	v_lshl_add_u64 v[36:37], v[10:11], 0, s[4:5]
	v_fmac_f32_e32 v51, v55, v63
	s_waitcnt vmcnt(40)
	v_fmac_f32_e32 v59, v65, v68
	global_store_dword v[36:37], v51, off nt
	s_and_saveexec_b64 s[4:5], s[40:41]
	s_cbranch_execz .LBB0_492
	s_mov_b64 s[8:9], 0xca00c00
	v_lshl_add_u64 v[36:37], v[12:13], 0, s[8:9]
	global_store_dword v[36:37], v59, off nt
.LBB0_492:
	s_or_b64 exec, exec, s[4:5]
	s_mov_b64 s[4:5], 0xca00d00
	v_lshl_add_u64 v[36:37], v[10:11], 0, s[4:5]
	v_fmac_f32_e32 v47, v51, v58
	s_waitcnt vmcnt(40)
	v_fmac_f32_e32 v54, v59, v61
	global_store_dword v[36:37], v47, off nt
	s_and_saveexec_b64 s[4:5], s[40:41]
	s_cbranch_execz .LBB0_494
	s_mov_b64 s[8:9], 0xca00d00
	v_lshl_add_u64 v[36:37], v[12:13], 0, s[8:9]
	global_store_dword v[36:37], v54, off nt
.LBB0_494:
	s_or_b64 exec, exec, s[4:5]
	s_mov_b64 s[4:5], 0xca00e00
	v_lshl_add_u64 v[36:37], v[10:11], 0, s[4:5]
	v_fmac_f32_e32 v44, v47, v53
	s_waitcnt vmcnt(40)
	v_fmac_f32_e32 v50, v54, v57
	global_store_dword v[36:37], v44, off nt
	s_and_saveexec_b64 s[4:5], s[40:41]
	s_cbranch_execz .LBB0_496
	s_mov_b64 s[8:9], 0xca00e00
	v_lshl_add_u64 v[36:37], v[12:13], 0, s[8:9]
	global_store_dword v[36:37], v50, off nt
.LBB0_496:
	s_or_b64 exec, exec, s[4:5]
	s_mov_b64 s[4:5], 0xca00f00
	v_lshl_add_u64 v[36:37], v[10:11], 0, s[4:5]
	v_fmac_f32_e32 v41, v44, v48
	s_waitcnt vmcnt(40)
	v_fmac_f32_e32 v45, v50, v52
	global_store_dword v[36:37], v41, off nt
	s_and_saveexec_b64 s[4:5], s[40:41]
	s_cbranch_execz .LBB0_498
	s_mov_b64 s[8:9], 0xca00f00
	v_lshl_add_u64 v[36:37], v[12:13], 0, s[8:9]
	global_store_dword v[36:37], v45, off nt
.LBB0_498:
	s_or_b64 exec, exec, s[4:5]
	s_mov_b64 s[4:5], 0xca01000
	v_lshl_add_u64 v[36:37], v[10:11], 0, s[4:5]
	v_fmac_f32_e32 v40, v41, v43
	s_waitcnt vmcnt(40)
	v_fmac_f32_e32 v42, v45, v46
	global_store_dword v[36:37], v40, off nt
	s_and_saveexec_b64 s[4:5], s[40:41]
	s_cbranch_execz .LBB0_500
	s_mov_b64 s[8:9], 0xca01000
	v_lshl_add_u64 v[36:37], v[12:13], 0, s[8:9]
	global_store_dword v[36:37], v42, off nt
.LBB0_500:
	s_or_b64 exec, exec, s[4:5]
	s_mov_b64 s[4:5], 0xca01100
	s_waitcnt vmcnt(39)
	v_mul_f32_e32 v40, v40, v49
	s_waitcnt vmcnt(24)
	v_mul_f32_e32 v41, v42, v56
	v_lshl_add_u64 v[36:37], v[10:11], 0, s[4:5]
	v_pk_add_f32 v[34:35], v[40:41], v[34:35]
	global_store_dword v[36:37], v34, off nt
	s_and_saveexec_b64 s[4:5], s[40:41]
	s_cbranch_execz .LBB0_502
	s_mov_b64 s[8:9], 0xca01100
	v_lshl_add_u64 v[36:37], v[12:13], 0, s[8:9]
	global_store_dword v[36:37], v35, off nt
.LBB0_502:
	s_or_b64 exec, exec, s[4:5]
	s_mov_b64 s[4:5], 0xca01200
	v_lshl_add_u64 v[36:37], v[10:11], 0, s[4:5]
	s_waitcnt vmcnt(24)
	v_pk_fma_f32 v[30:31], v[34:35], v[32:33], v[30:31]
	global_store_dword v[36:37], v30, off nt
	s_and_saveexec_b64 s[4:5], s[40:41]
	s_cbranch_execz .LBB0_504
	s_mov_b64 s[8:9], 0xca01200
	v_lshl_add_u64 v[32:33], v[12:13], 0, s[8:9]
	global_store_dword v[32:33], v31, off nt
.LBB0_504:
	s_or_b64 exec, exec, s[4:5]
	s_mov_b64 s[4:5], 0xca01300
	v_lshl_add_u64 v[32:33], v[10:11], 0, s[4:5]
	s_waitcnt vmcnt(24)
	v_pk_fma_f32 v[26:27], v[30:31], v[28:29], v[26:27]
	global_store_dword v[32:33], v26, off nt
	s_and_saveexec_b64 s[4:5], s[40:41]
	s_cbranch_execz .LBB0_506
	s_mov_b64 s[8:9], 0xca01300
	v_lshl_add_u64 v[28:29], v[12:13], 0, s[8:9]
	global_store_dword v[28:29], v27, off nt
.LBB0_506:
	s_or_b64 exec, exec, s[4:5]
	s_mov_b64 s[4:5], 0xca01400
	v_lshl_add_u64 v[28:29], v[10:11], 0, s[4:5]
	s_waitcnt vmcnt(24)
	v_pk_fma_f32 v[22:23], v[26:27], v[24:25], v[22:23]
	global_store_dword v[28:29], v22, off nt
	s_and_saveexec_b64 s[4:5], s[40:41]
	s_cbranch_execz .LBB0_508
	s_mov_b64 s[8:9], 0xca01400
	v_lshl_add_u64 v[24:25], v[12:13], 0, s[8:9]
	global_store_dword v[24:25], v23, off nt
.LBB0_508:
	s_or_b64 exec, exec, s[4:5]
	s_mov_b64 s[4:5], 0xca01500
	v_lshl_add_u64 v[24:25], v[10:11], 0, s[4:5]
	s_waitcnt vmcnt(23)
	v_pk_fma_f32 v[10:11], v[22:23], v[20:21], v[18:19]
	global_store_dword v[24:25], v10, off nt
	s_and_saveexec_b64 s[4:5], s[40:41]
	s_cbranch_execz .LBB0_465
	s_mov_b64 s[8:9], 0xca01500
	v_lshl_add_u64 v[12:13], v[12:13], 0, s[8:9]
	global_store_dword v[12:13], v11, off nt
	s_branch .LBB0_465

.LBB0_590:
	s_and_b32 s4, s6, 0x7f
	s_ashr_i32 s5, s6, 7
	s_and_b32 s0, s8, 0xffffe000
	s_lshl_b32 s1, s4, 6
	s_lshl_b32 s11, s5, 1
	s_or_b32 s76, s0, s1
	s_or_b32 s0, s11, 1
	s_mul_hi_i32 s1, s0, 0x2100
	s_mulk_i32 s0, 0x2100
	s_sub_i32 s0, s0, s4
	s_addk_i32 s0, 0x83
	v_mov_b32_e32 v130, v223
	v_mov_b32_e32 v70, v223
	s_lshl_b64 s[0:1], s[0:1], 8
	s_add_u32 s0, s36, s0
	v_ashrrev_i32_e32 v71, 31, v70
	s_addc_u32 s1, s37, s1
	v_lshlrev_b64 v[2:3], 2, v[70:71]
	s_ashr_i32 s77, s76, 31
	v_lshl_add_u64 v[4:5], s[0:1], 0, v[2:3]
	s_lshl_b64 s[36:37], s[76:77], 10
	v_readlane_b32 s0, v254, 29
	v_readlane_b32 s1, v254, 30
	s_add_u32 s0, s0, s36
	s_addc_u32 s1, s1, s37
	s_lshl_b32 s2, s5, 6
	s_and_b32 s2, s2, 0xc0
	s_lshl_b32 s10, s2, 2
	s_add_u32 s0, s0, s10
	v_add_co_u32_e32 v6, vcc, s16, v4
	s_addc_u32 s1, s1, 0
	s_lshl_b64 s[40:41], s[76:77], 9
	s_mov_b32 s77, 0x42000
	v_readlane_b32 s12, v254, 48
	v_addc_co_u32_e32 v7, vcc, 0, v5, vcc
	v_readlane_b32 s13, v254, 49
	s_add_u32 s3, s12, s40
	global_load_dword v8, v[4:5], off nt
	global_load_dword v9, v[6:7], off nt
	v_add_co_u32_e32 v6, vcc, s77, v4
	s_addc_u32 s12, s13, s41
	s_lshl_b32 s9, s2, 1
	v_addc_co_u32_e32 v7, vcc, 0, v5, vcc
	s_add_u32 s2, s3, s9
	global_load_dword v10, v[6:7], off nt
	v_add_co_u32_e32 v6, vcc, s24, v4
	s_addc_u32 s3, s12, 0
	s_nop 0
	v_addc_co_u32_e32 v7, vcc, 0, v5, vcc
	s_mov_b32 s12, 0x84000
	global_load_dword v11, v[6:7], off nt
	v_add_co_u32_e32 v6, vcc, s12, v4
	s_mov_b32 s12, 0xe7000
	s_nop 0
	v_addc_co_u32_e32 v7, vcc, 0, v5, vcc
	global_load_dword v12, v[6:7], off nt
	v_add_co_u32_e32 v6, vcc, s31, v4
	s_mov_b32 s30, 0x120000
	s_nop 0
	v_addc_co_u32_e32 v7, vcc, 0, v5, vcc
	global_load_dword v13, v[6:7], off nt
	v_add_co_u32_e32 v6, vcc, s38, v4
	s_mov_b32 s29, 0x141000
	s_nop 0
	v_addc_co_u32_e32 v7, vcc, 0, v5, vcc
	global_load_dword v14, v[6:7], off nt
	v_add_co_u32_e32 v6, vcc, s12, v4
	s_mov_b32 s12, 0x108000
	s_nop 0
	v_addc_co_u32_e32 v7, vcc, 0, v5, vcc
	global_load_dword v15, v[6:7], off nt
	v_add_co_u32_e32 v6, vcc, s12, v4
	s_mov_b32 s12, 0x129000
	s_nop 0
	v_addc_co_u32_e32 v7, vcc, 0, v5, vcc
	global_load_dword v16, v[6:7], off nt
	v_add_co_u32_e32 v6, vcc, s12, v4
	s_mov_b32 s12, 0x14a000
	s_nop 0
	v_addc_co_u32_e32 v7, vcc, 0, v5, vcc
	global_load_dword v17, v[6:7], off nt
	v_add_co_u32_e32 v6, vcc, s12, v4
	s_mov_b32 s12, 0x16b000
	s_nop 0
	v_addc_co_u32_e32 v7, vcc, 0, v5, vcc
	global_load_dword v18, v[6:7], off nt
	v_add_co_u32_e32 v6, vcc, s12, v4
	s_mov_b32 s12, 0x18c000
	s_nop 0
	v_addc_co_u32_e32 v7, vcc, 0, v5, vcc
	global_load_dword v19, v[6:7], off nt
	v_add_co_u32_e32 v6, vcc, s12, v4
	s_mov_b32 s12, 0x1ad000
	s_nop 0
	v_addc_co_u32_e32 v7, vcc, 0, v5, vcc
	global_load_dword v21, v[6:7], off nt
	v_add_co_u32_e32 v6, vcc, s12, v4
	s_mov_b32 s12, 0x1ce000
	s_nop 0
	v_addc_co_u32_e32 v7, vcc, 0, v5, vcc
	global_load_dword v23, v[6:7], off nt
	v_add_co_u32_e32 v6, vcc, s12, v4
	s_mov_b32 s12, 0x1ef000
	s_nop 0
	v_addc_co_u32_e32 v7, vcc, 0, v5, vcc
	global_load_dword v25, v[6:7], off nt
	v_add_co_u32_e32 v6, vcc, s12, v4
	s_mov_b32 s12, 0x6b000
	s_nop 0
	v_addc_co_u32_e32 v7, vcc, 0, v5, vcc
	global_load_dword v27, v[6:7], off nt
	v_add_co_u32_e32 v6, vcc, s97, v4
	s_mov_b32 s28, 0x162000
	s_nop 0
	v_addc_co_u32_e32 v7, vcc, 0, v5, vcc
	global_load_dword v20, v[6:7], off offset:1024 nt
	v_add_co_u32_e32 v6, vcc, s17, v4
	s_mov_b32 s27, 0x183000
	s_nop 0
	v_addc_co_u32_e32 v7, vcc, 0, v5, vcc
	global_load_dword v22, v[6:7], off offset:1024 nt
	v_add_co_u32_e32 v6, vcc, s20, v4
	s_mov_b32 s26, 0x1a4000
	s_nop 0
	v_addc_co_u32_e32 v7, vcc, 0, v5, vcc
	global_load_dword v24, v[6:7], off offset:1024 nt
	v_add_co_u32_e32 v6, vcc, s12, v4
	s_mov_b32 s12, 0x8c000
	s_nop 0
	v_addc_co_u32_e32 v7, vcc, 0, v5, vcc
	global_load_dword v26, v[6:7], off offset:1024 nt
	v_add_co_u32_e32 v6, vcc, s12, v4
	s_mov_b32 s12, 0xef000
	s_nop 0
	v_addc_co_u32_e32 v7, vcc, 0, v5, vcc
	global_load_dword v28, v[6:7], off offset:1024 nt
	v_add_co_u32_e32 v6, vcc, s33, v4
	s_mov_b32 s25, 0x1c5000
	s_nop 0
	v_addc_co_u32_e32 v7, vcc, 0, v5, vcc
	global_load_dword v29, v[6:7], off offset:1024 nt
	v_add_co_u32_e32 v6, vcc, s39, v4
	s_mov_b32 s23, 0x1e6000
	s_nop 0
	v_addc_co_u32_e32 v7, vcc, 0, v5, vcc
	global_load_dword v30, v[6:7], off offset:1024 nt
	v_add_co_u32_e32 v6, vcc, s12, v4
	s_mov_b32 s12, 0x110000
	s_nop 0
	v_addc_co_u32_e32 v7, vcc, 0, v5, vcc
	global_load_dword v31, v[6:7], off offset:1024 nt
	v_add_co_u32_e32 v6, vcc, s12, v4
	s_mov_b32 s12, 0x131000
	s_nop 0
	v_addc_co_u32_e32 v7, vcc, 0, v5, vcc
	global_load_dword v32, v[6:7], off offset:1024 nt
	v_add_co_u32_e32 v6, vcc, s12, v4
	s_mov_b32 s12, 0x152000
	s_nop 0
	v_addc_co_u32_e32 v7, vcc, 0, v5, vcc
	global_load_dword v33, v[6:7], off offset:1024 nt
	v_add_co_u32_e32 v6, vcc, s12, v4
	s_mov_b32 s12, 0x173000
	s_nop 0
	v_addc_co_u32_e32 v7, vcc, 0, v5, vcc
	global_load_dword v34, v[6:7], off offset:1024 nt
	v_add_co_u32_e32 v6, vcc, s12, v4
	s_mov_b32 s12, 0x194000
	s_nop 0
	v_addc_co_u32_e32 v7, vcc, 0, v5, vcc
	global_load_dword v35, v[6:7], off offset:1024 nt
	v_add_co_u32_e32 v6, vcc, s12, v4
	s_mov_b32 s12, 0x1b5000
	s_nop 0
	v_addc_co_u32_e32 v7, vcc, 0, v5, vcc
	global_load_dword v36, v[6:7], off offset:1024 nt
	v_add_co_u32_e32 v6, vcc, s12, v4
	s_mov_b32 s12, 0x1d6000
	s_nop 0
	v_addc_co_u32_e32 v7, vcc, 0, v5, vcc
	global_load_dword v37, v[6:7], off offset:1024 nt
	v_add_co_u32_e32 v6, vcc, s12, v4
	s_mov_b32 s12, 0x1f7000
	s_nop 0
	v_addc_co_u32_e32 v7, vcc, 0, v5, vcc
	global_load_dword v38, v[6:7], off offset:1024 nt
	v_add_co_u32_e32 v6, vcc, s12, v4
	s_mov_b32 s12, 0x73000
	s_nop 0
	v_addc_co_u32_e32 v7, vcc, 0, v5, vcc
	global_load_dword v39, v[6:7], off offset:1024 nt
	v_add_co_u32_e32 v6, vcc, s94, v4
	s_mov_b32 s22, 0x207000
	s_nop 0
	v_addc_co_u32_e32 v7, vcc, 0, v5, vcc
	global_load_dword v40, v[6:7], off offset:2048 nt
	v_add_co_u32_e32 v6, vcc, s18, v4
	v_and_b32_e32 v106, 0x7ffffff0, v70
	s_nop 0
	v_addc_co_u32_e32 v7, vcc, 0, v5, vcc
	global_load_dword v41, v[6:7], off offset:2048 nt
	v_add_co_u32_e32 v6, vcc, s21, v4
	v_lshlrev_b32_e32 v106, 1, v106
	s_nop 0
	v_addc_co_u32_e32 v7, vcc, 0, v5, vcc
	global_load_dword v42, v[6:7], off offset:2048 nt
	v_add_co_u32_e32 v6, vcc, s12, v4
	s_mov_b32 s12, 0x94000
	s_nop 0
	v_addc_co_u32_e32 v7, vcc, 0, v5, vcc
	global_load_dword v43, v[6:7], off offset:2048 nt
	v_add_co_u32_e32 v6, vcc, s12, v4
	s_mov_b32 s12, 0xf7000
	s_nop 0
	v_addc_co_u32_e32 v7, vcc, 0, v5, vcc
	global_load_dword v44, v[6:7], off offset:2048 nt
	v_add_co_u32_e32 v6, vcc, s34, v4
	s_waitcnt vmcnt(35)
	v_cvt_pk_bf16_f32 v8, v8, v9
	v_addc_co_u32_e32 v7, vcc, 0, v5, vcc
	global_load_dword v45, v[6:7], off offset:2048 nt
	v_add_co_u32_e32 v6, vcc, s52, v4
	s_waitcnt vmcnt(34)
	v_cvt_pk_bf16_f32 v9, v10, v11
	v_addc_co_u32_e32 v7, vcc, 0, v5, vcc
	global_load_dword v46, v[6:7], off offset:2048 nt
	v_add_co_u32_e32 v6, vcc, s12, v4
	s_mov_b32 s12, 0x118000
	s_nop 0
	v_addc_co_u32_e32 v7, vcc, 0, v5, vcc
	global_load_dword v47, v[6:7], off offset:2048 nt
	v_add_co_u32_e32 v6, vcc, s12, v4
	s_mov_b32 s12, 0x139000
	s_nop 0
	v_addc_co_u32_e32 v7, vcc, 0, v5, vcc
	global_load_dword v48, v[6:7], off offset:2048 nt
	v_add_co_u32_e32 v6, vcc, s12, v4
	s_mov_b32 s12, 0x15a000
	s_nop 0
	v_addc_co_u32_e32 v7, vcc, 0, v5, vcc
	global_load_dword v49, v[6:7], off offset:2048 nt
	v_add_co_u32_e32 v6, vcc, s12, v4
	s_mov_b32 s12, 0x17b000
	s_nop 0
	v_addc_co_u32_e32 v7, vcc, 0, v5, vcc
	global_load_dword v50, v[6:7], off offset:2048 nt
	v_add_co_u32_e32 v6, vcc, s12, v4
	s_mov_b32 s12, 0x19c000
	s_nop 0
	v_addc_co_u32_e32 v7, vcc, 0, v5, vcc
	global_load_dword v51, v[6:7], off offset:2048 nt
	v_add_co_u32_e32 v6, vcc, s12, v4
	s_mov_b32 s12, 0x1bd000
	s_nop 0
	v_addc_co_u32_e32 v7, vcc, 0, v5, vcc
	global_load_dword v54, v[6:7], off offset:2048 nt
	v_add_co_u32_e32 v6, vcc, s12, v4
	s_mov_b32 s12, 0x1de000
	s_nop 0
	v_addc_co_u32_e32 v7, vcc, 0, v5, vcc
	global_load_dword v55, v[6:7], off offset:2048 nt
	v_add_co_u32_e32 v6, vcc, s12, v4
	s_mov_b32 s12, 0x1ff000
	s_nop 0
	v_addc_co_u32_e32 v7, vcc, 0, v5, vcc
	global_load_dword v56, v[6:7], off offset:2048 nt
	v_add_co_u32_e32 v6, vcc, s12, v4
	s_mov_b32 s12, 0x5a000
	s_nop 0
	v_addc_co_u32_e32 v7, vcc, 0, v5, vcc
	global_load_dword v57, v[6:7], off offset:2048 nt
	v_add_co_u32_e32 v6, vcc, s96, v4
	s_waitcnt vmcnt(42)
	v_cvt_pk_bf16_f32 v10, v12, v13
	v_addc_co_u32_e32 v7, vcc, 0, v5, vcc
	global_load_dword v58, v[6:7], off offset:3072 nt
	v_add_co_u32_e32 v6, vcc, s19, v4
	s_waitcnt vmcnt(39)
	v_cvt_pk_bf16_f32 v12, v16, v17
	v_addc_co_u32_e32 v7, vcc, 0, v5, vcc
	global_load_dword v59, v[6:7], off offset:3072 nt
	v_add_co_u32_e32 v6, vcc, s12, v4
	s_mov_b32 s12, 0x7b000
	s_nop 0
	v_addc_co_u32_e32 v7, vcc, 0, v5, vcc
	global_load_dword v60, v[6:7], off offset:3072 nt
	v_add_co_u32_e32 v6, vcc, s12, v4
	s_mov_b32 s12, 0x9c000
	s_nop 0
	v_addc_co_u32_e32 v7, vcc, 0, v5, vcc
	global_load_dword v61, v[6:7], off offset:3072 nt
	v_add_co_u32_e32 v6, vcc, s12, v4
	s_mov_b32 s12, 0xff000
	s_nop 0
	v_addc_co_u32_e32 v7, vcc, 0, v5, vcc
	global_load_dword v62, v[6:7], off offset:3072 nt
	v_add_co_u32_e32 v6, vcc, s35, v4
	s_mov_b32 s13, s85
	s_nop 0
	v_addc_co_u32_e32 v7, vcc, 0, v5, vcc
	global_load_dword v63, v[6:7], off offset:3072 nt
	v_add_co_u32_e32 v6, vcc, s53, v4
	s_movk_i32 s85, 0x7000
	s_nop 0
	v_addc_co_u32_e32 v7, vcc, 0, v5, vcc
	global_load_dword v64, v[6:7], off offset:3072 nt
	v_add_co_u32_e32 v6, vcc, s12, v4
	s_waitcnt vmcnt(43)
	v_cvt_pk_bf16_f32 v13, v18, v19
	v_addc_co_u32_e32 v7, vcc, 0, v5, vcc
	global_load_dword v65, v[6:7], off offset:3072 nt
	v_add_co_u32_e32 v6, vcc, s30, v4
	v_cvt_pk_bf16_f32 v11, v14, v15
	s_nop 0
	v_addc_co_u32_e32 v7, vcc, 0, v5, vcc
	global_load_dword v66, v[6:7], off offset:3072 nt
	v_add_co_u32_e32 v6, vcc, s29, v4
	s_waitcnt vmcnt(43)
	v_cvt_pk_bf16_f32 v14, v21, v23
	v_addc_co_u32_e32 v7, vcc, 0, v5, vcc
	global_load_dword v67, v[6:7], off offset:3072 nt
	v_add_co_u32_e32 v6, vcc, s28, v4
	s_waitcnt vmcnt(42)
	v_cvt_pk_bf16_f32 v15, v25, v27
	v_addc_co_u32_e32 v7, vcc, 0, v5, vcc
	global_load_dword v68, v[6:7], off offset:3072 nt
	v_add_co_u32_e32 v6, vcc, s27, v4
	s_mov_b32 s12, s44
	s_nop 0
	v_addc_co_u32_e32 v7, vcc, 0, v5, vcc
	global_load_dword v69, v[6:7], off offset:3072 nt
	v_add_co_u32_e32 v6, vcc, s26, v4
	s_mulk_i32 s5, 0x4200
	s_nop 0
	v_addc_co_u32_e32 v7, vcc, 0, v5, vcc
	global_load_dword v72, v[6:7], off offset:3072 nt
	v_add_co_u32_e32 v6, vcc, s25, v4
	v_and_b32_e32 v0, 31, v130
	s_nop 0
	v_addc_co_u32_e32 v7, vcc, 0, v5, vcc
	global_load_dword v73, v[6:7], off offset:3072 nt
	v_add_co_u32_e32 v6, vcc, s23, v4
	s_nop 1
	v_addc_co_u32_e32 v7, vcc, 0, v5, vcc
	v_add_co_u32_e32 v4, vcc, s22, v4
	global_load_dword v74, v[6:7], off offset:3072 nt
	s_nop 0
	v_addc_co_u32_e32 v5, vcc, 0, v5, vcc
	global_load_dword v75, v[4:5], off offset:3072 nt
	v_lshl_add_u64 v[6:7], s[0:1], 0, v[2:3]
	s_mov_b32 s0, 0xf000
	v_add_co_u32_e32 v52, vcc, s0, v6
	v_lshlrev_b64 v[2:3], 1, v[70:71]
	s_nop 0
	v_addc_co_u32_e32 v53, vcc, 0, v7, vcc
	global_load_dword v71, v[52:53], off offset:3072 nt
	global_load_dword v76, v[52:53], off offset:2048 nt
	global_load_dword v77, v[52:53], off offset:1024 nt
	global_load_dword v78, v[52:53], off nt
	v_add_co_u32_e32 v52, vcc, s75, v6
	s_mov_b32 s0, 0xd000
	s_nop 0
	v_addc_co_u32_e32 v53, vcc, 0, v7, vcc
	global_load_dword v79, v[52:53], off offset:3072 nt
	global_load_dword v80, v[52:53], off offset:2048 nt
	global_load_dword v81, v[52:53], off offset:1024 nt
	global_load_dword v82, v[52:53], off nt
	v_add_co_u32_e32 v52, vcc, s0, v6
	s_mov_b32 s0, 0xb000
	s_nop 0
	v_addc_co_u32_e32 v53, vcc, 0, v7, vcc
	global_load_dword v83, v[52:53], off offset:3072 nt
	global_load_dword v84, v[52:53], off offset:2048 nt
	global_load_dword v85, v[52:53], off offset:1024 nt
	global_load_dword v86, v[52:53], off nt
	v_add_co_u32_e32 v52, vcc, s74, v6
	v_lshl_add_u64 v[4:5], s[2:3], 0, v[2:3]
	s_nop 0
	v_addc_co_u32_e32 v53, vcc, 0, v7, vcc
	global_load_dword v87, v[52:53], off offset:3072 nt
	global_load_dword v88, v[52:53], off offset:2048 nt
	global_load_dword v89, v[52:53], off offset:1024 nt
	global_load_dword v90, v[52:53], off nt
	v_add_co_u32_e32 v52, vcc, s0, v6
	s_mov_b32 s0, 0x9000
	s_nop 0
	v_addc_co_u32_e32 v53, vcc, 0, v7, vcc
	global_load_dword v91, v[52:53], off offset:3072 nt
	global_load_dword v92, v[52:53], off offset:2048 nt
	global_load_dword v93, v[52:53], off offset:1024 nt
	global_load_dword v94, v[52:53], off nt
	v_add_co_u32_e32 v52, vcc, s72, v6
	s_nop 1
	v_addc_co_u32_e32 v53, vcc, 0, v7, vcc
	global_load_dword v95, v[52:53], off offset:3072 nt
	global_load_dword v96, v[52:53], off offset:2048 nt
	global_load_dword v97, v[52:53], off offset:1024 nt
	global_load_dword v98, v[52:53], off nt
	v_add_co_u32_e32 v52, vcc, s0, v6
	s_nop 1
	v_addc_co_u32_e32 v53, vcc, 0, v7, vcc
	global_load_dword v99, v[52:53], off offset:3072 nt
	global_load_dword v100, v[52:53], off offset:2048 nt
	global_load_dword v101, v[52:53], off offset:1024 nt
	global_load_dword v102, v[52:53], off nt
	v_add_co_u32_e32 v52, vcc, s97, v6
	s_nop 1
	v_addc_co_u32_e32 v53, vcc, 0, v7, vcc
	global_load_dword v103, v[52:53], off offset:3072 nt
	global_load_dword v104, v[52:53], off offset:2048 nt
	global_load_dword v105, v[52:53], off offset:1024 nt
	s_nop 0
	global_load_dword v52, v[52:53], off nt
	v_and_b32_e32 v53, 15, v70
	v_mul_u32_u24_e32 v16, 0x90, v53
	v_add3_u32 v18, s7, v106, v16
	v_add_co_u32_e32 v16, vcc, s85, v4
	s_nop 1
	v_addc_co_u32_e32 v17, vcc, 0, v5, vcc
	global_load_ushort v19, v[16:17], off offset:3584
	global_load_ushort v21, v[16:17], off offset:3072
	global_load_ushort v23, v[16:17], off offset:2560
	global_load_ushort v25, v[16:17], off offset:2048
	global_load_ushort v27, v[16:17], off offset:1536
	global_load_ushort v53, v[16:17], off offset:1024
	global_load_ushort v106, v[16:17], off offset:512
	global_load_ushort v107, v[16:17], off
	v_add_co_u32_e32 v16, vcc, s95, v4
	s_nop 1
	v_addc_co_u32_e32 v17, vcc, 0, v5, vcc
	global_load_ushort v108, v[16:17], off offset:3584
	global_load_ushort v109, v[16:17], off offset:3072
	global_load_ushort v110, v[16:17], off offset:2560
	global_load_ushort v111, v[16:17], off offset:2048
	global_load_ushort v112, v[16:17], off offset:1536
	global_load_ushort v113, v[16:17], off offset:1024
	global_load_ushort v114, v[16:17], off offset:512
	global_load_ushort v115, v[16:17], off
	v_add_co_u32_e32 v16, vcc, s92, v4
	s_nop 1
	v_addc_co_u32_e32 v17, vcc, 0, v5, vcc
	global_load_ushort v116, v[16:17], off offset:3584
	global_load_ushort v117, v[16:17], off offset:3072
	global_load_ushort v118, v[16:17], off offset:2560
	global_load_ushort v119, v[16:17], off offset:2048
	global_load_ushort v120, v[16:17], off offset:1536
	global_load_ushort v121, v[16:17], off offset:1024
	global_load_ushort v122, v[16:17], off offset:512
	global_load_ushort v123, v[16:17], off
	v_add_co_u32_e32 v16, vcc, s81, v4
	s_nop 1
	v_addc_co_u32_e32 v17, vcc, 0, v5, vcc
	global_load_ushort v124, v[16:17], off offset:3584
	global_load_ushort v125, v[16:17], off offset:3072
	global_load_ushort v126, v[16:17], off offset:2560
	global_load_ushort v127, v[16:17], off offset:2048
	global_load_ushort v128, v[16:17], off offset:1536
	global_load_ushort v129, v[16:17], off offset:1024
	global_load_ushort v131, v[16:17], off offset:512
	s_nop 0
	global_load_ushort v16, v[16:17], off
	ds_write_b128 v18, v[8:11] offset:23040
	ds_write_b128 v18, v[12:15] offset:23056
	s_waitcnt vmcnt(62)
	v_cvt_pk_bf16_f32 v8, v20, v22
	v_cvt_pk_bf16_f32 v9, v24, v26
	v_cvt_pk_bf16_f32 v10, v28, v29
	v_cvt_pk_bf16_f32 v11, v30, v31
	v_cvt_pk_bf16_f32 v12, v32, v33
	v_cvt_pk_bf16_f32 v13, v34, v35
	v_cvt_pk_bf16_f32 v14, v36, v37
	v_cvt_pk_bf16_f32 v15, v38, v39
	ds_write_b128 v18, v[8:11] offset:25344
	ds_write_b128 v18, v[12:15] offset:25360
	v_cvt_pk_bf16_f32 v8, v40, v41
	v_cvt_pk_bf16_f32 v9, v42, v43
	v_cvt_pk_bf16_f32 v10, v44, v45
	v_cvt_pk_bf16_f32 v11, v46, v47
	v_cvt_pk_bf16_f32 v12, v48, v49
	v_cvt_pk_bf16_f32 v13, v50, v51
	v_cvt_pk_bf16_f32 v14, v54, v55
	v_cvt_pk_bf16_f32 v15, v56, v57
	ds_write_b128 v18, v[8:11] offset:27648
	ds_write_b128 v18, v[12:15] offset:27664
	v_cvt_pk_bf16_f32 v8, v58, v59
	v_cvt_pk_bf16_f32 v9, v60, v61
	v_cvt_pk_bf16_f32 v10, v62, v63
	v_cvt_pk_bf16_f32 v11, v64, v65
	v_cvt_pk_bf16_f32 v12, v66, v67
	v_cvt_pk_bf16_f32 v13, v68, v69
	v_cvt_pk_bf16_f32 v14, v72, v73
	v_cvt_pk_bf16_f32 v15, v74, v75
	ds_write_b128 v18, v[8:11] offset:29952
	ds_write_b128 v18, v[12:15] offset:29968
	v_rcp_f32_e32 v11, v71
	v_sub_f32_e32 v10, 1.0, v71
	v_lshl_add_u32 v8, v70, 1, s7
	v_mul_f32_e32 v10, v10, v11
	v_sub_f32_e32 v11, 1.0, v76
	s_waitcnt vmcnt(31)
	v_lshlrev_b32_e32 v9, 16, v19
	v_mul_f32_e32 v9, v71, v9
	v_cvt_pk_bf16_f32 v9, v9, s0
	ds_write_b16 v8, v9 offset:9216
	v_cvt_pk_bf16_f32 v9, v10, s0
	v_mul_f32_e32 v10, v71, v76
	v_rcp_f32_e32 v12, v10
	ds_write_b16 v8, v9
	s_waitcnt vmcnt(30)
	v_lshlrev_b32_e32 v9, 16, v21
	v_mul_f32_e32 v9, v10, v9
	v_mul_f32_e32 v10, v10, v77
	v_mul_f32_e32 v11, v11, v12
	v_cvt_pk_bf16_f32 v9, v9, s0
	v_rcp_f32_e32 v12, v10
	ds_write_b16 v8, v9 offset:9360
	v_cvt_pk_bf16_f32 v9, v11, s0
	ds_write_b16 v8, v9 offset:144
	s_waitcnt vmcnt(29)
	v_lshlrev_b32_e32 v9, 16, v23
	v_mul_f32_e32 v9, v10, v9
	v_sub_f32_e32 v11, 1.0, v77
	v_mul_f32_e32 v10, v10, v78
	v_mul_f32_e32 v11, v11, v12
	v_cvt_pk_bf16_f32 v9, v9, s0
	v_rcp_f32_e32 v12, v10
	ds_write_b16 v8, v9 offset:9504
	v_cvt_pk_bf16_f32 v9, v11, s0
	ds_write_b16 v8, v9 offset:288
	s_waitcnt vmcnt(28)
	v_lshlrev_b32_e32 v9, 16, v25
	v_mul_f32_e32 v9, v10, v9
	v_sub_f32_e32 v11, 1.0, v78
	v_mul_f32_e32 v10, v10, v79
	v_mul_f32_e32 v11, v11, v12
	v_cvt_pk_bf16_f32 v9, v9, s0
	v_rcp_f32_e32 v12, v10
	ds_write_b16 v8, v9 offset:9648
	v_cvt_pk_bf16_f32 v9, v11, s0
	ds_write_b16 v8, v9 offset:432
	s_waitcnt vmcnt(27)
	v_lshlrev_b32_e32 v9, 16, v27
	v_mul_f32_e32 v9, v10, v9
	v_sub_f32_e32 v11, 1.0, v79
	v_mul_f32_e32 v10, v10, v80
	v_mul_f32_e32 v11, v11, v12
	v_cvt_pk_bf16_f32 v9, v9, s0
	v_rcp_f32_e32 v12, v10
	ds_write_b16 v8, v9 offset:9792
	v_cvt_pk_bf16_f32 v9, v11, s0
	ds_write_b16 v8, v9 offset:576
	s_waitcnt vmcnt(26)
	v_lshlrev_b32_e32 v9, 16, v53
	v_mul_f32_e32 v9, v10, v9
	v_sub_f32_e32 v11, 1.0, v80
	v_mul_f32_e32 v10, v10, v81
	v_mul_f32_e32 v11, v11, v12
	v_cvt_pk_bf16_f32 v9, v9, s0
	v_rcp_f32_e32 v12, v10
	ds_write_b16 v8, v9 offset:9936
	v_cvt_pk_bf16_f32 v9, v11, s0
	ds_write_b16 v8, v9 offset:720
	s_waitcnt vmcnt(25)
	v_lshlrev_b32_e32 v9, 16, v106
	v_mul_f32_e32 v9, v10, v9
	v_sub_f32_e32 v11, 1.0, v81
	v_mul_f32_e32 v10, v10, v82
	v_mul_f32_e32 v11, v11, v12
	v_cvt_pk_bf16_f32 v9, v9, s0
	v_rcp_f32_e32 v12, v10
	ds_write_b16 v8, v9 offset:10080
	v_cvt_pk_bf16_f32 v9, v11, s0
	ds_write_b16 v8, v9 offset:864
	s_waitcnt vmcnt(24)
	v_lshlrev_b32_e32 v9, 16, v107
	v_mul_f32_e32 v9, v10, v9
	v_sub_f32_e32 v11, 1.0, v82
	v_mul_f32_e32 v10, v10, v83
	v_mul_f32_e32 v11, v11, v12
	v_cvt_pk_bf16_f32 v9, v9, s0
	v_rcp_f32_e32 v12, v10
	ds_write_b16 v8, v9 offset:10224
	v_cvt_pk_bf16_f32 v9, v11, s0
	ds_write_b16 v8, v9 offset:1008
	s_waitcnt vmcnt(23)
	v_lshlrev_b32_e32 v9, 16, v108
	v_mul_f32_e32 v9, v10, v9
	v_sub_f32_e32 v11, 1.0, v83
	v_mul_f32_e32 v10, v10, v84
	v_mul_f32_e32 v11, v11, v12
	v_cvt_pk_bf16_f32 v9, v9, s0
	v_rcp_f32_e32 v12, v10
	ds_write_b16 v8, v9 offset:10368
	v_cvt_pk_bf16_f32 v9, v11, s0
	ds_write_b16 v8, v9 offset:1152
	s_waitcnt vmcnt(22)
	v_lshlrev_b32_e32 v9, 16, v109
	v_mul_f32_e32 v9, v10, v9
	v_sub_f32_e32 v11, 1.0, v84
	v_mul_f32_e32 v10, v10, v85
	v_mul_f32_e32 v11, v11, v12
	v_cvt_pk_bf16_f32 v9, v9, s0
	v_rcp_f32_e32 v12, v10
	ds_write_b16 v8, v9 offset:10512
	v_cvt_pk_bf16_f32 v9, v11, s0
	ds_write_b16 v8, v9 offset:1296
	s_waitcnt vmcnt(21)
	v_lshlrev_b32_e32 v9, 16, v110
	v_mul_f32_e32 v9, v10, v9
	v_sub_f32_e32 v11, 1.0, v85
	v_mul_f32_e32 v10, v10, v86
	v_mul_f32_e32 v11, v11, v12
	v_cvt_pk_bf16_f32 v9, v9, s0
	v_rcp_f32_e32 v12, v10
	ds_write_b16 v8, v9 offset:10656
	v_cvt_pk_bf16_f32 v9, v11, s0
	ds_write_b16 v8, v9 offset:1440
	s_waitcnt vmcnt(20)
	v_lshlrev_b32_e32 v9, 16, v111
	v_mul_f32_e32 v9, v10, v9
	v_sub_f32_e32 v11, 1.0, v86
	v_mul_f32_e32 v10, v10, v87
	v_mul_f32_e32 v11, v11, v12
	v_cvt_pk_bf16_f32 v9, v9, s0
	v_rcp_f32_e32 v12, v10
	ds_write_b16 v8, v9 offset:10800
	v_cvt_pk_bf16_f32 v9, v11, s0
	ds_write_b16 v8, v9 offset:1584
	s_waitcnt vmcnt(19)
	v_lshlrev_b32_e32 v9, 16, v112
	v_mul_f32_e32 v9, v10, v9
	v_sub_f32_e32 v11, 1.0, v87
	v_mul_f32_e32 v10, v10, v88
	v_mul_f32_e32 v11, v11, v12
	v_cvt_pk_bf16_f32 v9, v9, s0
	v_rcp_f32_e32 v12, v10
	ds_write_b16 v8, v9 offset:10944
	v_cvt_pk_bf16_f32 v9, v11, s0
	ds_write_b16 v8, v9 offset:1728
	s_waitcnt vmcnt(18)
	v_lshlrev_b32_e32 v9, 16, v113
	v_mul_f32_e32 v9, v10, v9
	v_sub_f32_e32 v11, 1.0, v88
	v_mul_f32_e32 v10, v10, v89
	v_mul_f32_e32 v11, v11, v12
	v_cvt_pk_bf16_f32 v9, v9, s0
	v_rcp_f32_e32 v12, v10
	ds_write_b16 v8, v9 offset:11088
	v_cvt_pk_bf16_f32 v9, v11, s0
	ds_write_b16 v8, v9 offset:1872
	s_waitcnt vmcnt(17)
	v_lshlrev_b32_e32 v9, 16, v114
	v_mul_f32_e32 v9, v10, v9
	v_sub_f32_e32 v11, 1.0, v89
	v_mul_f32_e32 v10, v10, v90
	v_mul_f32_e32 v11, v11, v12
	v_cvt_pk_bf16_f32 v9, v9, s0
	v_rcp_f32_e32 v12, v10
	ds_write_b16 v8, v9 offset:11232
	v_cvt_pk_bf16_f32 v9, v11, s0
	ds_write_b16 v8, v9 offset:2016
	s_waitcnt vmcnt(16)
	v_lshlrev_b32_e32 v9, 16, v115
	v_mul_f32_e32 v9, v10, v9
	v_sub_f32_e32 v11, 1.0, v90
	v_mul_f32_e32 v10, v10, v91
	v_mul_f32_e32 v11, v11, v12
	v_cvt_pk_bf16_f32 v9, v9, s0
	v_rcp_f32_e32 v12, v10
	ds_write_b16 v8, v9 offset:11376
	v_cvt_pk_bf16_f32 v9, v11, s0
	ds_write_b16 v8, v9 offset:2160
	s_waitcnt vmcnt(15)
	v_lshlrev_b32_e32 v9, 16, v116
	v_mul_f32_e32 v9, v10, v9
	v_sub_f32_e32 v11, 1.0, v91
	v_mul_f32_e32 v10, v10, v92
	v_mul_f32_e32 v11, v11, v12
	v_cvt_pk_bf16_f32 v9, v9, s0
	v_rcp_f32_e32 v12, v10
	ds_write_b16 v8, v9 offset:11520
	v_cvt_pk_bf16_f32 v9, v11, s0
	ds_write_b16 v8, v9 offset:2304
	s_waitcnt vmcnt(14)
	v_lshlrev_b32_e32 v9, 16, v117
	v_mul_f32_e32 v9, v10, v9
	v_sub_f32_e32 v11, 1.0, v92
	v_mul_f32_e32 v10, v10, v93
	v_mul_f32_e32 v11, v11, v12
	v_cvt_pk_bf16_f32 v9, v9, s0
	v_rcp_f32_e32 v12, v10
	ds_write_b16 v8, v9 offset:11664
	v_cvt_pk_bf16_f32 v9, v11, s0
	ds_write_b16 v8, v9 offset:2448
	s_waitcnt vmcnt(13)
	v_lshlrev_b32_e32 v9, 16, v118
	v_mul_f32_e32 v9, v10, v9
	v_sub_f32_e32 v11, 1.0, v93
	v_mul_f32_e32 v10, v10, v94
	v_mul_f32_e32 v11, v11, v12
	v_cvt_pk_bf16_f32 v9, v9, s0
	v_rcp_f32_e32 v12, v10
	ds_write_b16 v8, v9 offset:11808
	v_cvt_pk_bf16_f32 v9, v11, s0
	ds_write_b16 v8, v9 offset:2592
	s_waitcnt vmcnt(12)
	v_lshlrev_b32_e32 v9, 16, v119
	v_mul_f32_e32 v9, v10, v9
	v_sub_f32_e32 v11, 1.0, v94
	v_mul_f32_e32 v10, v10, v95
	v_mul_f32_e32 v11, v11, v12
	v_cvt_pk_bf16_f32 v9, v9, s0
	v_rcp_f32_e32 v12, v10
	ds_write_b16 v8, v9 offset:11952
	v_cvt_pk_bf16_f32 v9, v11, s0
	ds_write_b16 v8, v9 offset:2736
	s_waitcnt vmcnt(11)
	v_lshlrev_b32_e32 v9, 16, v120
	v_mul_f32_e32 v9, v10, v9
	v_sub_f32_e32 v11, 1.0, v95
	v_mul_f32_e32 v10, v10, v96
	v_mul_f32_e32 v11, v11, v12
	v_cvt_pk_bf16_f32 v9, v9, s0
	v_rcp_f32_e32 v12, v10
	ds_write_b16 v8, v9 offset:12096
	v_cvt_pk_bf16_f32 v9, v11, s0
	ds_write_b16 v8, v9 offset:2880
	s_waitcnt vmcnt(10)
	v_lshlrev_b32_e32 v9, 16, v121
	v_mul_f32_e32 v9, v10, v9
	v_sub_f32_e32 v11, 1.0, v96
	v_mul_f32_e32 v10, v10, v97
	v_mul_f32_e32 v11, v11, v12
	v_cvt_pk_bf16_f32 v9, v9, s0
	v_rcp_f32_e32 v12, v10
	ds_write_b16 v8, v9 offset:12240
	v_cvt_pk_bf16_f32 v9, v11, s0
	ds_write_b16 v8, v9 offset:3024
	s_waitcnt vmcnt(9)
	v_lshlrev_b32_e32 v9, 16, v122
	v_mul_f32_e32 v9, v10, v9
	v_sub_f32_e32 v11, 1.0, v97
	v_mul_f32_e32 v10, v10, v98
	v_mul_f32_e32 v11, v11, v12
	v_cvt_pk_bf16_f32 v9, v9, s0
	v_rcp_f32_e32 v12, v10
	ds_write_b16 v8, v9 offset:12384
	v_cvt_pk_bf16_f32 v9, v11, s0
	ds_write_b16 v8, v9 offset:3168
	s_waitcnt vmcnt(8)
	v_lshlrev_b32_e32 v9, 16, v123
	v_mul_f32_e32 v9, v10, v9
	v_sub_f32_e32 v11, 1.0, v98
	v_mul_f32_e32 v10, v10, v99
	v_mul_f32_e32 v11, v11, v12
	v_cvt_pk_bf16_f32 v9, v9, s0
	v_rcp_f32_e32 v12, v10
	ds_write_b16 v8, v9 offset:12528
	v_cvt_pk_bf16_f32 v9, v11, s0
	ds_write_b16 v8, v9 offset:3312
	s_waitcnt vmcnt(7)
	v_lshlrev_b32_e32 v9, 16, v124
	v_mul_f32_e32 v9, v10, v9
	v_sub_f32_e32 v11, 1.0, v99
	v_mul_f32_e32 v10, v10, v100
	v_mul_f32_e32 v11, v11, v12
	v_cvt_pk_bf16_f32 v9, v9, s0
	v_rcp_f32_e32 v12, v10
	ds_write_b16 v8, v9 offset:12672
	v_cvt_pk_bf16_f32 v9, v11, s0
	ds_write_b16 v8, v9 offset:3456
	s_waitcnt vmcnt(6)
	v_lshlrev_b32_e32 v9, 16, v125
	v_mul_f32_e32 v9, v10, v9
	v_sub_f32_e32 v11, 1.0, v100
	v_mul_f32_e32 v10, v10, v101
	v_mul_f32_e32 v11, v11, v12
	v_cvt_pk_bf16_f32 v9, v9, s0
	v_rcp_f32_e32 v12, v10
	ds_write_b16 v8, v9 offset:12816
	v_cvt_pk_bf16_f32 v9, v11, s0
	ds_write_b16 v8, v9 offset:3600
	s_waitcnt vmcnt(5)
	v_lshlrev_b32_e32 v9, 16, v126
	v_mul_f32_e32 v9, v10, v9
	v_sub_f32_e32 v11, 1.0, v101
	v_mul_f32_e32 v10, v10, v102
	v_mul_f32_e32 v11, v11, v12
	v_cvt_pk_bf16_f32 v9, v9, s0
	v_rcp_f32_e32 v12, v10
	ds_write_b16 v8, v9 offset:12960
	v_cvt_pk_bf16_f32 v9, v11, s0
	ds_write_b16 v8, v9 offset:3744
	s_waitcnt vmcnt(4)
	v_lshlrev_b32_e32 v9, 16, v127
	v_mul_f32_e32 v9, v10, v9
	v_sub_f32_e32 v11, 1.0, v102
	v_mul_f32_e32 v10, v10, v103
	v_mul_f32_e32 v11, v11, v12
	v_cvt_pk_bf16_f32 v9, v9, s0
	v_rcp_f32_e32 v12, v10
	ds_write_b16 v8, v9 offset:13104
	v_cvt_pk_bf16_f32 v9, v11, s0
	ds_write_b16 v8, v9 offset:3888
	s_waitcnt vmcnt(3)
	v_lshlrev_b32_e32 v9, 16, v128
	v_mul_f32_e32 v9, v10, v9
	v_sub_f32_e32 v11, 1.0, v103
	v_mul_f32_e32 v10, v10, v104
	v_mul_f32_e32 v11, v11, v12
	v_cvt_pk_bf16_f32 v9, v9, s0
	v_rcp_f32_e32 v12, v10
	ds_write_b16 v8, v9 offset:13248
	v_cvt_pk_bf16_f32 v9, v11, s0
	ds_write_b16 v8, v9 offset:4032
	s_waitcnt vmcnt(2)
	v_lshlrev_b32_e32 v9, 16, v129
	v_mul_f32_e32 v9, v10, v9
	v_sub_f32_e32 v11, 1.0, v104
	v_mul_f32_e32 v10, v10, v105
	v_mul_f32_e32 v11, v11, v12
	v_cvt_pk_bf16_f32 v9, v9, s0
	v_rcp_f32_e32 v12, v10
	ds_write_b16 v8, v9 offset:13392
	v_cvt_pk_bf16_f32 v9, v11, s0
	ds_write_b16 v8, v9 offset:4176
	s_waitcnt vmcnt(1)
	v_lshlrev_b32_e32 v9, 16, v131
	v_mul_f32_e32 v9, v10, v9
	v_sub_f32_e32 v11, 1.0, v105
	v_mul_f32_e32 v11, v11, v12
	v_cvt_pk_bf16_f32 v9, v9, s0
	ds_write_b16 v8, v9 offset:13536
	v_cvt_pk_bf16_f32 v9, v11, s0
	ds_write_b16 v8, v9 offset:4320
	v_mul_f32_e32 v9, v10, v52
	v_rcp_f32_e32 v12, v9
	s_waitcnt vmcnt(0)
	v_lshlrev_b32_e32 v11, 16, v16
	v_mul_f32_e32 v10, v9, v11
	v_sub_f32_e32 v11, 1.0, v52
	v_mul_f32_e32 v11, v11, v12
	v_cvt_pk_bf16_f32 v10, v10, s0
	ds_write_b16 v8, v10 offset:13680
	v_cvt_pk_bf16_f32 v10, v11, s0
	ds_write_b16 v8, v10 offset:4464
	v_add_co_u32_e32 v10, vcc, s85, v6
	s_nop 1
	v_addc_co_u32_e32 v11, vcc, 0, v7, vcc
	global_load_dword v26, v[10:11], off offset:3072 nt
	global_load_dword v27, v[10:11], off offset:2048 nt
	global_load_dword v28, v[10:11], off offset:1024 nt
	global_load_dword v29, v[10:11], off nt
	v_add_co_u32_e32 v10, vcc, s95, v6
	s_waitcnt vmcnt(3)
	v_rcp_f32_e32 v44, v26
	v_addc_co_u32_e32 v11, vcc, 0, v7, vcc
	global_load_dword v30, v[10:11], off offset:3072 nt
	global_load_dword v31, v[10:11], off offset:2048 nt
	global_load_dword v32, v[10:11], off offset:1024 nt
	global_load_dword v33, v[10:11], off nt
	v_add_co_u32_e32 v10, vcc, s92, v6
	v_sub_f32_e32 v43, 1.0, v26
	s_nop 0
	v_addc_co_u32_e32 v11, vcc, 0, v7, vcc
	global_load_dword v34, v[10:11], off offset:3072 nt
	global_load_dword v35, v[10:11], off offset:2048 nt
	global_load_dword v36, v[10:11], off offset:1024 nt
	global_load_dword v37, v[10:11], off nt
	v_add_co_u32_e32 v10, vcc, s81, v6
	v_mul_f32_e32 v43, v43, v44
	s_nop 0
	v_addc_co_u32_e32 v11, vcc, 0, v7, vcc
	global_load_dword v38, v[10:11], off offset:3072 nt
	global_load_dword v39, v[10:11], off offset:2048 nt
	global_load_dword v40, v[10:11], off offset:1024 nt
	global_load_dword v41, v[10:11], off nt
	v_add_co_u32_e32 v10, vcc, s87, v6
	s_nop 1
	v_addc_co_u32_e32 v11, vcc, 0, v7, vcc
	global_load_dword v42, v[10:11], off offset:3072 nt
	global_load_dword v23, v[10:11], off offset:2048 nt
	global_load_dword v22, v[10:11], off offset:1024 nt
	global_load_dword v20, v[10:11], off nt
	v_add_co_u32_e32 v10, vcc, s93, v6
	s_nop 1
	v_addc_co_u32_e32 v11, vcc, 0, v7, vcc
	global_load_dword v21, v[10:11], off offset:3072 nt
	global_load_dword v19, v[10:11], off offset:2048 nt
	global_load_dword v18, v[10:11], off offset:1024 nt
	global_load_dword v16, v[10:11], off nt
	v_add_co_u32_e32 v10, vcc, s15, v6
	s_nop 1
	v_addc_co_u32_e32 v11, vcc, 0, v7, vcc
	v_add_co_u32_e32 v24, vcc, s87, v4
	global_load_dword v17, v[10:11], off offset:3072 nt
	global_load_dword v15, v[10:11], off offset:2048 nt
	global_load_dword v14, v[10:11], off offset:1024 nt
	global_load_dword v13, v[10:11], off nt
	global_load_dword v12, v[6:7], off offset:3072 nt
	s_nop 0
	global_load_dword v11, v[6:7], off offset:2048 nt
	global_load_dword v10, v[6:7], off offset:1024 nt
	s_nop 0
	global_load_dword v6, v[6:7], off nt
	v_addc_co_u32_e32 v25, vcc, 0, v5, vcc
	global_load_ushort v7, v[24:25], off offset:3584
	global_load_ushort v45, v[24:25], off offset:3072
	global_load_ushort v46, v[24:25], off offset:2560
	global_load_ushort v47, v[24:25], off offset:2048
	global_load_ushort v48, v[24:25], off offset:1536
	global_load_ushort v49, v[24:25], off offset:1024
	global_load_ushort v50, v[24:25], off offset:512
	global_load_ushort v51, v[24:25], off
	v_add_co_u32_e32 v24, vcc, s93, v4
	s_waitcnt vmcnt(7)
	v_lshlrev_b32_e32 v7, 16, v7
	v_addc_co_u32_e32 v25, vcc, 0, v5, vcc
	global_load_ushort v52, v[24:25], off offset:3584
	global_load_ushort v53, v[24:25], off offset:3072
	global_load_ushort v54, v[24:25], off offset:2560
	global_load_ushort v55, v[24:25], off offset:2048
	global_load_ushort v56, v[24:25], off offset:1536
	global_load_ushort v57, v[24:25], off offset:1024
	global_load_ushort v58, v[24:25], off offset:512
	global_load_ushort v59, v[24:25], off
	v_add_co_u32_e32 v24, vcc, s15, v4
	v_mul_f32_e32 v7, v26, v7
	s_nop 0
	v_addc_co_u32_e32 v25, vcc, 0, v5, vcc
	global_load_ushort v60, v[24:25], off offset:3584
	global_load_ushort v61, v[24:25], off offset:3072
	global_load_ushort v62, v[24:25], off offset:2560
	global_load_ushort v63, v[24:25], off offset:2048
	global_load_ushort v64, v[24:25], off offset:1536
	global_load_ushort v65, v[24:25], off offset:1024
	global_load_ushort v66, v[24:25], off offset:512
	s_nop 0
	global_load_ushort v24, v[24:25], off
	s_nop 0
	global_load_ushort v25, v[4:5], off offset:3584
	global_load_ushort v67, v[4:5], off offset:3072
	global_load_ushort v68, v[4:5], off offset:2560
	global_load_ushort v69, v[4:5], off offset:2048
	global_load_ushort v71, v[4:5], off offset:1536
	global_load_ushort v72, v[4:5], off offset:1024
	global_load_ushort v73, v[4:5], off offset:512
	s_nop 0
	global_load_ushort v4, v[4:5], off
	v_cvt_pk_bf16_f32 v5, v43, s0
	v_cvt_pk_bf16_f32 v44, v7, s0
	ds_write_b16 v8, v5 offset:4608
	v_mul_f32_e32 v5, v9, v7
	v_mul_f32_e32 v7, v26, v27
	v_sub_f32_e32 v26, 1.0, v27
	v_rcp_f32_e32 v27, v7
	v_cvt_pk_bf16_f32 v5, v5, s0
	ds_write_b16 v8, v5 offset:18432
	s_waitcnt vmcnt(30)
	v_lshlrev_b32_e32 v5, 16, v45
	v_mul_f32_e32 v5, v7, v5
	v_mul_f32_e32 v26, v26, v27
	v_cvt_pk_bf16_f32 v27, v5, s0
	v_mul_f32_e32 v7, v7, v28
	ds_write_b16 v8, v27 offset:13968
	v_mul_f32_e32 v5, v9, v5
	v_rcp_f32_e32 v27, v7
	v_cvt_pk_bf16_f32 v5, v5, s0
	v_cvt_pk_bf16_f32 v26, v26, s0
	ds_write_b16 v8, v5 offset:18576
	s_waitcnt vmcnt(29)
	v_lshlrev_b32_e32 v5, 16, v46
	ds_write_b16 v8, v26 offset:4752
	v_mul_f32_e32 v5, v7, v5
	v_sub_f32_e32 v26, 1.0, v28
	v_mul_f32_e32 v26, v26, v27
	v_cvt_pk_bf16_f32 v27, v5, s0
	v_mul_f32_e32 v7, v7, v29
	ds_write_b16 v8, v27 offset:14112
	v_mul_f32_e32 v5, v9, v5
	v_rcp_f32_e32 v27, v7
	v_cvt_pk_bf16_f32 v5, v5, s0
	v_cvt_pk_bf16_f32 v26, v26, s0
	ds_write_b16 v8, v5 offset:18720
	s_waitcnt vmcnt(28)
	v_lshlrev_b32_e32 v5, 16, v47
	ds_write_b16 v8, v26 offset:4896
	v_mul_f32_e32 v5, v7, v5
	v_sub_f32_e32 v26, 1.0, v29
	v_mul_f32_e32 v26, v26, v27
	v_cvt_pk_bf16_f32 v27, v5, s0
	v_mul_f32_e32 v7, v7, v30
	ds_write_b16 v8, v27 offset:14256
	v_mul_f32_e32 v5, v9, v5
	v_rcp_f32_e32 v27, v7
	v_cvt_pk_bf16_f32 v5, v5, s0
	v_cvt_pk_bf16_f32 v26, v26, s0
	ds_write_b16 v8, v5 offset:18864
	s_waitcnt vmcnt(27)
	v_lshlrev_b32_e32 v5, 16, v48
	ds_write_b16 v8, v26 offset:5040
	v_mul_f32_e32 v5, v7, v5
	v_sub_f32_e32 v26, 1.0, v30
	v_mul_f32_e32 v26, v26, v27
	v_cvt_pk_bf16_f32 v27, v5, s0
	v_mul_f32_e32 v7, v7, v31
	ds_write_b16 v8, v27 offset:14400
	v_mul_f32_e32 v5, v9, v5
	v_rcp_f32_e32 v27, v7
	v_cvt_pk_bf16_f32 v5, v5, s0
	v_cvt_pk_bf16_f32 v26, v26, s0
	ds_write_b16 v8, v5 offset:19008
	s_waitcnt vmcnt(26)
	v_lshlrev_b32_e32 v5, 16, v49
	ds_write_b16 v8, v26 offset:5184
	v_mul_f32_e32 v5, v7, v5
	v_sub_f32_e32 v26, 1.0, v31
	v_mul_f32_e32 v26, v26, v27
	v_cvt_pk_bf16_f32 v27, v5, s0
	v_mul_f32_e32 v7, v7, v32
	ds_write_b16 v8, v27 offset:14544
	v_mul_f32_e32 v5, v9, v5
	v_rcp_f32_e32 v27, v7
	v_cvt_pk_bf16_f32 v5, v5, s0
	v_cvt_pk_bf16_f32 v26, v26, s0
	ds_write_b16 v8, v5 offset:19152
	s_waitcnt vmcnt(25)
	v_lshlrev_b32_e32 v5, 16, v50
	ds_write_b16 v8, v26 offset:5328
	v_mul_f32_e32 v5, v7, v5
	v_sub_f32_e32 v26, 1.0, v32
	v_mul_f32_e32 v26, v26, v27
	v_cvt_pk_bf16_f32 v27, v5, s0
	v_mul_f32_e32 v7, v7, v33
	ds_write_b16 v8, v27 offset:14688
	v_mul_f32_e32 v5, v9, v5
	v_rcp_f32_e32 v27, v7
	v_cvt_pk_bf16_f32 v5, v5, s0
	v_cvt_pk_bf16_f32 v26, v26, s0
	ds_write_b16 v8, v5 offset:19296
	s_waitcnt vmcnt(24)
	v_lshlrev_b32_e32 v5, 16, v51
	ds_write_b16 v8, v26 offset:5472
	v_mul_f32_e32 v5, v7, v5
	v_sub_f32_e32 v26, 1.0, v33
	v_mul_f32_e32 v26, v26, v27
	v_cvt_pk_bf16_f32 v27, v5, s0
	v_mul_f32_e32 v7, v7, v34
	ds_write_b16 v8, v27 offset:14832
	v_mul_f32_e32 v5, v9, v5
	v_rcp_f32_e32 v27, v7
	v_cvt_pk_bf16_f32 v5, v5, s0
	v_cvt_pk_bf16_f32 v26, v26, s0
	ds_write_b16 v8, v5 offset:19440
	s_waitcnt vmcnt(23)
	v_lshlrev_b32_e32 v5, 16, v52
	ds_write_b16 v8, v26 offset:5616
	v_mul_f32_e32 v5, v7, v5
	v_sub_f32_e32 v26, 1.0, v34
	v_mul_f32_e32 v26, v26, v27
	v_cvt_pk_bf16_f32 v27, v5, s0
	v_mul_f32_e32 v7, v7, v35
	ds_write_b16 v8, v27 offset:14976
	v_mul_f32_e32 v5, v9, v5
	v_rcp_f32_e32 v27, v7
	v_cvt_pk_bf16_f32 v5, v5, s0
	v_cvt_pk_bf16_f32 v26, v26, s0
	ds_write_b16 v8, v5 offset:19584
	s_waitcnt vmcnt(22)
	v_lshlrev_b32_e32 v5, 16, v53
	ds_write_b16 v8, v26 offset:5760
	v_mul_f32_e32 v5, v7, v5
	v_sub_f32_e32 v26, 1.0, v35
	v_mul_f32_e32 v26, v26, v27
	v_cvt_pk_bf16_f32 v27, v5, s0
	v_mul_f32_e32 v7, v7, v36
	ds_write_b16 v8, v27 offset:15120
	v_mul_f32_e32 v5, v9, v5
	v_rcp_f32_e32 v27, v7
	v_cvt_pk_bf16_f32 v5, v5, s0
	v_cvt_pk_bf16_f32 v26, v26, s0
	ds_write_b16 v8, v5 offset:19728
	s_waitcnt vmcnt(21)
	v_lshlrev_b32_e32 v5, 16, v54
	ds_write_b16 v8, v26 offset:5904
	v_mul_f32_e32 v5, v7, v5
	v_sub_f32_e32 v26, 1.0, v36
	v_mul_f32_e32 v26, v26, v27
	v_cvt_pk_bf16_f32 v27, v5, s0
	v_mul_f32_e32 v7, v7, v37
	ds_write_b16 v8, v27 offset:15264
	v_mul_f32_e32 v5, v9, v5
	v_rcp_f32_e32 v27, v7
	v_cvt_pk_bf16_f32 v5, v5, s0
	v_cvt_pk_bf16_f32 v26, v26, s0
	ds_write_b16 v8, v5 offset:19872
	s_waitcnt vmcnt(20)
	v_lshlrev_b32_e32 v5, 16, v55
	ds_write_b16 v8, v26 offset:6048
	v_mul_f32_e32 v5, v7, v5
	v_sub_f32_e32 v26, 1.0, v37
	v_mul_f32_e32 v26, v26, v27
	v_cvt_pk_bf16_f32 v27, v5, s0
	v_mul_f32_e32 v7, v7, v38
	ds_write_b16 v8, v27 offset:15408
	v_mul_f32_e32 v5, v9, v5
	v_rcp_f32_e32 v27, v7
	v_cvt_pk_bf16_f32 v5, v5, s0
	v_cvt_pk_bf16_f32 v26, v26, s0
	ds_write_b16 v8, v5 offset:20016
	s_waitcnt vmcnt(19)
	v_lshlrev_b32_e32 v5, 16, v56
	ds_write_b16 v8, v26 offset:6192
	v_mul_f32_e32 v5, v7, v5
	v_sub_f32_e32 v26, 1.0, v38
	v_mul_f32_e32 v26, v26, v27
	v_cvt_pk_bf16_f32 v27, v5, s0
	v_mul_f32_e32 v7, v7, v39
	ds_write_b16 v8, v27 offset:15552
	v_mul_f32_e32 v5, v9, v5
	v_rcp_f32_e32 v27, v7
	v_cvt_pk_bf16_f32 v5, v5, s0
	v_cvt_pk_bf16_f32 v26, v26, s0
	ds_write_b16 v8, v5 offset:20160
	s_waitcnt vmcnt(18)
	v_lshlrev_b32_e32 v5, 16, v57
	ds_write_b16 v8, v26 offset:6336
	v_mul_f32_e32 v5, v7, v5
	v_sub_f32_e32 v26, 1.0, v39
	v_mul_f32_e32 v26, v26, v27
	v_cvt_pk_bf16_f32 v27, v5, s0
	v_mul_f32_e32 v7, v7, v40
	ds_write_b16 v8, v27 offset:15696
	v_mul_f32_e32 v5, v9, v5
	v_rcp_f32_e32 v27, v7
	v_cvt_pk_bf16_f32 v5, v5, s0
	v_cvt_pk_bf16_f32 v26, v26, s0
	ds_write_b16 v8, v5 offset:20304
	s_waitcnt vmcnt(17)
	v_lshlrev_b32_e32 v5, 16, v58
	ds_write_b16 v8, v26 offset:6480
	v_mul_f32_e32 v5, v7, v5
	v_sub_f32_e32 v26, 1.0, v40
	v_mul_f32_e32 v26, v26, v27
	v_cvt_pk_bf16_f32 v27, v5, s0
	v_mul_f32_e32 v7, v7, v41
	ds_write_b16 v8, v27 offset:15840
	v_mul_f32_e32 v5, v9, v5
	v_rcp_f32_e32 v27, v7
	v_cvt_pk_bf16_f32 v5, v5, s0
	v_cvt_pk_bf16_f32 v26, v26, s0
	ds_write_b16 v8, v5 offset:20448
	s_waitcnt vmcnt(16)
	v_lshlrev_b32_e32 v5, 16, v59
	ds_write_b16 v8, v26 offset:6624
	v_mul_f32_e32 v5, v7, v5
	v_sub_f32_e32 v26, 1.0, v41
	v_mul_f32_e32 v26, v26, v27
	v_cvt_pk_bf16_f32 v27, v5, s0
	v_mul_f32_e32 v7, v7, v42
	ds_write_b16 v8, v27 offset:15984
	v_rcp_f32_e32 v27, v7
	v_cvt_pk_bf16_f32 v26, v26, s0
	v_mul_f32_e32 v5, v9, v5
	ds_write_b16 v8, v26 offset:6768
	v_cvt_pk_bf16_f32 v5, v5, s0
	v_sub_f32_e32 v26, 1.0, v42
	ds_write_b16 v8, v5 offset:20592
	s_waitcnt vmcnt(15)
	v_lshlrev_b32_e32 v5, 16, v60
	v_mul_f32_e32 v26, v26, v27
	v_mul_f32_e32 v5, v7, v5
	v_cvt_pk_bf16_f32 v26, v26, s0
	v_mul_f32_e32 v7, v7, v23
	ds_write_b16 v8, v26 offset:6912
	v_rcp_f32_e32 v26, v7
	v_cvt_pk_bf16_f32 v27, v5, s0
	v_mul_f32_e32 v5, v9, v5
	v_cvt_pk_bf16_f32 v5, v5, s0
	v_sub_f32_e32 v23, 1.0, v23
	ds_write_b16 v8, v5 offset:20736
	s_waitcnt vmcnt(14)
	v_lshlrev_b32_e32 v5, 16, v61
	v_mul_f32_e32 v23, v23, v26
	v_mul_f32_e32 v5, v7, v5
	v_cvt_pk_bf16_f32 v23, v23, s0
	v_mul_f32_e32 v7, v7, v22
	ds_write_b16 v8, v23 offset:7056
	v_rcp_f32_e32 v23, v7
	v_cvt_pk_bf16_f32 v26, v5, s0
	v_mul_f32_e32 v5, v9, v5
	v_cvt_pk_bf16_f32 v5, v5, s0
	v_sub_f32_e32 v22, 1.0, v22
	ds_write_b16 v8, v5 offset:20880
	s_waitcnt vmcnt(13)
	v_lshlrev_b32_e32 v5, 16, v62
	v_mul_f32_e32 v22, v22, v23
	v_mul_f32_e32 v5, v7, v5
	v_cvt_pk_bf16_f32 v22, v22, s0
	v_mul_f32_e32 v7, v7, v20
	ds_write_b16 v8, v22 offset:7200
	v_rcp_f32_e32 v22, v7
	v_cvt_pk_bf16_f32 v23, v5, s0
	v_mul_f32_e32 v5, v9, v5
	v_cvt_pk_bf16_f32 v5, v5, s0
	v_sub_f32_e32 v20, 1.0, v20
	ds_write_b16 v8, v5 offset:21024
	s_waitcnt vmcnt(12)
	v_lshlrev_b32_e32 v5, 16, v63
	v_mul_f32_e32 v20, v20, v22
	v_mul_f32_e32 v5, v7, v5
	v_cvt_pk_bf16_f32 v20, v20, s0
	v_mul_f32_e32 v7, v7, v21
	ds_write_b16 v8, v20 offset:7344
	v_sub_f32_e32 v20, 1.0, v21
	v_rcp_f32_e32 v21, v7
	v_cvt_pk_bf16_f32 v22, v5, s0
	v_mul_f32_e32 v5, v9, v5
	v_cvt_pk_bf16_f32 v5, v5, s0
	ds_write_b16 v8, v5 offset:21168
	s_waitcnt vmcnt(11)
	v_lshlrev_b32_e32 v5, 16, v64
	v_mul_f32_e32 v20, v20, v21
	v_mul_f32_e32 v5, v7, v5
	v_cvt_pk_bf16_f32 v20, v20, s0
	v_mul_f32_e32 v7, v7, v19
	ds_write_b16 v8, v20 offset:7488
	v_rcp_f32_e32 v20, v7
	v_cvt_pk_bf16_f32 v21, v5, s0
	v_mul_f32_e32 v5, v9, v5
	v_cvt_pk_bf16_f32 v5, v5, s0
	v_sub_f32_e32 v19, 1.0, v19
	ds_write_b16 v8, v5 offset:21312
	s_waitcnt vmcnt(10)
	v_lshlrev_b32_e32 v5, 16, v65
	v_mul_f32_e32 v19, v19, v20
	v_mul_f32_e32 v5, v7, v5
	v_cvt_pk_bf16_f32 v19, v19, s0
	v_mul_f32_e32 v7, v7, v18
	ds_write_b16 v8, v19 offset:7632
	v_rcp_f32_e32 v19, v7
	v_cvt_pk_bf16_f32 v20, v5, s0
	v_mul_f32_e32 v5, v9, v5
	v_cvt_pk_bf16_f32 v5, v5, s0
	v_sub_f32_e32 v18, 1.0, v18
	ds_write_b16 v8, v5 offset:21456
	s_waitcnt vmcnt(9)
	v_lshlrev_b32_e32 v5, 16, v66
	v_mul_f32_e32 v18, v18, v19
	v_mul_f32_e32 v5, v7, v5
	v_cvt_pk_bf16_f32 v18, v18, s0
	v_mul_f32_e32 v7, v7, v16
	ds_write_b16 v8, v18 offset:7776
	v_rcp_f32_e32 v18, v7
	v_cvt_pk_bf16_f32 v19, v5, s0
	v_mul_f32_e32 v5, v9, v5
	v_cvt_pk_bf16_f32 v5, v5, s0
	v_sub_f32_e32 v16, 1.0, v16
	ds_write_b16 v8, v5 offset:21600
	s_waitcnt vmcnt(8)
	v_lshlrev_b32_e32 v5, 16, v24
	v_mul_f32_e32 v16, v16, v18
	v_mul_f32_e32 v5, v7, v5
	v_cvt_pk_bf16_f32 v16, v16, s0
	v_mul_f32_e32 v7, v7, v17
	ds_write_b16 v8, v16 offset:7920
	v_sub_f32_e32 v16, 1.0, v17
	v_rcp_f32_e32 v17, v7
	v_cvt_pk_bf16_f32 v18, v5, s0
	v_mul_f32_e32 v5, v9, v5
	v_cvt_pk_bf16_f32 v5, v5, s0
	ds_write_b16 v8, v5 offset:21744
	s_waitcnt vmcnt(7)
	v_lshlrev_b32_e32 v5, 16, v25
	v_mul_f32_e32 v16, v16, v17
	v_mul_f32_e32 v5, v7, v5
	v_cvt_pk_bf16_f32 v16, v16, s0
	v_mul_f32_e32 v7, v7, v15
	ds_write_b16 v8, v16 offset:8064
	v_rcp_f32_e32 v16, v7
	v_cvt_pk_bf16_f32 v17, v5, s0
	v_mul_f32_e32 v5, v9, v5
	v_cvt_pk_bf16_f32 v5, v5, s0
	v_sub_f32_e32 v15, 1.0, v15
	ds_write_b16 v8, v5 offset:21888
	s_waitcnt vmcnt(6)
	v_lshlrev_b32_e32 v5, 16, v67
	v_mul_f32_e32 v15, v15, v16
	v_mul_f32_e32 v5, v7, v5
	v_cvt_pk_bf16_f32 v15, v15, s0
	v_mul_f32_e32 v7, v7, v14
	ds_write_b16 v8, v15 offset:8208
	v_rcp_f32_e32 v15, v7
	v_cvt_pk_bf16_f32 v16, v5, s0
	v_mul_f32_e32 v5, v9, v5
	v_cvt_pk_bf16_f32 v5, v5, s0
	v_sub_f32_e32 v14, 1.0, v14
	ds_write_b16 v8, v5 offset:22032
	s_waitcnt vmcnt(5)
	v_lshlrev_b32_e32 v5, 16, v68
	v_mul_f32_e32 v14, v14, v15
	v_mul_f32_e32 v5, v7, v5
	v_cvt_pk_bf16_f32 v14, v14, s0
	v_mul_f32_e32 v7, v7, v13
	ds_write_b16 v8, v14 offset:8352
	v_rcp_f32_e32 v14, v7
	v_cvt_pk_bf16_f32 v15, v5, s0
	v_mul_f32_e32 v5, v9, v5
	v_cvt_pk_bf16_f32 v5, v5, s0
	v_sub_f32_e32 v13, 1.0, v13
	ds_write_b16 v8, v5 offset:22176
	s_waitcnt vmcnt(4)
	v_lshlrev_b32_e32 v5, 16, v69
	v_mul_f32_e32 v13, v13, v14
	v_mul_f32_e32 v5, v7, v5
	v_cvt_pk_bf16_f32 v13, v13, s0
	v_mul_f32_e32 v7, v7, v12
	ds_write_b16 v8, v13 offset:8496
	v_rcp_f32_e32 v13, v7
	v_cvt_pk_bf16_f32 v14, v5, s0
	v_mul_f32_e32 v5, v9, v5
	v_cvt_pk_bf16_f32 v5, v5, s0
	v_sub_f32_e32 v12, 1.0, v12
	ds_write_b16 v8, v5 offset:22320
	s_waitcnt vmcnt(3)
	v_lshlrev_b32_e32 v5, 16, v71
	v_mul_f32_e32 v12, v12, v13
	v_mul_f32_e32 v5, v7, v5
	v_cvt_pk_bf16_f32 v12, v12, s0
	v_mul_f32_e32 v7, v7, v11
	ds_write_b16 v8, v12 offset:8640
	v_rcp_f32_e32 v12, v7
	v_cvt_pk_bf16_f32 v13, v5, s0
	v_mul_f32_e32 v5, v9, v5
	v_cvt_pk_bf16_f32 v5, v5, s0
	v_sub_f32_e32 v11, 1.0, v11
	ds_write_b16 v8, v5 offset:22464
	s_waitcnt vmcnt(2)
	v_lshlrev_b32_e32 v5, 16, v72
	v_mul_f32_e32 v11, v11, v12
	v_mul_f32_e32 v5, v7, v5
	v_cvt_pk_bf16_f32 v11, v11, s0
	v_mul_f32_e32 v7, v7, v10
	v_cvt_pk_bf16_f32 v12, v5, s0
	ds_write_b16 v8, v11 offset:8784
	v_mul_f32_e32 v5, v9, v5
	v_rcp_f32_e32 v11, v7
	v_cvt_pk_bf16_f32 v5, v5, s0
	ds_write_b16 v8, v5 offset:22608
	s_waitcnt vmcnt(1)
	v_lshlrev_b32_e32 v5, 16, v73
	v_mul_f32_e32 v5, v7, v5
	v_sub_f32_e32 v10, 1.0, v10
	v_mul_f32_e32 v10, v10, v11
	v_cvt_pk_bf16_f32 v11, v5, s0
	v_mul_f32_e32 v5, v9, v5
	v_cvt_pk_bf16_f32 v5, v5, s0
	ds_write_b16 v8, v5 offset:22752
	s_waitcnt vmcnt(0)
	v_lshlrev_b32_e32 v4, 16, v4
	v_mul_f32_e32 v5, v7, v6
	v_mul_f32_e32 v4, v5, v4
	v_rcp_f32_e32 v5, v5
	v_sub_f32_e32 v6, 1.0, v6
	v_cvt_pk_bf16_f32 v10, v10, s0
	ds_write_b16 v8, v44 offset:13824
	v_mul_f32_e32 v5, v6, v5
	v_cvt_pk_bf16_f32 v6, v4, s0
	v_mul_f32_e32 v4, v9, v4
	v_cvt_pk_bf16_f32 v5, v5, s0
	v_cvt_pk_bf16_f32 v4, v4, s0
	v_readlane_b32 s0, v254, 46
	v_readlane_b32 s1, v254, 47
	s_add_u32 s0, s0, s40
	s_addc_u32 s1, s1, s41
	s_add_u32 s88, s0, s9
	s_addc_u32 s89, s1, 0
	ds_write_b16 v8, v27 offset:16128
	ds_write_b16 v8, v26 offset:16272
	ds_write_b16 v8, v23 offset:16416
	ds_write_b16 v8, v22 offset:16560
	ds_write_b16 v8, v21 offset:16704
	ds_write_b16 v8, v20 offset:16848
	ds_write_b16 v8, v19 offset:16992
	ds_write_b16 v8, v18 offset:17136
	ds_write_b16 v8, v17 offset:17280
	ds_write_b16 v8, v16 offset:17424
	ds_write_b16 v8, v15 offset:17568
	ds_write_b16 v8, v14 offset:17712
	ds_write_b16 v8, v13 offset:17856
	ds_write_b16 v8, v12 offset:18000
	ds_write_b16 v8, v11 offset:18144
	ds_write_b16 v8, v10 offset:8928
	ds_write_b16 v8, v6 offset:18288
	ds_write_b16 v8, v5 offset:9072
	ds_write_b16 v8, v4 offset:22896
	v_lshl_add_u64 v[2:3], s[88:89], 0, v[2:3]
	v_add_co_u32_e32 v4, vcc, s85, v2
	s_waitcnt lgkmcnt(0)
	v_and_b32_e32 v71, 31, v70
	s_nop 0
	v_addc_co_u32_e32 v5, vcc, 0, v3, vcc
	global_load_ushort v136, v[4:5], off offset:3584
	global_load_ushort v137, v[4:5], off offset:3072
	v_ashrrev_i32_e32 v72, 5, v70
	v_lshlrev_b32_e32 v74, 3, v72
	s_or_b32 s0, s4, s5
	s_mul_hi_i32 s1, s11, 0x2100
	s_add_i32 s0, s0, 4
	s_lshl_b64 s[0:1], s[0:1], 8
	v_readlane_b32 s4, v254, 56
	v_readlane_b32 s5, v254, 57
	s_add_u32 s4, s4, s0
	global_load_ushort v138, v[4:5], off offset:2560
	global_load_ushort v139, v[4:5], off offset:2048
	global_load_ushort v140, v[4:5], off offset:1536
	global_load_ushort v141, v[4:5], off offset:1024
	global_load_ushort v142, v[4:5], off offset:512
	s_nop 0
	global_load_ushort v143, v[4:5], off
	v_add_co_u32_e32 v4, vcc, s95, v2
	s_nop 1
	v_addc_co_u32_e32 v5, vcc, 0, v3, vcc
	global_load_ushort v144, v[4:5], off offset:3584
	global_load_ushort v145, v[4:5], off offset:3072
	global_load_ushort v146, v[4:5], off offset:2560
	global_load_ushort v147, v[4:5], off offset:2048
	global_load_ushort v148, v[4:5], off offset:1536
	global_load_ushort v149, v[4:5], off offset:1024
	global_load_ushort v150, v[4:5], off offset:512
	s_nop 0
	global_load_ushort v151, v[4:5], off
	v_add_co_u32_e32 v4, vcc, s92, v2
	s_nop 1
	v_addc_co_u32_e32 v5, vcc, 0, v3, vcc
	global_load_ushort v152, v[4:5], off offset:3584
	global_load_ushort v153, v[4:5], off offset:3072
	global_load_ushort v154, v[4:5], off offset:2560
	global_load_ushort v155, v[4:5], off offset:2048
	global_load_ushort v156, v[4:5], off offset:1536
	global_load_ushort v157, v[4:5], off offset:1024
	global_load_ushort v158, v[4:5], off offset:512
	s_nop 0
	global_load_ushort v159, v[4:5], off
	v_add_co_u32_e32 v4, vcc, s81, v2
	s_nop 1
	v_addc_co_u32_e32 v5, vcc, 0, v3, vcc
	global_load_ushort v160, v[4:5], off offset:3584
	global_load_ushort v161, v[4:5], off offset:3072
	global_load_ushort v162, v[4:5], off offset:2560
	global_load_ushort v163, v[4:5], off offset:2048
	global_load_ushort v164, v[4:5], off offset:1536
	global_load_ushort v165, v[4:5], off offset:1024
	global_load_ushort v166, v[4:5], off offset:512
	s_nop 0
	global_load_ushort v167, v[4:5], off
	v_add_co_u32_e32 v4, vcc, s87, v2
	s_nop 1
	v_addc_co_u32_e32 v5, vcc, 0, v3, vcc
	global_load_ushort v168, v[4:5], off offset:3584
	global_load_ushort v169, v[4:5], off offset:3072
	global_load_ushort v170, v[4:5], off offset:2560
	global_load_ushort v171, v[4:5], off offset:2048
	global_load_ushort v172, v[4:5], off offset:1536
	global_load_ushort v173, v[4:5], off offset:1024
	global_load_ushort v174, v[4:5], off offset:512
	s_nop 0
	global_load_ushort v175, v[4:5], off
	v_add_co_u32_e32 v4, vcc, s93, v2
	s_nop 1
	v_addc_co_u32_e32 v5, vcc, 0, v3, vcc
	global_load_ushort v176, v[4:5], off offset:3584
	global_load_ushort v177, v[4:5], off offset:3072
	global_load_ushort v178, v[4:5], off offset:2560
	global_load_ushort v179, v[4:5], off offset:2048
	global_load_ushort v192, v[4:5], off offset:1536
	global_load_ushort v193, v[4:5], off offset:1024
	global_load_ushort v194, v[4:5], off offset:512
	s_nop 0
	global_load_ushort v195, v[4:5], off
	v_add_co_u32_e32 v4, vcc, s15, v2
	s_nop 1
	v_addc_co_u32_e32 v5, vcc, 0, v3, vcc
	global_load_ushort v196, v[4:5], off offset:3584
	global_load_ushort v197, v[4:5], off offset:3072
	global_load_ushort v198, v[4:5], off offset:2560
	global_load_ushort v199, v[4:5], off offset:2048
	global_load_ushort v200, v[4:5], off offset:1536
	global_load_ushort v201, v[4:5], off offset:1024
	global_load_ushort v202, v[4:5], off offset:512
	s_nop 0
	global_load_ushort v203, v[4:5], off
	global_load_ushort v204, v[2:3], off offset:3584
	global_load_ushort v205, v[2:3], off offset:3072
	global_load_ushort v206, v[2:3], off offset:2560
	global_load_ushort v207, v[2:3], off offset:2048
	global_load_ushort v224, v[2:3], off offset:1536
	global_load_ushort v225, v[2:3], off offset:1024
	global_load_ushort v226, v[2:3], off offset:512
	s_nop 0
	global_load_ushort v227, v[2:3], off
	s_waitcnt vmcnt(0)
	v_lshl_or_b32 v34, v137, 16, v136
	v_lshl_or_b32 v35, v139, 16, v138
	v_lshl_or_b32 v36, v141, 16, v140
	v_lshl_or_b32 v37, v143, 16, v142
	v_lshl_or_b32 v38, v145, 16, v144
	v_lshl_or_b32 v39, v147, 16, v146
	v_lshl_or_b32 v40, v149, 16, v148
	v_lshl_or_b32 v41, v151, 16, v150
	v_lshl_or_b32 v42, v153, 16, v152
	v_lshl_or_b32 v43, v155, 16, v154
	v_lshl_or_b32 v44, v157, 16, v156
	v_lshl_or_b32 v45, v159, 16, v158
	v_lshl_or_b32 v46, v161, 16, v160
	v_lshl_or_b32 v47, v163, 16, v162
	v_lshl_or_b32 v48, v165, 16, v164
	v_lshl_or_b32 v49, v167, 16, v166
	v_lshl_or_b32 v50, v169, 16, v168
	v_lshl_or_b32 v51, v171, 16, v170
	v_lshl_or_b32 v52, v173, 16, v172
	v_lshl_or_b32 v53, v175, 16, v174
	v_lshl_or_b32 v54, v177, 16, v176
	v_lshl_or_b32 v55, v179, 16, v178
	v_lshl_or_b32 v56, v193, 16, v192
	v_lshl_or_b32 v57, v195, 16, v194
	v_lshl_or_b32 v58, v197, 16, v196
	v_lshl_or_b32 v59, v199, 16, v198
	v_lshl_or_b32 v60, v201, 16, v200
	v_lshl_or_b32 v61, v203, 16, v202
	v_lshl_or_b32 v62, v205, 16, v204
	v_lshl_or_b32 v63, v207, 16, v206
	v_lshl_or_b32 v64, v225, 16, v224
	v_lshl_or_b32 v65, v227, 16, v226
	v_mul_u32_u24_e32 v2, 0x48, v71
	v_lshl_add_u32 v75, v2, 1, s7
	v_lshl_add_u32 v73, v72, 4, v75
	ds_read_b128 v[18:21], v73 offset:4608
	ds_read_b128 v[2:5], v73 offset:9216
	ds_read_b128 v[22:25], v73 offset:13824
	ds_read_b128 v[66:69], v73 offset:18432
	ds_read_b128 v[76:79], v73
	ds_read_b128 v[80:83], v73 offset:32
	s_waitcnt lgkmcnt(3)
	v_mfma_f32_32x32x16_bf16 v[18:33], v[18:21], v[22:25], 0
	ds_read_b128 v[84:87], v73 offset:4640
	ds_read_b128 v[88:91], v73 offset:9248
	ds_read_b128 v[92:95], v73 offset:13856
	ds_read_b128 v[96:99], v73 offset:18464
	v_lshlrev_b32_e32 v72, 2, v72
	v_cmp_gt_i32_e32 vcc, v72, v71
	v_cmp_lt_i32_e64 s[40:41], v72, v71
	s_waitcnt lgkmcnt(5)
	v_mfma_f32_32x32x16_bf16 v[2:17], v[76:79], v[2:5], 0
	s_waitcnt lgkmcnt(1)
	v_mfma_f32_32x32x16_bf16 v[18:33], v[84:87], v[92:95], v[18:33]
	v_mfma_f32_32x32x16_bf16 v[2:17], v[80:83], v[88:91], v[2:17]
	ds_read_b128 v[84:87], v73 offset:64
	ds_read_b128 v[88:91], v73 offset:4672
	ds_read_b128 v[92:95], v73 offset:9280
	ds_read_b128 v[100:103], v73 offset:13888
	ds_read_b128 v[104:107], v73 offset:18496
	s_waitcnt lgkmcnt(1)
	v_mfma_f32_32x32x16_bf16 v[18:33], v[88:91], v[100:103], v[18:33]
	v_mfma_f32_32x32x16_bf16 v[2:17], v[84:87], v[92:95], v[2:17]
	ds_read_b128 v[88:91], v73 offset:96
	ds_read_b128 v[92:95], v73 offset:4704
	ds_read_b128 v[100:103], v73 offset:9312
	ds_read_b128 v[108:111], v73 offset:13920
	ds_read_b128 v[112:115], v73 offset:18528
	s_waitcnt lgkmcnt(1)
	v_mfma_f32_32x32x16_bf16 v[18:33], v[92:95], v[108:111], v[18:33]
	v_mfma_f32_32x32x16_bf16 v[2:17], v[88:91], v[100:103], v[2:17]
	s_nop 10
	v_cndmask_b32_e64 v92, v18, 0, vcc
	v_cndmask_b32_e64 v92, v92, v18, s[40:41]
	v_or_b32_e32 v18, 2, v72
	v_cmp_gt_i32_e64 s[42:43], v18, v71
	v_or_b32_e32 v18, 3, v72
	v_cmp_gt_i32_e64 s[44:45], v18, v71
	v_add_u32_e32 v18, 8, v72
	v_cmp_gt_i32_e64 s[46:47], v18, v71
	v_cmp_lt_i32_e64 s[48:49], v18, v71
	v_add_u32_e32 v18, 10, v72
	v_cmp_gt_i32_e64 s[50:51], v18, v71
	v_add_u32_e32 v18, 11, v72
	v_cmp_gt_i32_e64 s[54:55], v18, v71
	v_add_u32_e32 v18, 16, v72
	v_cmp_gt_i32_e64 s[56:57], v18, v71
	v_cmp_lt_i32_e64 s[58:59], v18, v71
	v_add_u32_e32 v18, 18, v72
	v_cmp_gt_i32_e64 s[60:61], v18, v71
	v_add_u32_e32 v18, 19, v72
	v_cmp_gt_i32_e64 s[62:63], v18, v71
	v_add_u32_e32 v18, 24, v72
	v_cndmask_b32_e64 v93, 0, v19, s[40:41]
	v_cndmask_b32_e64 v19, v22, 0, s[46:47]
	v_cmp_gt_i32_e64 s[64:65], v18, v71
	v_cmp_lt_i32_e64 s[66:67], v18, v71
	v_add_u32_e32 v18, 26, v72
	v_cndmask_b32_e64 v100, v19, v22, s[48:49]
	v_cndmask_b32_e64 v19, v26, 0, s[56:57]
	v_cmp_gt_i32_e64 s[68:69], v18, v71
	v_add_u32_e32 v18, 27, v72
	v_cndmask_b32_e64 v108, v19, v26, s[58:59]
	v_cndmask_b32_e64 v19, v30, 0, s[64:65]
	v_cmp_gt_i32_e64 s[70:71], v18, v71
	v_cndmask_b32_e64 v94, v20, 0, s[42:43]
	v_cndmask_b32_e64 v95, v21, 0, s[44:45]
	v_cndmask_b32_e64 v101, 0, v23, s[48:49]
	v_cndmask_b32_e64 v102, v24, 0, s[50:51]
	v_cndmask_b32_e64 v103, v25, 0, s[54:55]
	v_cndmask_b32_e64 v109, 0, v27, s[58:59]
	v_cndmask_b32_e64 v110, v28, 0, s[60:61]
	v_cndmask_b32_e64 v111, v29, 0, s[62:63]
	v_cndmask_b32_e64 v116, v19, v30, s[66:67]
	v_cndmask_b32_e64 v117, 0, v31, s[66:67]
	v_cndmask_b32_e64 v118, v32, 0, s[68:69]
	v_cndmask_b32_e64 v71, v33, 0, s[70:71]
	v_mfma_f32_32x32x16_bf16 v[18:33], v[76:79], v[66:69], 0
	v_mul_lo_u32 v66, v70, s14
	v_add_u32_e32 v66, s7, v66
	ds_write_b128 v66, v[34:37]
	ds_write_b128 v66, v[38:41] offset:16
	ds_write_b128 v66, v[42:45] offset:32
	ds_write_b128 v66, v[46:49] offset:48
	ds_write_b128 v66, v[50:53] offset:64
	ds_write_b128 v66, v[54:57] offset:80
	ds_write_b128 v66, v[58:61] offset:96
	ds_write_b128 v66, v[62:65] offset:112
	v_cndmask_b32_e64 v34, v2, 0, vcc
	v_cndmask_b32_e64 v2, v34, v2, s[40:41]
	v_cndmask_b32_e64 v34, v6, 0, s[46:47]
	v_cndmask_b32_e64 v6, v34, v6, s[48:49]
	v_mfma_f32_32x32x16_bf16 v[18:33], v[80:83], v[96:99], v[18:33]
	v_cndmask_b32_e64 v34, v10, 0, s[56:57]
	v_cndmask_b32_e64 v10, v34, v10, s[58:59]
	v_cndmask_b32_e64 v34, v14, 0, s[64:65]
	v_cndmask_b32_e64 v3, 0, v3, s[40:41]
	v_cndmask_b32_e64 v4, v4, 0, s[42:43]
	v_cndmask_b32_e64 v5, v5, 0, s[44:45]
	v_cndmask_b32_e64 v7, 0, v7, s[48:49]
	v_mfma_f32_32x32x16_bf16 v[18:33], v[84:87], v[104:107], v[18:33]
	v_cndmask_b32_e64 v8, v8, 0, s[50:51]
	v_cndmask_b32_e64 v9, v9, 0, s[54:55]
	v_cndmask_b32_e64 v11, 0, v11, s[58:59]
	v_cndmask_b32_e64 v12, v12, 0, s[60:61]
	v_cndmask_b32_e64 v13, v13, 0, s[62:63]
	v_cndmask_b32_e64 v14, v34, v14, s[66:67]
	v_cndmask_b32_e64 v15, 0, v15, s[66:67]
	s_waitcnt lgkmcnt(8)
	v_mfma_f32_32x32x16_bf16 v[18:33], v[88:91], v[112:115], v[18:33]
	v_cndmask_b32_e64 v16, v16, 0, s[68:69]
	v_cndmask_b32_e64 v17, v17, 0, s[70:71]
	v_add_u32_e32 v66, v75, v74
	v_cvt_pk_bf16_f32 v2, v2, v3
	v_cvt_pk_bf16_f32 v3, v4, v5
	v_cvt_pk_bf16_f32 v4, v6, v7
	v_cvt_pk_bf16_f32 v5, v8, v9
	s_nop 4
	v_cvt_pk_bf16_f32 v38, v18, v19
	v_cvt_pk_bf16_f32 v39, v20, v21
	v_cvt_pk_bf16_f32 v40, v22, v23
	v_cvt_pk_bf16_f32 v41, v24, v25
	v_cvt_pk_bf16_f32 v42, v10, v11
	v_cvt_pk_bf16_f32 v43, v12, v13
	v_cvt_pk_bf16_f32 v44, v14, v15
	v_cvt_pk_bf16_f32 v45, v16, v17
	ds_read2_b64 v[6:9], v66 offset0:8 offset1:10
	ds_read2_b64 v[10:13], v66 offset1:2
	ds_read2_b64 v[14:17], v66 offset0:4 offset1:6
	v_cvt_pk_bf16_f32 v34, v92, v93
	v_cvt_pk_bf16_f32 v35, v94, v95
	s_waitcnt lgkmcnt(1)
	v_mfma_f32_32x32x16_bf16 v[82:97], v[38:41], v[10:13], 0
	v_cvt_pk_bf16_f32 v36, v100, v101
	v_cvt_pk_bf16_f32 v37, v102, v103
	v_cvt_pk_bf16_f32 v50, v26, v27
	v_cvt_pk_bf16_f32 v51, v28, v29
	v_cvt_pk_bf16_f32 v52, v30, v31
	v_cvt_pk_bf16_f32 v53, v32, v33
	v_cvt_pk_bf16_f32 v46, v108, v109
	v_mfma_f32_32x32x16_bf16 v[82:97], v[34:37], v[6:9], v[82:97]
	v_cvt_pk_bf16_f32 v47, v110, v111
	v_cvt_pk_bf16_f32 v48, v116, v117
	v_cvt_pk_bf16_f32 v49, v118, v71
	ds_read2_b64 v[6:9], v66 offset0:12 offset1:14
	v_add_u32_e32 v122, v66, v74
	v_add_u32_e32 v123, 0x1000, v66
	v_readlane_b32 s40, v254, 56
	v_mfma_f32_32x32x16_bf16 v[18:33], v[2:5], v[10:13], 0
	v_readlane_b32 s41, v254, 57
	s_addc_u32 s5, s41, s1
	v_readlane_b32 s0, v254, 25
	v_readlane_b32 s1, v254, 26
	s_add_u32 s0, s0, s36
	s_addc_u32 s1, s1, s37
	s_add_u32 s0, s0, s10
	s_waitcnt lgkmcnt(1)
	v_mfma_f32_32x32x16_bf16 v[82:97], v[50:53], v[14:17], v[82:97]
	s_addc_u32 s1, s1, 0
	v_readlane_b32 s36, v254, 56
	v_readlane_b32 s37, v254, 57
	v_mfma_f32_32x32x16_bf16 v[18:33], v[42:45], v[14:17], v[18:33]
	s_waitcnt lgkmcnt(0)
	v_mfma_f32_32x32x16_bf16 v[82:97], v[46:49], v[6:9], v[82:97]
	ds_read_b128 v[54:57], v73 offset:18432
	ds_read_b128 v[6:9], v122 offset:23040
	ds_read_b128 v[10:13], v122 offset:23072
	ds_read_b128 v[58:61], v73 offset:9216
	ds_read_b128 v[62:65], v73 offset:9248
	ds_read_b128 v[98:101], v73 offset:18464
	s_waitcnt lgkmcnt(2)
	v_mfma_f32_32x32x16_bf16 v[18:33], v[58:61], v[6:9], v[18:33]
	v_mfma_f32_32x32x16_bf16 v[82:97], v[54:57], v[6:9], v[82:97]
	ds_read_b128 v[6:9], v122 offset:23104
	ds_read_b128 v[102:105], v73 offset:9280
	ds_read_b128 v[106:109], v73 offset:18496
	s_waitcnt lgkmcnt(4)
	v_mfma_f32_32x32x16_bf16 v[18:33], v[62:65], v[10:13], v[18:33]
	s_waitcnt lgkmcnt(3)
	v_mfma_f32_32x32x16_bf16 v[82:97], v[98:101], v[10:13], v[82:97]
	s_waitcnt lgkmcnt(1)
	v_mfma_f32_32x32x16_bf16 v[18:33], v[102:105], v[6:9], v[18:33]
	s_waitcnt lgkmcnt(0)
	v_mfma_f32_32x32x16_bf16 v[82:97], v[106:109], v[6:9], v[82:97]
	ds_read_b128 v[6:9], v122 offset:23136
	ds_read_b128 v[110:113], v73 offset:9312
	ds_read_b128 v[114:117], v73 offset:18528
	ds_read2_b64 v[66:69], v123 offset0:64 offset1:66
	ds_read2_b64 v[118:121], v123 offset0:72 offset1:74
	s_waitcnt lgkmcnt(3)
	v_mfma_f32_32x32x16_bf16 v[18:33], v[110:113], v[6:9], v[18:33]
	s_waitcnt lgkmcnt(2)
	v_mfma_f32_32x32x16_bf16 v[82:97], v[114:117], v[6:9], v[82:97]
	s_waitcnt lgkmcnt(1)
	v_mfma_f32_32x32x16_bf16 v[2:17], v[2:5], v[66:69], 0
	v_mfma_f32_32x32x16_bf16 v[66:81], v[38:41], v[66:69], 0
	s_waitcnt lgkmcnt(0)
	v_mfma_f32_32x32x16_bf16 v[66:81], v[34:37], v[118:121], v[66:81]
	ds_read2_b64 v[34:37], v123 offset0:68 offset1:70
	ds_read2_b64 v[38:41], v123 offset0:76 offset1:78
	s_waitcnt lgkmcnt(1)
	v_mfma_f32_32x32x16_bf16 v[66:81], v[50:53], v[34:37], v[66:81]
	v_mfma_f32_32x32x16_bf16 v[2:17], v[42:45], v[34:37], v[2:17]
	ds_read_b128 v[34:37], v122 offset:27648
	s_waitcnt lgkmcnt(1)
	v_mfma_f32_32x32x16_bf16 v[66:81], v[46:49], v[38:41], v[66:81]
	s_waitcnt lgkmcnt(0)
	v_mfma_f32_32x32x16_bf16 v[2:17], v[58:61], v[34:37], v[2:17]
	v_mfma_f32_32x32x16_bf16 v[66:81], v[54:57], v[34:37], v[66:81]
	ds_read_b128 v[34:37], v122 offset:27680
	s_waitcnt lgkmcnt(0)
	v_mfma_f32_32x32x16_bf16 v[2:17], v[62:65], v[34:37], v[2:17]
	v_mfma_f32_32x32x16_bf16 v[66:81], v[98:101], v[34:37], v[66:81]
	ds_read_b128 v[34:37], v122 offset:27712
	v_mov_b32_e32 v98, v223
	s_waitcnt lgkmcnt(0)
	v_mfma_f32_32x32x16_bf16 v[2:17], v[102:105], v[34:37], v[2:17]
	v_mfma_f32_32x32x16_bf16 v[66:81], v[106:109], v[34:37], v[66:81]
	ds_read_b128 v[34:37], v122 offset:27744
	s_waitcnt lgkmcnt(0)
	s_nop 0
	v_ashrrev_i32_e32 v99, 31, v98
	v_and_b32_e32 v176, 15, v98
	s_waitcnt lgkmcnt(0)
	v_mfma_f32_32x32x16_bf16 v[2:17], v[110:113], v[34:37], v[2:17]
	v_mfma_f32_32x32x16_bf16 v[66:81], v[114:117], v[34:37], v[66:81]
	v_lshlrev_b64 v[34:35], 2, v[98:99]
	v_lshl_add_u64 v[36:37], s[4:5], 0, v[34:35]
	v_add_co_u32_e32 v38, vcc, s16, v36
	global_load_dword v40, v[36:37], off nt
	s_nop 0
	v_addc_co_u32_e32 v39, vcc, 0, v37, vcc
	global_load_dword v41, v[38:39], off nt
	v_add_co_u32_e32 v38, vcc, s77, v36
	s_mov_b32 s4, 0x84000
	s_nop 0
	v_addc_co_u32_e32 v39, vcc, 0, v37, vcc
	global_load_dword v44, v[38:39], off nt
	v_add_co_u32_e32 v38, vcc, s24, v36
	s_nop 1
	v_addc_co_u32_e32 v39, vcc, 0, v37, vcc
	global_load_dword v45, v[38:39], off nt
	v_add_co_u32_e32 v38, vcc, s4, v36
	s_mov_b32 s4, 0xe7000
	s_nop 0
	v_addc_co_u32_e32 v39, vcc, 0, v37, vcc
	global_load_dword v46, v[38:39], off nt
	v_add_co_u32_e32 v38, vcc, s31, v36
	s_nop 1
	v_addc_co_u32_e32 v39, vcc, 0, v37, vcc
	global_load_dword v47, v[38:39], off nt
	v_add_co_u32_e32 v38, vcc, s38, v36
	s_waitcnt vmcnt(0)
	v_cvt_pk_bf16_f32 v144, v46, v47
	v_addc_co_u32_e32 v39, vcc, 0, v37, vcc
	global_load_dword v49, v[38:39], off nt
	v_add_co_u32_e32 v38, vcc, s4, v36
	s_mov_b32 s4, 0x108000
	s_nop 0
	v_addc_co_u32_e32 v39, vcc, 0, v37, vcc
	global_load_dword v52, v[38:39], off nt
	v_add_co_u32_e32 v38, vcc, s4, v36
	s_mov_b32 s4, 0x129000
	s_nop 0
	v_addc_co_u32_e32 v39, vcc, 0, v37, vcc
	global_load_dword v53, v[38:39], off nt
	v_add_co_u32_e32 v38, vcc, s4, v36
	s_mov_b32 s4, 0x14a000
	s_nop 0
	v_addc_co_u32_e32 v39, vcc, 0, v37, vcc
	global_load_dword v56, v[38:39], off nt
	v_add_co_u32_e32 v38, vcc, s4, v36
	s_mov_b32 s4, 0x16b000
	s_nop 0
	v_addc_co_u32_e32 v39, vcc, 0, v37, vcc
	global_load_dword v58, v[38:39], off nt
	v_add_co_u32_e32 v38, vcc, s4, v36
	s_mov_b32 s4, 0x18c000
	s_nop 0
	v_addc_co_u32_e32 v39, vcc, 0, v37, vcc
	global_load_dword v60, v[38:39], off nt
	v_add_co_u32_e32 v38, vcc, s4, v36
	s_mov_b32 s4, 0x1ad000
	s_nop 0
	v_addc_co_u32_e32 v39, vcc, 0, v37, vcc
	global_load_dword v62, v[38:39], off nt
	v_add_co_u32_e32 v38, vcc, s4, v36
	s_mov_b32 s4, 0x1ce000
	s_nop 0
	v_addc_co_u32_e32 v39, vcc, 0, v37, vcc
	global_load_dword v64, v[38:39], off nt
	v_add_co_u32_e32 v38, vcc, s4, v36
	s_mov_b32 s4, 0x1ef000
	s_nop 0
	v_addc_co_u32_e32 v39, vcc, 0, v37, vcc
	global_load_dword v100, v[38:39], off nt
	v_add_co_u32_e32 v38, vcc, s4, v36
	s_mov_b32 s4, 0x6b000
	s_nop 0
	v_addc_co_u32_e32 v39, vcc, 0, v37, vcc
	global_load_dword v102, v[38:39], off nt
	v_add_co_u32_e32 v38, vcc, s97, v36
	s_waitcnt vmcnt(8)
	v_cvt_pk_bf16_f32 v145, v49, v52
	v_addc_co_u32_e32 v39, vcc, 0, v37, vcc
	global_load_dword v48, v[38:39], off offset:1024 nt
	v_add_co_u32_e32 v38, vcc, s17, v36
	s_waitcnt vmcnt(3)
	v_cvt_pk_bf16_f32 v46, v62, v64
	v_addc_co_u32_e32 v39, vcc, 0, v37, vcc
	global_load_dword v50, v[38:39], off offset:1024 nt
	v_add_co_u32_e32 v38, vcc, s20, v36
	s_waitcnt vmcnt(2)
	v_cvt_pk_bf16_f32 v47, v100, v102
	v_addc_co_u32_e32 v39, vcc, 0, v37, vcc
	global_load_dword v51, v[38:39], off offset:1024 nt
	v_add_co_u32_e32 v38, vcc, s4, v36
	s_mov_b32 s4, 0x8c000
	s_nop 0
	v_addc_co_u32_e32 v39, vcc, 0, v37, vcc
	global_load_dword v54, v[38:39], off offset:1024 nt
	v_add_co_u32_e32 v38, vcc, s4, v36
	s_mov_b32 s4, 0xef000
	s_nop 0
	v_addc_co_u32_e32 v39, vcc, 0, v37, vcc
	global_load_dword v55, v[38:39], off offset:1024 nt
	v_add_co_u32_e32 v38, vcc, s33, v36
	s_nop 1
	v_addc_co_u32_e32 v39, vcc, 0, v37, vcc
	global_load_dword v57, v[38:39], off offset:1024 nt
	v_add_co_u32_e32 v38, vcc, s39, v36
	s_nop 1
	v_addc_co_u32_e32 v39, vcc, 0, v37, vcc
	global_load_dword v59, v[38:39], off offset:1024 nt
	v_add_co_u32_e32 v38, vcc, s4, v36
	s_mov_b32 s4, 0x110000
	s_nop 0
	v_addc_co_u32_e32 v39, vcc, 0, v37, vcc
	global_load_dword v61, v[38:39], off offset:1024 nt
	v_add_co_u32_e32 v38, vcc, s4, v36
	s_mov_b32 s4, 0x131000
	s_nop 0
	v_addc_co_u32_e32 v39, vcc, 0, v37, vcc
	global_load_dword v63, v[38:39], off offset:1024 nt
	v_add_co_u32_e32 v38, vcc, s4, v36
	s_mov_b32 s4, 0x152000
	s_nop 0
	v_addc_co_u32_e32 v39, vcc, 0, v37, vcc
	global_load_dword v65, v[38:39], off offset:1024 nt
	v_add_co_u32_e32 v38, vcc, s4, v36
	s_mov_b32 s4, 0x173000
	s_nop 0
	v_addc_co_u32_e32 v39, vcc, 0, v37, vcc
	global_load_dword v101, v[38:39], off offset:1024 nt
	v_add_co_u32_e32 v38, vcc, s4, v36
	s_mov_b32 s4, 0x194000
	s_nop 0
	v_addc_co_u32_e32 v39, vcc, 0, v37, vcc
	global_load_dword v103, v[38:39], off offset:1024 nt
	v_add_co_u32_e32 v38, vcc, s4, v36
	s_mov_b32 s4, 0x1b5000
	s_nop 0
	v_addc_co_u32_e32 v39, vcc, 0, v37, vcc
	global_load_dword v104, v[38:39], off offset:1024 nt
	v_add_co_u32_e32 v38, vcc, s4, v36
	s_mov_b32 s4, 0x1d6000
	s_nop 0
	v_addc_co_u32_e32 v39, vcc, 0, v37, vcc
	global_load_dword v105, v[38:39], off offset:1024 nt
	v_add_co_u32_e32 v38, vcc, s4, v36
	s_mov_b32 s4, 0x1f7000
	s_nop 0
	v_addc_co_u32_e32 v39, vcc, 0, v37, vcc
	global_load_dword v106, v[38:39], off offset:1024 nt
	v_add_co_u32_e32 v38, vcc, s4, v36
	s_mov_b32 s4, 0x73000
	s_nop 0
	v_addc_co_u32_e32 v39, vcc, 0, v37, vcc
	global_load_dword v107, v[38:39], off offset:1024 nt
	v_add_co_u32_e32 v38, vcc, s94, v36
	s_waitcnt vmcnt(4)
	v_cvt_pk_bf16_f32 v49, v101, v103
	v_addc_co_u32_e32 v39, vcc, 0, v37, vcc
	global_load_dword v108, v[38:39], off offset:2048 nt
	v_add_co_u32_e32 v38, vcc, s18, v36
	s_nop 1
	v_addc_co_u32_e32 v39, vcc, 0, v37, vcc
	global_load_dword v109, v[38:39], off offset:2048 nt
	v_add_co_u32_e32 v38, vcc, s21, v36
	s_nop 1
	v_addc_co_u32_e32 v39, vcc, 0, v37, vcc
	global_load_dword v110, v[38:39], off offset:2048 nt
	v_add_co_u32_e32 v38, vcc, s4, v36
	s_mov_b32 s4, 0x94000
	s_nop 0
	v_addc_co_u32_e32 v39, vcc, 0, v37, vcc
	global_load_dword v111, v[38:39], off offset:2048 nt
	v_add_co_u32_e32 v38, vcc, s4, v36
	s_mov_b32 s4, 0xf7000
	s_nop 0
	v_addc_co_u32_e32 v39, vcc, 0, v37, vcc
	global_load_dword v112, v[38:39], off offset:2048 nt
	v_add_co_u32_e32 v38, vcc, s34, v36
	s_nop 1
	v_addc_co_u32_e32 v39, vcc, 0, v37, vcc
	global_load_dword v113, v[38:39], off offset:2048 nt
	v_add_co_u32_e32 v38, vcc, s52, v36
	s_nop 1
	v_addc_co_u32_e32 v39, vcc, 0, v37, vcc
	global_load_dword v114, v[38:39], off offset:2048 nt
	v_add_co_u32_e32 v38, vcc, s4, v36
	s_mov_b32 s4, 0x118000
	s_nop 0
	v_addc_co_u32_e32 v39, vcc, 0, v37, vcc
	global_load_dword v115, v[38:39], off offset:2048 nt
	v_add_co_u32_e32 v38, vcc, s4, v36
	s_mov_b32 s4, 0x139000
	s_nop 0
	v_addc_co_u32_e32 v39, vcc, 0, v37, vcc
	global_load_dword v116, v[38:39], off offset:2048 nt
	v_add_co_u32_e32 v38, vcc, s4, v36
	s_mov_b32 s4, 0x15a000
	s_nop 0
	v_addc_co_u32_e32 v39, vcc, 0, v37, vcc
	global_load_dword v117, v[38:39], off offset:2048 nt
	v_add_co_u32_e32 v38, vcc, s4, v36
	s_mov_b32 s4, 0x17b000
	s_nop 0
	v_addc_co_u32_e32 v39, vcc, 0, v37, vcc
	global_load_dword v118, v[38:39], off offset:2048 nt
	v_add_co_u32_e32 v38, vcc, s4, v36
	s_mov_b32 s4, 0x19c000
	s_nop 0
	v_addc_co_u32_e32 v39, vcc, 0, v37, vcc
	global_load_dword v119, v[38:39], off offset:2048 nt
	v_add_co_u32_e32 v38, vcc, s4, v36
	s_mov_b32 s4, 0x1bd000
	s_nop 0
	v_addc_co_u32_e32 v39, vcc, 0, v37, vcc
	global_load_dword v120, v[38:39], off offset:2048 nt
	v_add_co_u32_e32 v38, vcc, s4, v36
	s_mov_b32 s4, 0x1de000
	s_nop 0
	v_addc_co_u32_e32 v39, vcc, 0, v37, vcc
	global_load_dword v121, v[38:39], off offset:2048 nt
	v_add_co_u32_e32 v38, vcc, s4, v36
	s_mov_b32 s4, 0x1ff000
	s_nop 0
	v_addc_co_u32_e32 v39, vcc, 0, v37, vcc
	global_load_dword v122, v[38:39], off offset:2048 nt
	v_add_co_u32_e32 v38, vcc, s4, v36
	s_mov_b32 s4, 0x5a000
	s_nop 0
	v_addc_co_u32_e32 v39, vcc, 0, v37, vcc
	global_load_dword v123, v[38:39], off offset:2048 nt
	v_add_co_u32_e32 v38, vcc, s96, v36
	s_nop 1
	v_addc_co_u32_e32 v39, vcc, 0, v37, vcc
	global_load_dword v124, v[38:39], off offset:3072 nt
	v_add_co_u32_e32 v38, vcc, s19, v36
	s_nop 1
	v_addc_co_u32_e32 v39, vcc, 0, v37, vcc
	global_load_dword v125, v[38:39], off offset:3072 nt
	v_add_co_u32_e32 v38, vcc, s4, v36
	s_mov_b32 s4, 0x7b000
	s_nop 0
	v_addc_co_u32_e32 v39, vcc, 0, v37, vcc
	global_load_dword v126, v[38:39], off offset:3072 nt
	v_add_co_u32_e32 v38, vcc, s4, v36
	s_mov_b32 s4, 0x9c000
	s_nop 0
	v_addc_co_u32_e32 v39, vcc, 0, v37, vcc
	global_load_dword v127, v[38:39], off offset:3072 nt
	v_add_co_u32_e32 v38, vcc, s4, v36
	s_mov_b32 s4, 0xff000
	s_nop 0
	v_addc_co_u32_e32 v39, vcc, 0, v37, vcc
	global_load_dword v128, v[38:39], off offset:3072 nt
	v_add_co_u32_e32 v38, vcc, s35, v36
	s_nop 1
	v_addc_co_u32_e32 v39, vcc, 0, v37, vcc
	global_load_dword v129, v[38:39], off offset:3072 nt
	v_add_co_u32_e32 v38, vcc, s53, v36
	s_nop 1
	v_addc_co_u32_e32 v39, vcc, 0, v37, vcc
	global_load_dword v131, v[38:39], off offset:3072 nt
	v_add_co_u32_e32 v38, vcc, s4, v36
	s_nop 1
	v_addc_co_u32_e32 v39, vcc, 0, v37, vcc
	global_load_dword v132, v[38:39], off offset:3072 nt
	v_add_co_u32_e32 v38, vcc, s30, v36
	s_nop 1
	v_addc_co_u32_e32 v39, vcc, 0, v37, vcc
	global_load_dword v133, v[38:39], off offset:3072 nt
	v_add_co_u32_e32 v38, vcc, s29, v36
	s_nop 1
	v_addc_co_u32_e32 v39, vcc, 0, v37, vcc
	global_load_dword v134, v[38:39], off offset:3072 nt
	v_add_co_u32_e32 v38, vcc, s28, v36
	s_nop 1
	v_addc_co_u32_e32 v39, vcc, 0, v37, vcc
	global_load_dword v135, v[38:39], off offset:3072 nt
	v_add_co_u32_e32 v38, vcc, s27, v36
	s_nop 1
	v_addc_co_u32_e32 v39, vcc, 0, v37, vcc
	global_load_dword v136, v[38:39], off offset:3072 nt
	v_add_co_u32_e32 v38, vcc, s26, v36
	s_nop 1
	v_addc_co_u32_e32 v39, vcc, 0, v37, vcc
	global_load_dword v137, v[38:39], off offset:3072 nt
	v_add_co_u32_e32 v38, vcc, s25, v36
	s_nop 1
	v_addc_co_u32_e32 v39, vcc, 0, v37, vcc
	global_load_dword v138, v[38:39], off offset:3072 nt
	v_add_co_u32_e32 v38, vcc, s23, v36
	s_nop 1
	v_addc_co_u32_e32 v39, vcc, 0, v37, vcc
	v_add_co_u32_e32 v36, vcc, s22, v36
	global_load_dword v139, v[38:39], off offset:3072 nt
	s_nop 0
	v_addc_co_u32_e32 v37, vcc, 0, v37, vcc
	global_load_dword v140, v[36:37], off offset:3072 nt
	v_lshl_add_u64 v[38:39], s[0:1], 0, v[34:35]
	v_add_co_u32_e32 v42, vcc, s15, v38
	v_lshlrev_b64 v[34:35], 1, v[98:99]
	s_nop 0
	v_addc_co_u32_e32 v43, vcc, 0, v39, vcc
	v_add_co_u32_e32 v142, vcc, s93, v38
	global_load_dword v99, v[38:39], off nt
	global_load_dword v141, v[38:39], off offset:1024 nt
	global_load_dword v146, v[38:39], off offset:2048 nt
	global_load_dword v147, v[38:39], off offset:3072 nt
	v_addc_co_u32_e32 v143, vcc, 0, v39, vcc
	global_load_dword v148, v[142:143], off offset:-4096 nt
	global_load_dword v149, v[42:43], off offset:1024 nt
	global_load_dword v150, v[42:43], off offset:2048 nt
	global_load_dword v151, v[42:43], off offset:3072 nt
	global_load_dword v152, v[142:143], off nt
	global_load_dword v153, v[142:143], off offset:1024 nt
	global_load_dword v154, v[142:143], off offset:2048 nt
	global_load_dword v155, v[142:143], off offset:3072 nt
	v_add_co_u32_e32 v42, vcc, s87, v38
	v_lshl_add_u64 v[36:37], s[2:3], 0, v[34:35]
	s_nop 0
	v_addc_co_u32_e32 v43, vcc, 0, v39, vcc
	v_add_co_u32_e32 v142, vcc, s81, v38
	v_lshl_add_u64 v[34:35], s[88:89], 0, v[34:35]
	s_nop 0
	v_addc_co_u32_e32 v143, vcc, 0, v39, vcc
	global_load_dword v156, v[142:143], off offset:-4096 nt
	global_load_dword v157, v[42:43], off offset:1024 nt
	global_load_dword v158, v[42:43], off offset:2048 nt
	global_load_dword v159, v[42:43], off offset:3072 nt
	global_load_dword v160, v[142:143], off nt
	global_load_dword v161, v[142:143], off offset:1024 nt
	global_load_dword v162, v[142:143], off offset:2048 nt
	global_load_dword v163, v[142:143], off offset:3072 nt
	v_add_co_u32_e32 v42, vcc, s92, v38
	s_nop 1
	v_addc_co_u32_e32 v43, vcc, 0, v39, vcc
	v_add_co_u32_e32 v142, vcc, s95, v38
	s_nop 1
	v_addc_co_u32_e32 v143, vcc, 0, v39, vcc
	global_load_dword v164, v[142:143], off offset:-4096 nt
	global_load_dword v165, v[42:43], off offset:1024 nt
	global_load_dword v166, v[42:43], off offset:2048 nt
	global_load_dword v167, v[42:43], off offset:3072 nt
	global_load_dword v168, v[142:143], off nt
	global_load_dword v169, v[142:143], off offset:1024 nt
	global_load_dword v170, v[142:143], off offset:2048 nt
	global_load_dword v171, v[142:143], off offset:3072 nt
	v_add_co_u32_e32 v142, vcc, s85, v38
	s_nop 1
	v_addc_co_u32_e32 v143, vcc, 0, v39, vcc
	v_add_co_u32_e32 v42, vcc, s97, v38
	s_nop 1
	v_addc_co_u32_e32 v43, vcc, 0, v39, vcc
	global_load_dword v172, v[42:43], off offset:-4096 nt
	global_load_dword v173, v[142:143], off offset:1024 nt
	global_load_dword v174, v[142:143], off offset:2048 nt
	global_load_dword v175, v[142:143], off offset:3072 nt
	v_and_b32_e32 v142, 0x7ffffff0, v98
	v_lshlrev_b32_e32 v177, 1, v142
	v_cvt_pk_bf16_f32 v142, v40, v41
	v_mul_u32_u24_e32 v40, 0x90, v176
	v_cvt_pk_bf16_f32 v143, v44, v45
	v_cvt_pk_bf16_f32 v44, v53, v56
	v_cvt_pk_bf16_f32 v45, v58, v60
	v_add3_u32 v56, s7, v177, v40
	global_load_ushort v58, v[36:37], off
	global_load_ushort v60, v[36:37], off offset:512
	global_load_ushort v62, v[36:37], off offset:1024
	global_load_ushort v64, v[36:37], off offset:1536
	global_load_ushort v100, v[36:37], off offset:2048
	global_load_ushort v102, v[36:37], off offset:2560
	global_load_ushort v176, v[36:37], off offset:3072
	global_load_ushort v177, v[36:37], off offset:3584
	v_add_co_u32_e32 v40, vcc, s15, v36
	s_nop 1
	v_addc_co_u32_e32 v41, vcc, 0, v37, vcc
	v_add_co_u32_e32 v52, vcc, s93, v36
	s_nop 1
	v_addc_co_u32_e32 v53, vcc, 0, v37, vcc
	global_load_ushort v178, v[52:53], off offset:-4096
	global_load_ushort v179, v[40:41], off offset:512
	global_load_ushort v180, v[40:41], off offset:1024
	global_load_ushort v181, v[40:41], off offset:1536
	global_load_ushort v186, v[40:41], off offset:2048
	global_load_ushort v187, v[40:41], off offset:2560
	global_load_ushort v189, v[40:41], off offset:3072
	global_load_ushort v192, v[40:41], off offset:3584
	global_load_ushort v193, v[52:53], off
	global_load_ushort v194, v[52:53], off offset:512
	global_load_ushort v195, v[52:53], off offset:1024
	global_load_ushort v196, v[52:53], off offset:1536
	global_load_ushort v197, v[52:53], off offset:2048
	global_load_ushort v198, v[52:53], off offset:2560
	global_load_ushort v199, v[52:53], off offset:3072
	global_load_ushort v200, v[52:53], off offset:3584
	v_add_co_u32_e32 v52, vcc, s87, v36
	s_nop 1
	v_addc_co_u32_e32 v53, vcc, 0, v37, vcc
	v_add_co_u32_e32 v40, vcc, s81, v36
	s_nop 1
	v_addc_co_u32_e32 v41, vcc, 0, v37, vcc
	global_load_ushort v201, v[40:41], off offset:-4096
	global_load_ushort v202, v[52:53], off offset:512
	global_load_ushort v203, v[52:53], off offset:1024
	global_load_ushort v204, v[52:53], off offset:1536
	global_load_ushort v205, v[52:53], off offset:2048
	global_load_ushort v206, v[52:53], off offset:2560
	global_load_ushort v207, v[52:53], off offset:3072
	s_nop 0
	global_load_ushort v52, v[52:53], off offset:3584
	ds_write_b128 v56, v[142:145] offset:23040
	ds_write_b128 v56, v[44:47] offset:23056
	v_cvt_pk_bf16_f32 v44, v48, v50
	v_cvt_pk_bf16_f32 v45, v51, v54
	v_cvt_pk_bf16_f32 v46, v55, v57
	v_cvt_pk_bf16_f32 v47, v59, v61
	v_cvt_pk_bf16_f32 v48, v63, v65
	s_waitcnt vmcnt(62)
	v_cvt_pk_bf16_f32 v50, v104, v105
	v_cvt_pk_bf16_f32 v51, v106, v107
	ds_write_b128 v56, v[44:47] offset:25344
	ds_write_b128 v56, v[48:51] offset:25360
	v_cvt_pk_bf16_f32 v44, v108, v109
	v_cvt_pk_bf16_f32 v45, v110, v111
	v_cvt_pk_bf16_f32 v46, v112, v113
	v_cvt_pk_bf16_f32 v47, v114, v115
	v_cvt_pk_bf16_f32 v48, v116, v117
	v_cvt_pk_bf16_f32 v49, v118, v119
	v_cvt_pk_bf16_f32 v50, v120, v121
	v_cvt_pk_bf16_f32 v51, v122, v123
	ds_write_b128 v56, v[44:47] offset:27648
	ds_write_b128 v56, v[48:51] offset:27664
	v_cvt_pk_bf16_f32 v44, v124, v125
	v_cvt_pk_bf16_f32 v45, v126, v127
	v_cvt_pk_bf16_f32 v46, v128, v129
	v_cvt_pk_bf16_f32 v47, v131, v132
	v_cvt_pk_bf16_f32 v48, v133, v134
	v_cvt_pk_bf16_f32 v49, v135, v136
	v_cvt_pk_bf16_f32 v50, v137, v138
	v_cvt_pk_bf16_f32 v51, v139, v140
	ds_write_b128 v56, v[44:47] offset:29952
	ds_write_b128 v56, v[48:51] offset:29968
	v_rcp_f32_e32 v47, v99
	v_sub_f32_e32 v46, 1.0, v99
	v_lshl_add_u32 v44, v98, 1, s7
	v_mul_f32_e32 v46, v46, v47
	v_sub_f32_e32 v47, 1.0, v141
	s_waitcnt vmcnt(31)
	v_lshlrev_b32_e32 v45, 16, v58
	v_mul_f32_e32 v45, v99, v45
	v_cvt_pk_bf16_f32 v45, v45, s0
	ds_write_b16 v44, v45 offset:9216
	v_cvt_pk_bf16_f32 v45, v46, s0
	v_mul_f32_e32 v46, v99, v141
	v_rcp_f32_e32 v48, v46
	ds_write_b16 v44, v45
	s_waitcnt vmcnt(30)
	v_lshlrev_b32_e32 v45, 16, v60
	v_mul_f32_e32 v45, v46, v45
	v_mul_f32_e32 v46, v46, v146
	v_mul_f32_e32 v47, v47, v48
	v_cvt_pk_bf16_f32 v45, v45, s0
	v_rcp_f32_e32 v48, v46
	ds_write_b16 v44, v45 offset:9360
	v_cvt_pk_bf16_f32 v45, v47, s0
	ds_write_b16 v44, v45 offset:144
	s_waitcnt vmcnt(29)
	v_lshlrev_b32_e32 v45, 16, v62
	v_mul_f32_e32 v45, v46, v45
	v_sub_f32_e32 v47, 1.0, v146
	v_mul_f32_e32 v46, v46, v147
	v_mul_f32_e32 v47, v47, v48
	v_cvt_pk_bf16_f32 v45, v45, s0
	v_rcp_f32_e32 v48, v46
	ds_write_b16 v44, v45 offset:9504
	v_cvt_pk_bf16_f32 v45, v47, s0
	ds_write_b16 v44, v45 offset:288
	s_waitcnt vmcnt(28)
	v_lshlrev_b32_e32 v45, 16, v64
	v_mul_f32_e32 v45, v46, v45
	v_sub_f32_e32 v47, 1.0, v147
	v_mul_f32_e32 v46, v46, v148
	v_mul_f32_e32 v47, v47, v48
	v_cvt_pk_bf16_f32 v45, v45, s0
	v_rcp_f32_e32 v48, v46
	ds_write_b16 v44, v45 offset:9648
	v_cvt_pk_bf16_f32 v45, v47, s0
	ds_write_b16 v44, v45 offset:432
	s_waitcnt vmcnt(27)
	v_lshlrev_b32_e32 v45, 16, v100
	v_mul_f32_e32 v45, v46, v45
	v_sub_f32_e32 v47, 1.0, v148
	v_mul_f32_e32 v46, v46, v149
	v_mul_f32_e32 v47, v47, v48
	v_cvt_pk_bf16_f32 v45, v45, s0
	v_rcp_f32_e32 v48, v46
	ds_write_b16 v44, v45 offset:9792
	v_cvt_pk_bf16_f32 v45, v47, s0
	ds_write_b16 v44, v45 offset:576
	s_waitcnt vmcnt(26)
	v_lshlrev_b32_e32 v45, 16, v102
	v_mul_f32_e32 v45, v46, v45
	v_sub_f32_e32 v47, 1.0, v149
	v_mul_f32_e32 v46, v46, v150
	v_mul_f32_e32 v47, v47, v48
	v_cvt_pk_bf16_f32 v45, v45, s0
	v_rcp_f32_e32 v48, v46
	ds_write_b16 v44, v45 offset:9936
	v_cvt_pk_bf16_f32 v45, v47, s0
	ds_write_b16 v44, v45 offset:720
	s_waitcnt vmcnt(25)
	v_lshlrev_b32_e32 v45, 16, v176
	v_mul_f32_e32 v45, v46, v45
	v_sub_f32_e32 v47, 1.0, v150
	v_mul_f32_e32 v46, v46, v151
	v_mul_f32_e32 v47, v47, v48
	v_cvt_pk_bf16_f32 v45, v45, s0
	v_rcp_f32_e32 v48, v46
	ds_write_b16 v44, v45 offset:10080
	v_cvt_pk_bf16_f32 v45, v47, s0
	ds_write_b16 v44, v45 offset:864
	s_waitcnt vmcnt(24)
	v_lshlrev_b32_e32 v45, 16, v177
	v_mul_f32_e32 v45, v46, v45
	v_sub_f32_e32 v47, 1.0, v151
	v_mul_f32_e32 v46, v46, v152
	v_mul_f32_e32 v47, v47, v48
	v_cvt_pk_bf16_f32 v45, v45, s0
	v_rcp_f32_e32 v48, v46
	ds_write_b16 v44, v45 offset:10224
	v_cvt_pk_bf16_f32 v45, v47, s0
	ds_write_b16 v44, v45 offset:1008
	s_waitcnt vmcnt(23)
	v_lshlrev_b32_e32 v45, 16, v178
	v_mul_f32_e32 v45, v46, v45
	v_sub_f32_e32 v47, 1.0, v152
	v_mul_f32_e32 v46, v46, v153
	v_mul_f32_e32 v47, v47, v48
	v_cvt_pk_bf16_f32 v45, v45, s0
	v_rcp_f32_e32 v48, v46
	ds_write_b16 v44, v45 offset:10368
	v_cvt_pk_bf16_f32 v45, v47, s0
	ds_write_b16 v44, v45 offset:1152
	s_waitcnt vmcnt(22)
	v_lshlrev_b32_e32 v45, 16, v179
	v_mul_f32_e32 v45, v46, v45
	v_sub_f32_e32 v47, 1.0, v153
	v_mul_f32_e32 v46, v46, v154
	v_mul_f32_e32 v47, v47, v48
	v_cvt_pk_bf16_f32 v45, v45, s0
	v_rcp_f32_e32 v48, v46
	ds_write_b16 v44, v45 offset:10512
	v_cvt_pk_bf16_f32 v45, v47, s0
	ds_write_b16 v44, v45 offset:1296
	s_waitcnt vmcnt(21)
	v_lshlrev_b32_e32 v45, 16, v180
	v_mul_f32_e32 v45, v46, v45
	v_sub_f32_e32 v47, 1.0, v154
	v_mul_f32_e32 v46, v46, v155
	v_mul_f32_e32 v47, v47, v48
	v_cvt_pk_bf16_f32 v45, v45, s0
	v_rcp_f32_e32 v48, v46
	ds_write_b16 v44, v45 offset:10656
	v_cvt_pk_bf16_f32 v45, v47, s0
	ds_write_b16 v44, v45 offset:1440
	s_waitcnt vmcnt(20)
	v_lshlrev_b32_e32 v45, 16, v181
	v_mul_f32_e32 v45, v46, v45
	v_sub_f32_e32 v47, 1.0, v155
	v_mul_f32_e32 v46, v46, v156
	v_mul_f32_e32 v47, v47, v48
	v_cvt_pk_bf16_f32 v45, v45, s0
	v_rcp_f32_e32 v48, v46
	ds_write_b16 v44, v45 offset:10800
	v_cvt_pk_bf16_f32 v45, v47, s0
	ds_write_b16 v44, v45 offset:1584
	s_waitcnt vmcnt(19)
	v_lshlrev_b32_e32 v45, 16, v186
	v_mul_f32_e32 v45, v46, v45
	v_sub_f32_e32 v47, 1.0, v156
	v_mul_f32_e32 v46, v46, v157
	v_mul_f32_e32 v47, v47, v48
	v_cvt_pk_bf16_f32 v45, v45, s0
	v_rcp_f32_e32 v48, v46
	ds_write_b16 v44, v45 offset:10944
	v_cvt_pk_bf16_f32 v45, v47, s0
	ds_write_b16 v44, v45 offset:1728
	s_waitcnt vmcnt(18)
	v_lshlrev_b32_e32 v45, 16, v187
	v_mul_f32_e32 v45, v46, v45
	v_sub_f32_e32 v47, 1.0, v157
	v_mul_f32_e32 v46, v46, v158
	v_mul_f32_e32 v47, v47, v48
	v_cvt_pk_bf16_f32 v45, v45, s0
	v_rcp_f32_e32 v48, v46
	ds_write_b16 v44, v45 offset:11088
	v_cvt_pk_bf16_f32 v45, v47, s0
	ds_write_b16 v44, v45 offset:1872
	s_waitcnt vmcnt(17)
	v_lshlrev_b32_e32 v45, 16, v189
	v_mul_f32_e32 v45, v46, v45
	v_sub_f32_e32 v47, 1.0, v158
	v_mul_f32_e32 v46, v46, v159
	v_mul_f32_e32 v47, v47, v48
	v_cvt_pk_bf16_f32 v45, v45, s0
	v_rcp_f32_e32 v48, v46
	ds_write_b16 v44, v45 offset:11232
	v_cvt_pk_bf16_f32 v45, v47, s0
	ds_write_b16 v44, v45 offset:2016
	s_waitcnt vmcnt(16)
	v_lshlrev_b32_e32 v45, 16, v192
	v_mul_f32_e32 v45, v46, v45
	v_sub_f32_e32 v47, 1.0, v159
	v_mul_f32_e32 v46, v46, v160
	v_mul_f32_e32 v47, v47, v48
	v_cvt_pk_bf16_f32 v45, v45, s0
	v_rcp_f32_e32 v48, v46
	ds_write_b16 v44, v45 offset:11376
	v_cvt_pk_bf16_f32 v45, v47, s0
	ds_write_b16 v44, v45 offset:2160
	s_waitcnt vmcnt(15)
	v_lshlrev_b32_e32 v45, 16, v193
	v_mul_f32_e32 v45, v46, v45
	v_sub_f32_e32 v47, 1.0, v160
	v_mul_f32_e32 v46, v46, v161
	v_mul_f32_e32 v47, v47, v48
	v_cvt_pk_bf16_f32 v45, v45, s0
	v_rcp_f32_e32 v48, v46
	ds_write_b16 v44, v45 offset:11520
	v_cvt_pk_bf16_f32 v45, v47, s0
	ds_write_b16 v44, v45 offset:2304
	s_waitcnt vmcnt(14)
	v_lshlrev_b32_e32 v45, 16, v194
	v_mul_f32_e32 v45, v46, v45
	v_sub_f32_e32 v47, 1.0, v161
	v_mul_f32_e32 v46, v46, v162
	v_mul_f32_e32 v47, v47, v48
	v_cvt_pk_bf16_f32 v45, v45, s0
	v_rcp_f32_e32 v48, v46
	ds_write_b16 v44, v45 offset:11664
	v_cvt_pk_bf16_f32 v45, v47, s0
	ds_write_b16 v44, v45 offset:2448
	s_waitcnt vmcnt(13)
	v_lshlrev_b32_e32 v45, 16, v195
	v_mul_f32_e32 v45, v46, v45
	v_sub_f32_e32 v47, 1.0, v162
	v_mul_f32_e32 v46, v46, v163
	v_mul_f32_e32 v47, v47, v48
	v_cvt_pk_bf16_f32 v45, v45, s0
	v_rcp_f32_e32 v48, v46
	ds_write_b16 v44, v45 offset:11808
	v_cvt_pk_bf16_f32 v45, v47, s0
	ds_write_b16 v44, v45 offset:2592
	s_waitcnt vmcnt(12)
	v_lshlrev_b32_e32 v45, 16, v196
	v_mul_f32_e32 v45, v46, v45
	v_sub_f32_e32 v47, 1.0, v163
	v_mul_f32_e32 v46, v46, v164
	v_mul_f32_e32 v47, v47, v48
	v_cvt_pk_bf16_f32 v45, v45, s0
	v_rcp_f32_e32 v48, v46
	ds_write_b16 v44, v45 offset:11952
	v_cvt_pk_bf16_f32 v45, v47, s0
	ds_write_b16 v44, v45 offset:2736
	s_waitcnt vmcnt(11)
	v_lshlrev_b32_e32 v45, 16, v197
	v_mul_f32_e32 v45, v46, v45
	v_sub_f32_e32 v47, 1.0, v164
	v_mul_f32_e32 v46, v46, v165
	v_mul_f32_e32 v47, v47, v48
	v_cvt_pk_bf16_f32 v45, v45, s0
	v_rcp_f32_e32 v48, v46
	ds_write_b16 v44, v45 offset:12096
	v_cvt_pk_bf16_f32 v45, v47, s0
	ds_write_b16 v44, v45 offset:2880
	s_waitcnt vmcnt(10)
	v_lshlrev_b32_e32 v45, 16, v198
	v_mul_f32_e32 v45, v46, v45
	v_sub_f32_e32 v47, 1.0, v165
	v_mul_f32_e32 v46, v46, v166
	v_mul_f32_e32 v47, v47, v48
	v_cvt_pk_bf16_f32 v45, v45, s0
	v_rcp_f32_e32 v48, v46
	ds_write_b16 v44, v45 offset:12240
	v_cvt_pk_bf16_f32 v45, v47, s0
	ds_write_b16 v44, v45 offset:3024
	s_waitcnt vmcnt(9)
	v_lshlrev_b32_e32 v45, 16, v199
	v_mul_f32_e32 v45, v46, v45
	v_sub_f32_e32 v47, 1.0, v166
	v_mul_f32_e32 v46, v46, v167
	v_mul_f32_e32 v47, v47, v48
	v_cvt_pk_bf16_f32 v45, v45, s0
	v_rcp_f32_e32 v48, v46
	ds_write_b16 v44, v45 offset:12384
	v_cvt_pk_bf16_f32 v45, v47, s0
	ds_write_b16 v44, v45 offset:3168
	s_waitcnt vmcnt(8)
	v_lshlrev_b32_e32 v45, 16, v200
	v_mul_f32_e32 v45, v46, v45
	v_sub_f32_e32 v47, 1.0, v167
	v_mul_f32_e32 v46, v46, v168
	v_mul_f32_e32 v47, v47, v48
	v_cvt_pk_bf16_f32 v45, v45, s0
	v_rcp_f32_e32 v48, v46
	ds_write_b16 v44, v45 offset:12528
	v_cvt_pk_bf16_f32 v45, v47, s0
	ds_write_b16 v44, v45 offset:3312
	s_waitcnt vmcnt(7)
	v_lshlrev_b32_e32 v45, 16, v201
	v_mul_f32_e32 v45, v46, v45
	v_sub_f32_e32 v47, 1.0, v168
	v_mul_f32_e32 v46, v46, v169
	v_mul_f32_e32 v47, v47, v48
	v_cvt_pk_bf16_f32 v45, v45, s0
	v_rcp_f32_e32 v48, v46
	ds_write_b16 v44, v45 offset:12672
	v_cvt_pk_bf16_f32 v45, v47, s0
	ds_write_b16 v44, v45 offset:3456
	s_waitcnt vmcnt(6)
	v_lshlrev_b32_e32 v45, 16, v202
	v_mul_f32_e32 v45, v46, v45
	v_sub_f32_e32 v47, 1.0, v169
	v_mul_f32_e32 v46, v46, v170
	v_mul_f32_e32 v47, v47, v48
	v_cvt_pk_bf16_f32 v45, v45, s0
	v_rcp_f32_e32 v48, v46
	ds_write_b16 v44, v45 offset:12816
	v_cvt_pk_bf16_f32 v45, v47, s0
	ds_write_b16 v44, v45 offset:3600
	s_waitcnt vmcnt(5)
	v_lshlrev_b32_e32 v45, 16, v203
	v_mul_f32_e32 v45, v46, v45
	v_sub_f32_e32 v47, 1.0, v170
	v_mul_f32_e32 v46, v46, v171
	v_mul_f32_e32 v47, v47, v48
	v_cvt_pk_bf16_f32 v45, v45, s0
	v_rcp_f32_e32 v48, v46
	ds_write_b16 v44, v45 offset:12960
	v_cvt_pk_bf16_f32 v45, v47, s0
	ds_write_b16 v44, v45 offset:3744
	s_waitcnt vmcnt(4)
	v_lshlrev_b32_e32 v45, 16, v204
	v_mul_f32_e32 v45, v46, v45
	v_sub_f32_e32 v47, 1.0, v171
	v_mul_f32_e32 v46, v46, v172
	v_mul_f32_e32 v47, v47, v48
	v_cvt_pk_bf16_f32 v45, v45, s0
	v_rcp_f32_e32 v48, v46
	ds_write_b16 v44, v45 offset:13104
	v_cvt_pk_bf16_f32 v45, v47, s0
	ds_write_b16 v44, v45 offset:3888
	s_waitcnt vmcnt(3)
	v_lshlrev_b32_e32 v45, 16, v205
	v_mul_f32_e32 v45, v46, v45
	v_sub_f32_e32 v47, 1.0, v172
	v_mul_f32_e32 v46, v46, v173
	v_mul_f32_e32 v47, v47, v48
	v_cvt_pk_bf16_f32 v45, v45, s0
	v_rcp_f32_e32 v48, v46
	ds_write_b16 v44, v45 offset:13248
	v_cvt_pk_bf16_f32 v45, v47, s0
	ds_write_b16 v44, v45 offset:4032
	s_waitcnt vmcnt(2)
	v_lshlrev_b32_e32 v45, 16, v206
	v_mul_f32_e32 v45, v46, v45
	v_sub_f32_e32 v47, 1.0, v173
	v_mul_f32_e32 v46, v46, v174
	v_mul_f32_e32 v47, v47, v48
	v_cvt_pk_bf16_f32 v45, v45, s0
	v_rcp_f32_e32 v48, v46
	ds_write_b16 v44, v45 offset:13392
	v_cvt_pk_bf16_f32 v45, v47, s0
	ds_write_b16 v44, v45 offset:4176
	s_waitcnt vmcnt(1)
	v_lshlrev_b32_e32 v45, 16, v207
	v_mul_f32_e32 v45, v46, v45
	v_sub_f32_e32 v47, 1.0, v174
	v_mul_f32_e32 v47, v47, v48
	v_cvt_pk_bf16_f32 v45, v45, s0
	ds_write_b16 v44, v45 offset:13536
	v_cvt_pk_bf16_f32 v45, v47, s0
	ds_write_b16 v44, v45 offset:4320
	v_mul_f32_e32 v45, v46, v175
	v_rcp_f32_e32 v48, v45
	s_waitcnt vmcnt(0)
	v_lshlrev_b32_e32 v47, 16, v52
	v_mul_f32_e32 v46, v45, v47
	v_sub_f32_e32 v47, 1.0, v175
	v_mul_f32_e32 v47, v47, v48
	v_cvt_pk_bf16_f32 v46, v46, s0
	ds_write_b16 v44, v46 offset:13680
	v_cvt_pk_bf16_f32 v46, v47, s0
	ds_write_b16 v44, v46 offset:4464
	s_mov_b32 s0, 0x9000
	global_load_dword v48, v[42:43], off nt
	global_load_dword v49, v[42:43], off offset:1024 nt
	global_load_dword v50, v[42:43], off offset:2048 nt
	global_load_dword v51, v[42:43], off offset:3072 nt
	v_add_co_u32_e32 v42, vcc, s0, v38
	s_mov_b32 s0, 0xb000
	s_nop 0
	v_addc_co_u32_e32 v43, vcc, 0, v39, vcc
	v_add_co_u32_e32 v46, vcc, s72, v38
	s_nop 1
	v_addc_co_u32_e32 v47, vcc, 0, v39, vcc
	global_load_dword v52, v[46:47], off offset:-4096 nt
	global_load_dword v53, v[42:43], off offset:1024 nt
	global_load_dword v54, v[42:43], off offset:2048 nt
	global_load_dword v55, v[42:43], off offset:3072 nt
	global_load_dword v56, v[46:47], off nt
	global_load_dword v57, v[46:47], off offset:1024 nt
	global_load_dword v58, v[46:47], off offset:2048 nt
	global_load_dword v59, v[46:47], off offset:3072 nt
	v_add_co_u32_e32 v42, vcc, s0, v38
	s_mov_b32 s0, 0xd000
	s_nop 0
	v_addc_co_u32_e32 v43, vcc, 0, v39, vcc
	v_add_co_u32_e32 v46, vcc, s74, v38
	s_nop 1
	v_addc_co_u32_e32 v47, vcc, 0, v39, vcc
	global_load_dword v60, v[46:47], off offset:-4096 nt
	global_load_dword v61, v[42:43], off offset:1024 nt
	global_load_dword v62, v[42:43], off offset:2048 nt
	global_load_dword v63, v[42:43], off offset:3072 nt
	global_load_dword v64, v[46:47], off nt
	global_load_dword v65, v[46:47], off offset:1024 nt
	global_load_dword v99, v[46:47], off offset:2048 nt
	global_load_dword v100, v[46:47], off offset:3072 nt
	v_add_co_u32_e32 v42, vcc, s0, v38
	s_mov_b32 s0, 0xf000
	s_nop 0
	v_addc_co_u32_e32 v43, vcc, 0, v39, vcc
	v_add_co_u32_e32 v46, vcc, s75, v38
	s_nop 1
	v_addc_co_u32_e32 v47, vcc, 0, v39, vcc
	v_add_co_u32_e32 v38, vcc, s0, v38
	global_load_dword v101, v[46:47], off offset:-4096 nt
	global_load_dword v102, v[42:43], off offset:1024 nt
	global_load_dword v103, v[42:43], off offset:2048 nt
	s_nop 0
	global_load_dword v42, v[42:43], off offset:3072 nt
	s_nop 0
	global_load_dword v43, v[46:47], off nt
	global_load_dword v104, v[46:47], off offset:1024 nt
	global_load_dword v105, v[46:47], off offset:2048 nt
	s_nop 0
	global_load_dword v46, v[46:47], off offset:3072 nt
	v_addc_co_u32_e32 v39, vcc, 0, v39, vcc
	global_load_dword v47, v[38:39], off nt
	global_load_dword v106, v[38:39], off offset:1024 nt
	global_load_dword v107, v[38:39], off offset:2048 nt
	global_load_dword v108, v[38:39], off offset:3072 nt
	s_nop 0
	global_load_ushort v38, v[40:41], off
	global_load_ushort v112, v[40:41], off offset:512
	global_load_ushort v113, v[40:41], off offset:1024
	global_load_ushort v114, v[40:41], off offset:1536
	global_load_ushort v115, v[40:41], off offset:2048
	global_load_ushort v116, v[40:41], off offset:2560
	global_load_ushort v117, v[40:41], off offset:3072
	global_load_ushort v118, v[40:41], off offset:3584
	s_waitcnt vmcnt(39)
	v_rcp_f32_e32 v39, v48
	s_waitcnt vmcnt(7)
	v_lshlrev_b32_e32 v38, 16, v38
	v_mul_f32_e32 v109, v48, v38
	v_sub_f32_e32 v38, 1.0, v48
	v_mul_f32_e32 v110, v38, v39
	v_add_co_u32_e32 v38, vcc, s92, v36
	v_mul_f32_e32 v48, v48, v49
	s_nop 0
	v_addc_co_u32_e32 v39, vcc, 0, v37, vcc
	v_add_co_u32_e32 v40, vcc, s95, v36
	v_cvt_pk_bf16_f32 v111, v109, s0
	s_nop 0
	v_addc_co_u32_e32 v41, vcc, 0, v37, vcc
	global_load_ushort v119, v[40:41], off offset:-4096
	global_load_ushort v120, v[38:39], off offset:512
	global_load_ushort v121, v[38:39], off offset:1024
	global_load_ushort v122, v[38:39], off offset:1536
	global_load_ushort v123, v[38:39], off offset:2048
	global_load_ushort v124, v[38:39], off offset:2560
	global_load_ushort v125, v[38:39], off offset:3072
	s_nop 0
	global_load_ushort v38, v[38:39], off offset:3584
	s_nop 0
	global_load_ushort v39, v[40:41], off
	global_load_ushort v126, v[40:41], off offset:512
	global_load_ushort v127, v[40:41], off offset:1024
	global_load_ushort v128, v[40:41], off offset:1536
	global_load_ushort v129, v[40:41], off offset:2048
	global_load_ushort v131, v[40:41], off offset:2560
	global_load_ushort v132, v[40:41], off offset:3072
	s_nop 0
	global_load_ushort v40, v[40:41], off offset:3584
	v_add_co_u32_e32 v36, vcc, s85, v36
	v_sub_f32_e32 v49, 1.0, v49
	s_nop 0
	v_addc_co_u32_e32 v37, vcc, 0, v37, vcc
	global_load_ushort v41, v[36:37], off
	global_load_ushort v133, v[36:37], off offset:512
	global_load_ushort v134, v[36:37], off offset:1024
	global_load_ushort v135, v[36:37], off offset:1536
	global_load_ushort v136, v[36:37], off offset:2048
	global_load_ushort v137, v[36:37], off offset:2560
	global_load_ushort v138, v[36:37], off offset:3072
	s_nop 0
	global_load_ushort v36, v[36:37], off offset:3584
	v_cvt_pk_bf16_f32 v37, v110, s0
	ds_write_b16 v44, v37 offset:4608
	v_mul_f32_e32 v37, v45, v109
	v_rcp_f32_e32 v109, v48
	v_cvt_pk_bf16_f32 v37, v37, s0
	ds_write_b16 v44, v37 offset:18432
	s_waitcnt vmcnt(30)
	v_lshlrev_b32_e32 v37, 16, v112
	v_mul_f32_e32 v49, v49, v109
	v_mul_f32_e32 v37, v48, v37
	v_cvt_pk_bf16_f32 v49, v49, s0
	v_mul_f32_e32 v48, v48, v50
	v_cvt_pk_bf16_f32 v109, v37, s0
	ds_write_b16 v44, v49 offset:4752
	v_mul_f32_e32 v37, v45, v37
	v_sub_f32_e32 v49, 1.0, v50
	v_rcp_f32_e32 v50, v48
	v_cvt_pk_bf16_f32 v37, v37, s0
	ds_write_b16 v44, v37 offset:18576
	s_waitcnt vmcnt(29)
	v_lshlrev_b32_e32 v37, 16, v113
	v_mul_f32_e32 v37, v48, v37
	v_mul_f32_e32 v49, v49, v50
	v_cvt_pk_bf16_f32 v50, v37, s0
	v_mul_f32_e32 v48, v48, v51
	ds_write_b16 v44, v50 offset:14112
	v_mul_f32_e32 v37, v45, v37
	v_rcp_f32_e32 v50, v48
	v_cvt_pk_bf16_f32 v37, v37, s0
	v_cvt_pk_bf16_f32 v49, v49, s0
	ds_write_b16 v44, v37 offset:18720
	s_waitcnt vmcnt(28)
	v_lshlrev_b32_e32 v37, 16, v114
	ds_write_b16 v44, v49 offset:4896
	v_mul_f32_e32 v37, v48, v37
	v_sub_f32_e32 v49, 1.0, v51
	v_mul_f32_e32 v49, v49, v50
	v_cvt_pk_bf16_f32 v50, v37, s0
	v_mul_f32_e32 v48, v48, v52
	ds_write_b16 v44, v50 offset:14256
	v_mul_f32_e32 v37, v45, v37
	v_rcp_f32_e32 v50, v48
	v_cvt_pk_bf16_f32 v37, v37, s0
	v_cvt_pk_bf16_f32 v49, v49, s0
	ds_write_b16 v44, v37 offset:18864
	s_waitcnt vmcnt(27)
	v_lshlrev_b32_e32 v37, 16, v115
	ds_write_b16 v44, v49 offset:5040
	v_mul_f32_e32 v37, v48, v37
	v_sub_f32_e32 v49, 1.0, v52
	v_mul_f32_e32 v49, v49, v50
	v_cvt_pk_bf16_f32 v50, v37, s0
	v_mul_f32_e32 v48, v48, v53
	ds_write_b16 v44, v50 offset:14400
	v_mul_f32_e32 v37, v45, v37
	v_rcp_f32_e32 v50, v48
	v_cvt_pk_bf16_f32 v37, v37, s0
	v_cvt_pk_bf16_f32 v49, v49, s0
	ds_write_b16 v44, v37 offset:19008
	s_waitcnt vmcnt(26)
	v_lshlrev_b32_e32 v37, 16, v116
	ds_write_b16 v44, v49 offset:5184
	v_mul_f32_e32 v37, v48, v37
	v_sub_f32_e32 v49, 1.0, v53
	v_mul_f32_e32 v49, v49, v50
	v_cvt_pk_bf16_f32 v50, v37, s0
	v_mul_f32_e32 v48, v48, v54
	ds_write_b16 v44, v50 offset:14544
	v_mul_f32_e32 v37, v45, v37
	v_rcp_f32_e32 v50, v48
	v_cvt_pk_bf16_f32 v37, v37, s0
	v_cvt_pk_bf16_f32 v49, v49, s0
	ds_write_b16 v44, v37 offset:19152
	s_waitcnt vmcnt(25)
	v_lshlrev_b32_e32 v37, 16, v117
	ds_write_b16 v44, v49 offset:5328
	v_mul_f32_e32 v37, v48, v37
	v_sub_f32_e32 v49, 1.0, v54
	v_mul_f32_e32 v49, v49, v50
	v_cvt_pk_bf16_f32 v50, v37, s0
	v_mul_f32_e32 v48, v48, v55
	ds_write_b16 v44, v50 offset:14688
	v_mul_f32_e32 v37, v45, v37
	v_rcp_f32_e32 v50, v48
	v_cvt_pk_bf16_f32 v37, v37, s0
	v_cvt_pk_bf16_f32 v49, v49, s0
	ds_write_b16 v44, v37 offset:19296
	s_waitcnt vmcnt(24)
	v_lshlrev_b32_e32 v37, 16, v118
	ds_write_b16 v44, v49 offset:5472
	v_mul_f32_e32 v37, v48, v37
	v_sub_f32_e32 v49, 1.0, v55
	v_mul_f32_e32 v49, v49, v50
	v_cvt_pk_bf16_f32 v50, v37, s0
	v_mul_f32_e32 v48, v48, v56
	ds_write_b16 v44, v50 offset:14832
	v_mul_f32_e32 v37, v45, v37
	v_rcp_f32_e32 v50, v48
	v_cvt_pk_bf16_f32 v37, v37, s0
	v_cvt_pk_bf16_f32 v49, v49, s0
	ds_write_b16 v44, v37 offset:19440
	s_waitcnt vmcnt(23)
	v_lshlrev_b32_e32 v37, 16, v119
	ds_write_b16 v44, v49 offset:5616
	v_mul_f32_e32 v37, v48, v37
	v_sub_f32_e32 v49, 1.0, v56
	v_mul_f32_e32 v49, v49, v50
	v_cvt_pk_bf16_f32 v50, v37, s0
	v_mul_f32_e32 v48, v48, v57
	ds_write_b16 v44, v50 offset:14976
	v_mul_f32_e32 v37, v45, v37
	v_rcp_f32_e32 v50, v48
	v_cvt_pk_bf16_f32 v37, v37, s0
	v_cvt_pk_bf16_f32 v49, v49, s0
	ds_write_b16 v44, v37 offset:19584
	s_waitcnt vmcnt(22)
	v_lshlrev_b32_e32 v37, 16, v120
	ds_write_b16 v44, v49 offset:5760
	v_mul_f32_e32 v37, v48, v37
	v_sub_f32_e32 v49, 1.0, v57
	v_mul_f32_e32 v49, v49, v50
	v_cvt_pk_bf16_f32 v50, v37, s0
	v_mul_f32_e32 v48, v48, v58
	ds_write_b16 v44, v50 offset:15120
	v_mul_f32_e32 v37, v45, v37
	v_rcp_f32_e32 v50, v48
	v_cvt_pk_bf16_f32 v37, v37, s0
	v_cvt_pk_bf16_f32 v49, v49, s0
	ds_write_b16 v44, v37 offset:19728
	s_waitcnt vmcnt(21)
	v_lshlrev_b32_e32 v37, 16, v121
	ds_write_b16 v44, v49 offset:5904
	v_mul_f32_e32 v37, v48, v37
	v_sub_f32_e32 v49, 1.0, v58
	v_mul_f32_e32 v49, v49, v50
	v_cvt_pk_bf16_f32 v50, v37, s0
	v_mul_f32_e32 v48, v48, v59
	ds_write_b16 v44, v50 offset:15264
	v_mul_f32_e32 v37, v45, v37
	v_rcp_f32_e32 v50, v48
	v_cvt_pk_bf16_f32 v37, v37, s0
	v_cvt_pk_bf16_f32 v49, v49, s0
	ds_write_b16 v44, v37 offset:19872
	s_waitcnt vmcnt(20)
	v_lshlrev_b32_e32 v37, 16, v122
	ds_write_b16 v44, v49 offset:6048
	v_mul_f32_e32 v37, v48, v37
	v_sub_f32_e32 v49, 1.0, v59
	v_mul_f32_e32 v49, v49, v50
	v_cvt_pk_bf16_f32 v50, v37, s0
	v_mul_f32_e32 v48, v48, v60
	ds_write_b16 v44, v50 offset:15408
	v_mul_f32_e32 v37, v45, v37
	v_rcp_f32_e32 v50, v48
	v_cvt_pk_bf16_f32 v37, v37, s0
	v_cvt_pk_bf16_f32 v49, v49, s0
	ds_write_b16 v44, v37 offset:20016
	s_waitcnt vmcnt(19)
	v_lshlrev_b32_e32 v37, 16, v123
	ds_write_b16 v44, v49 offset:6192
	v_mul_f32_e32 v37, v48, v37
	v_sub_f32_e32 v49, 1.0, v60
	v_mul_f32_e32 v49, v49, v50
	v_cvt_pk_bf16_f32 v50, v37, s0
	v_mul_f32_e32 v48, v48, v61
	ds_write_b16 v44, v50 offset:15552
	v_mul_f32_e32 v37, v45, v37
	v_rcp_f32_e32 v50, v48
	v_cvt_pk_bf16_f32 v37, v37, s0
	v_cvt_pk_bf16_f32 v49, v49, s0
	ds_write_b16 v44, v37 offset:20160
	s_waitcnt vmcnt(18)
	v_lshlrev_b32_e32 v37, 16, v124
	ds_write_b16 v44, v49 offset:6336
	v_mul_f32_e32 v37, v48, v37
	v_sub_f32_e32 v49, 1.0, v61
	v_mul_f32_e32 v49, v49, v50
	v_cvt_pk_bf16_f32 v50, v37, s0
	v_mul_f32_e32 v48, v48, v62
	ds_write_b16 v44, v50 offset:15696
	v_mul_f32_e32 v37, v45, v37
	v_rcp_f32_e32 v50, v48
	v_cvt_pk_bf16_f32 v37, v37, s0
	v_cvt_pk_bf16_f32 v49, v49, s0
	ds_write_b16 v44, v37 offset:20304
	s_waitcnt vmcnt(17)
	v_lshlrev_b32_e32 v37, 16, v125
	ds_write_b16 v44, v49 offset:6480
	v_mul_f32_e32 v37, v48, v37
	v_sub_f32_e32 v49, 1.0, v62
	v_mul_f32_e32 v49, v49, v50
	v_cvt_pk_bf16_f32 v50, v37, s0
	v_mul_f32_e32 v37, v45, v37
	v_cvt_pk_bf16_f32 v37, v37, s0
	v_cvt_pk_bf16_f32 v49, v49, s0
	ds_write_b16 v44, v37 offset:20448
	s_waitcnt vmcnt(16)
	v_lshlrev_b32_e32 v37, 16, v38
	v_mul_f32_e32 v38, v48, v63
	ds_write_b16 v44, v49 offset:6624
	v_rcp_f32_e32 v49, v38
	v_sub_f32_e32 v48, 1.0, v63
	v_mul_f32_e32 v37, v38, v37
	v_mul_f32_e32 v38, v38, v64
	v_mul_f32_e32 v48, v48, v49
	v_cvt_pk_bf16_f32 v48, v48, s0
	v_cvt_pk_bf16_f32 v49, v37, s0
	ds_write_b16 v44, v48 offset:6768
	v_mul_f32_e32 v37, v45, v37
	v_rcp_f32_e32 v48, v38
	v_cvt_pk_bf16_f32 v37, v37, s0
	ds_write_b16 v44, v37 offset:20592
	s_waitcnt vmcnt(15)
	v_lshlrev_b32_e32 v37, 16, v39
	v_mul_f32_e32 v37, v38, v37
	v_sub_f32_e32 v39, 1.0, v64
	v_mul_f32_e32 v39, v39, v48
	v_cvt_pk_bf16_f32 v48, v37, s0
	v_mul_f32_e32 v38, v38, v65
	ds_write_b16 v44, v48 offset:16128
	v_mul_f32_e32 v37, v45, v37
	v_rcp_f32_e32 v48, v38
	v_cvt_pk_bf16_f32 v37, v37, s0
	v_cvt_pk_bf16_f32 v39, v39, s0
	ds_write_b16 v44, v37 offset:20736
	s_waitcnt vmcnt(14)
	v_lshlrev_b32_e32 v37, 16, v126
	ds_write_b16 v44, v39 offset:6912
	v_mul_f32_e32 v37, v38, v37
	v_sub_f32_e32 v39, 1.0, v65
	v_mul_f32_e32 v39, v39, v48
	v_cvt_pk_bf16_f32 v48, v37, s0
	v_mul_f32_e32 v38, v38, v99
	ds_write_b16 v44, v48 offset:16272
	v_mul_f32_e32 v37, v45, v37
	v_rcp_f32_e32 v48, v38
	v_cvt_pk_bf16_f32 v37, v37, s0
	v_cvt_pk_bf16_f32 v39, v39, s0
	ds_write_b16 v44, v37 offset:20880
	s_waitcnt vmcnt(13)
	v_lshlrev_b32_e32 v37, 16, v127
	ds_write_b16 v44, v39 offset:7056
	v_mul_f32_e32 v37, v38, v37
	v_sub_f32_e32 v39, 1.0, v99
	v_mul_f32_e32 v39, v39, v48
	v_cvt_pk_bf16_f32 v48, v37, s0
	v_mul_f32_e32 v38, v38, v100
	ds_write_b16 v44, v48 offset:16416
	v_mul_f32_e32 v37, v45, v37
	v_rcp_f32_e32 v48, v38
	v_cvt_pk_bf16_f32 v37, v37, s0
	v_cvt_pk_bf16_f32 v39, v39, s0
	ds_write_b16 v44, v37 offset:21024
	s_waitcnt vmcnt(12)
	v_lshlrev_b32_e32 v37, 16, v128
	ds_write_b16 v44, v39 offset:7200
	v_mul_f32_e32 v37, v38, v37
	v_sub_f32_e32 v39, 1.0, v100
	v_mul_f32_e32 v39, v39, v48
	v_cvt_pk_bf16_f32 v48, v37, s0
	v_mul_f32_e32 v38, v38, v101
	ds_write_b16 v44, v48 offset:16560
	v_mul_f32_e32 v37, v45, v37
	v_rcp_f32_e32 v48, v38
	v_cvt_pk_bf16_f32 v37, v37, s0
	v_cvt_pk_bf16_f32 v39, v39, s0
	ds_write_b16 v44, v37 offset:21168
	s_waitcnt vmcnt(11)
	v_lshlrev_b32_e32 v37, 16, v129
	ds_write_b16 v44, v39 offset:7344
	v_mul_f32_e32 v37, v38, v37
	v_sub_f32_e32 v39, 1.0, v101
	v_mul_f32_e32 v39, v39, v48
	v_cvt_pk_bf16_f32 v48, v37, s0
	v_mul_f32_e32 v38, v38, v102
	ds_write_b16 v44, v48 offset:16704
	v_mul_f32_e32 v37, v45, v37
	v_rcp_f32_e32 v48, v38
	v_cvt_pk_bf16_f32 v37, v37, s0
	v_cvt_pk_bf16_f32 v39, v39, s0
	ds_write_b16 v44, v37 offset:21312
	s_waitcnt vmcnt(10)
	v_lshlrev_b32_e32 v37, 16, v131
	ds_write_b16 v44, v39 offset:7488
	v_mul_f32_e32 v37, v38, v37
	v_sub_f32_e32 v39, 1.0, v102
	v_mul_f32_e32 v39, v39, v48
	v_cvt_pk_bf16_f32 v48, v37, s0
	v_mul_f32_e32 v38, v38, v103
	ds_write_b16 v44, v48 offset:16848
	v_mul_f32_e32 v37, v45, v37
	v_rcp_f32_e32 v48, v38
	v_cvt_pk_bf16_f32 v37, v37, s0
	v_cvt_pk_bf16_f32 v39, v39, s0
	ds_write_b16 v44, v37 offset:21456
	s_waitcnt vmcnt(9)
	v_lshlrev_b32_e32 v37, 16, v132
	ds_write_b16 v44, v39 offset:7632
	v_mul_f32_e32 v37, v38, v37
	v_sub_f32_e32 v39, 1.0, v103
	v_mul_f32_e32 v39, v39, v48
	v_cvt_pk_bf16_f32 v48, v37, s0
	v_mul_f32_e32 v37, v45, v37
	v_cvt_pk_bf16_f32 v37, v37, s0
	v_mul_f32_e32 v38, v38, v42
	ds_write_b16 v44, v37 offset:21600
	s_waitcnt vmcnt(8)
	v_lshlrev_b32_e32 v37, 16, v40
	v_rcp_f32_e32 v40, v38
	v_cvt_pk_bf16_f32 v39, v39, s0
	ds_write_b16 v44, v39 offset:7776
	v_mul_f32_e32 v37, v38, v37
	v_sub_f32_e32 v39, 1.0, v42
	v_mul_f32_e32 v39, v39, v40
	v_cvt_pk_bf16_f32 v40, v37, s0
	v_mul_f32_e32 v38, v38, v43
	ds_write_b16 v44, v40 offset:17136
	v_mul_f32_e32 v37, v45, v37
	v_rcp_f32_e32 v40, v38
	v_cvt_pk_bf16_f32 v37, v37, s0
	v_cvt_pk_bf16_f32 v39, v39, s0
	ds_write_b16 v44, v37 offset:21744
	s_waitcnt vmcnt(7)
	v_lshlrev_b32_e32 v37, 16, v41
	ds_write_b16 v44, v39 offset:7920
	v_mul_f32_e32 v37, v38, v37
	v_sub_f32_e32 v39, 1.0, v43
	v_mul_f32_e32 v39, v39, v40
	v_cvt_pk_bf16_f32 v40, v37, s0
	v_mul_f32_e32 v38, v38, v104
	ds_write_b16 v44, v40 offset:17280
	v_mul_f32_e32 v37, v45, v37
	v_rcp_f32_e32 v40, v38
	v_cvt_pk_bf16_f32 v37, v37, s0
	v_cvt_pk_bf16_f32 v39, v39, s0
	ds_write_b16 v44, v37 offset:21888
	s_waitcnt vmcnt(6)
	v_lshlrev_b32_e32 v37, 16, v133
	ds_write_b16 v44, v39 offset:8064
	v_mul_f32_e32 v37, v38, v37
	v_sub_f32_e32 v39, 1.0, v104
	v_mul_f32_e32 v39, v39, v40
	v_cvt_pk_bf16_f32 v40, v37, s0
	v_mul_f32_e32 v38, v38, v105
	ds_write_b16 v44, v40 offset:17424
	v_mul_f32_e32 v37, v45, v37
	v_rcp_f32_e32 v40, v38
	v_cvt_pk_bf16_f32 v37, v37, s0
	v_cvt_pk_bf16_f32 v39, v39, s0
	ds_write_b16 v44, v37 offset:22032
	s_waitcnt vmcnt(5)
	v_lshlrev_b32_e32 v37, 16, v134
	ds_write_b16 v44, v39 offset:8208
	v_mul_f32_e32 v37, v38, v37
	v_sub_f32_e32 v39, 1.0, v105
	v_mul_f32_e32 v39, v39, v40
	v_cvt_pk_bf16_f32 v40, v37, s0
	v_mul_f32_e32 v38, v38, v46
	ds_write_b16 v44, v40 offset:17568
	v_mul_f32_e32 v37, v45, v37
	v_rcp_f32_e32 v40, v38
	v_cvt_pk_bf16_f32 v37, v37, s0
	v_cvt_pk_bf16_f32 v39, v39, s0
	ds_write_b16 v44, v37 offset:22176
	s_waitcnt vmcnt(4)
	v_lshlrev_b32_e32 v37, 16, v135
	ds_write_b16 v44, v39 offset:8352
	v_mul_f32_e32 v37, v38, v37
	v_sub_f32_e32 v39, 1.0, v46
	v_mul_f32_e32 v39, v39, v40
	v_cvt_pk_bf16_f32 v40, v37, s0
	v_mul_f32_e32 v38, v38, v47
	ds_write_b16 v44, v40 offset:17712
	v_mul_f32_e32 v37, v45, v37
	v_rcp_f32_e32 v40, v38
	v_cvt_pk_bf16_f32 v37, v37, s0
	v_cvt_pk_bf16_f32 v39, v39, s0
	ds_write_b16 v44, v37 offset:22320
	s_waitcnt vmcnt(3)
	v_lshlrev_b32_e32 v37, 16, v136
	ds_write_b16 v44, v39 offset:8496
	v_mul_f32_e32 v37, v38, v37
	v_sub_f32_e32 v39, 1.0, v47
	v_mul_f32_e32 v39, v39, v40
	v_cvt_pk_bf16_f32 v40, v37, s0
	v_mul_f32_e32 v38, v38, v106
	ds_write_b16 v44, v40 offset:17856
	v_mul_f32_e32 v37, v45, v37
	v_rcp_f32_e32 v40, v38
	v_cvt_pk_bf16_f32 v37, v37, s0
	v_cvt_pk_bf16_f32 v39, v39, s0
	ds_write_b16 v44, v37 offset:22464
	s_waitcnt vmcnt(2)
	v_lshlrev_b32_e32 v37, 16, v137
	ds_write_b16 v44, v39 offset:8640
	v_mul_f32_e32 v37, v38, v37
	v_sub_f32_e32 v39, 1.0, v106
	v_mul_f32_e32 v39, v39, v40
	v_cvt_pk_bf16_f32 v40, v37, s0
	v_mul_f32_e32 v38, v38, v107
	ds_write_b16 v44, v40 offset:18000
	v_mul_f32_e32 v37, v45, v37
	v_rcp_f32_e32 v40, v38
	v_cvt_pk_bf16_f32 v37, v37, s0
	v_cvt_pk_bf16_f32 v39, v39, s0
	ds_write_b16 v44, v37 offset:22608
	s_waitcnt vmcnt(1)
	v_lshlrev_b32_e32 v37, 16, v138
	ds_write_b16 v44, v39 offset:8784
	v_mul_f32_e32 v37, v38, v37
	v_sub_f32_e32 v39, 1.0, v107
	v_mul_f32_e32 v39, v39, v40
	v_cvt_pk_bf16_f32 v40, v37, s0
	v_mul_f32_e32 v37, v45, v37
	v_cvt_pk_bf16_f32 v37, v37, s0
	ds_write_b16 v44, v37 offset:22752
	s_waitcnt vmcnt(0)
	v_lshlrev_b32_e32 v36, 16, v36
	v_mul_f32_e32 v37, v38, v108
	v_mul_f32_e32 v36, v37, v36
	v_rcp_f32_e32 v37, v37
	v_sub_f32_e32 v38, 1.0, v108
	v_cvt_pk_bf16_f32 v39, v39, s0
	ds_write_b16 v44, v111 offset:13824
	v_mul_f32_e32 v37, v38, v37
	v_cvt_pk_bf16_f32 v38, v36, s0
	v_mul_f32_e32 v36, v45, v36
	v_cvt_pk_bf16_f32 v37, v37, s0
	v_cvt_pk_bf16_f32 v36, v36, s0
	ds_write_b16 v44, v109 offset:13968
	ds_write_b16 v44, v50 offset:15840
	ds_write_b16 v44, v49 offset:15984
	ds_write_b16 v44, v48 offset:16992
	ds_write_b16 v44, v40 offset:18144
	ds_write_b16 v44, v39 offset:8928
	ds_write_b16 v44, v38 offset:18288
	ds_write_b16 v44, v37 offset:9072
	ds_write_b16 v44, v36 offset:22896
	s_waitcnt lgkmcnt(0)
	global_load_ushort v136, v[34:35], off
	global_load_ushort v137, v[34:35], off offset:512
	v_and_b32_e32 v99, 31, v98
	v_ashrrev_i32_e32 v128, 5, v98
	v_lshlrev_b32_e32 v131, 3, v128
	v_mul_lo_u32 v98, v98, s14
	v_add_u32_e32 v98, s7, v98
	global_load_ushort v138, v[34:35], off offset:1024
	global_load_ushort v139, v[34:35], off offset:1536
	global_load_ushort v140, v[34:35], off offset:2048
	global_load_ushort v141, v[34:35], off offset:2560
	global_load_ushort v142, v[34:35], off offset:3072
	global_load_ushort v143, v[34:35], off offset:3584
	v_add_co_u32_e32 v36, vcc, s15, v34
	s_nop 1
	v_addc_co_u32_e32 v37, vcc, 0, v35, vcc
	v_add_co_u32_e32 v38, vcc, s93, v34
	s_nop 1
	v_addc_co_u32_e32 v39, vcc, 0, v35, vcc
	global_load_ushort v144, v[38:39], off offset:-4096
	global_load_ushort v145, v[36:37], off offset:512
	global_load_ushort v146, v[36:37], off offset:1024
	global_load_ushort v147, v[36:37], off offset:1536
	global_load_ushort v148, v[36:37], off offset:2048
	global_load_ushort v149, v[36:37], off offset:2560
	global_load_ushort v150, v[36:37], off offset:3072
	s_nop 0
	global_load_ushort v151, v[36:37], off offset:3584
	global_load_ushort v152, v[38:39], off
	global_load_ushort v153, v[38:39], off offset:512
	global_load_ushort v154, v[38:39], off offset:1024
	global_load_ushort v155, v[38:39], off offset:1536
	global_load_ushort v156, v[38:39], off offset:2048
	global_load_ushort v157, v[38:39], off offset:2560
	global_load_ushort v158, v[38:39], off offset:3072
	global_load_ushort v159, v[38:39], off offset:3584
	v_add_co_u32_e32 v36, vcc, s87, v34
	s_nop 1
	v_addc_co_u32_e32 v37, vcc, 0, v35, vcc
	v_add_co_u32_e32 v38, vcc, s81, v34
	s_nop 1
	v_addc_co_u32_e32 v39, vcc, 0, v35, vcc
	global_load_ushort v160, v[38:39], off offset:-4096
	global_load_ushort v161, v[36:37], off offset:512
	global_load_ushort v162, v[36:37], off offset:1024
	global_load_ushort v163, v[36:37], off offset:1536
	global_load_ushort v164, v[36:37], off offset:2048
	global_load_ushort v165, v[36:37], off offset:2560
	global_load_ushort v166, v[36:37], off offset:3072
	s_nop 0
	global_load_ushort v167, v[36:37], off offset:3584
	global_load_ushort v168, v[38:39], off
	global_load_ushort v169, v[38:39], off offset:512
	global_load_ushort v170, v[38:39], off offset:1024
	global_load_ushort v171, v[38:39], off offset:1536
	global_load_ushort v172, v[38:39], off offset:2048
	global_load_ushort v173, v[38:39], off offset:2560
	global_load_ushort v174, v[38:39], off offset:3072
	global_load_ushort v175, v[38:39], off offset:3584
	v_add_co_u32_e32 v36, vcc, s92, v34
	s_nop 1
	v_addc_co_u32_e32 v37, vcc, 0, v35, vcc
	v_add_co_u32_e32 v38, vcc, s95, v34
	s_nop 1
	v_addc_co_u32_e32 v39, vcc, 0, v35, vcc
	global_load_ushort v176, v[38:39], off offset:-4096
	global_load_ushort v177, v[36:37], off offset:512
	v_add_co_u32_e32 v34, vcc, s85, v34
	s_mov_b32 s85, s13
	s_nop 0
	v_addc_co_u32_e32 v35, vcc, 0, v35, vcc
	global_load_ushort v178, v[36:37], off offset:1024
	global_load_ushort v179, v[36:37], off offset:1536
	global_load_ushort v192, v[36:37], off offset:2048
	global_load_ushort v193, v[36:37], off offset:2560
	global_load_ushort v194, v[36:37], off offset:3072
	s_nop 0
	global_load_ushort v195, v[36:37], off offset:3584
	global_load_ushort v196, v[38:39], off
	global_load_ushort v197, v[38:39], off offset:512
	global_load_ushort v198, v[38:39], off offset:1024
	global_load_ushort v199, v[38:39], off offset:1536
	global_load_ushort v200, v[38:39], off offset:2048
	global_load_ushort v201, v[38:39], off offset:2560
	global_load_ushort v202, v[38:39], off offset:3072
	global_load_ushort v203, v[38:39], off offset:3584
	global_load_ushort v204, v[34:35], off
	global_load_ushort v205, v[34:35], off offset:512
	global_load_ushort v206, v[34:35], off offset:1024
	global_load_ushort v207, v[34:35], off offset:1536
	global_load_ushort v224, v[34:35], off offset:2048
	global_load_ushort v225, v[34:35], off offset:2560
	global_load_ushort v226, v[34:35], off offset:3072
	s_nop 0
	global_load_ushort v227, v[34:35], off offset:3584
	s_waitcnt vmcnt(0)
	v_lshl_or_b32 v100, v137, 16, v136
	v_lshl_or_b32 v101, v139, 16, v138
	v_lshl_or_b32 v102, v141, 16, v140
	v_lshl_or_b32 v103, v143, 16, v142
	v_lshl_or_b32 v104, v145, 16, v144
	v_lshl_or_b32 v105, v147, 16, v146
	v_lshl_or_b32 v106, v149, 16, v148
	v_lshl_or_b32 v107, v151, 16, v150
	v_lshl_or_b32 v108, v153, 16, v152
	v_lshl_or_b32 v109, v155, 16, v154
	v_lshl_or_b32 v110, v157, 16, v156
	v_lshl_or_b32 v111, v159, 16, v158
	v_lshl_or_b32 v112, v161, 16, v160
	v_lshl_or_b32 v113, v163, 16, v162
	v_lshl_or_b32 v114, v165, 16, v164
	v_lshl_or_b32 v115, v167, 16, v166
	v_lshl_or_b32 v116, v169, 16, v168
	v_lshl_or_b32 v117, v171, 16, v170
	v_lshl_or_b32 v118, v173, 16, v172
	v_lshl_or_b32 v119, v175, 16, v174
	v_lshl_or_b32 v120, v177, 16, v176
	v_lshl_or_b32 v121, v179, 16, v178
	v_lshl_or_b32 v122, v193, 16, v192
	v_lshl_or_b32 v123, v195, 16, v194
	v_lshl_or_b32 v124, v197, 16, v196
	v_lshl_or_b32 v125, v199, 16, v198
	v_lshl_or_b32 v126, v201, 16, v200
	v_lshl_or_b32 v127, v203, 16, v202
	v_lshl_or_b32 v132, v205, 16, v204
	v_lshl_or_b32 v133, v207, 16, v206
	v_lshl_or_b32 v134, v225, 16, v224
	v_lshl_or_b32 v135, v227, 16, v226
	v_mul_u32_u24_e32 v34, 0x48, v99
	v_lshl_add_u32 v129, v34, 1, s7
	v_lshl_add_u32 v180, v128, 4, v129
	ds_read_b128 v[50:53], v180 offset:4608
	ds_read_b128 v[34:37], v180 offset:9216
	ds_read_b128 v[54:57], v180 offset:13824
	ds_read_b128 v[136:139], v180 offset:18432
	ds_read_b128 v[140:143], v180
	ds_read_b128 v[144:147], v180 offset:32
	s_waitcnt lgkmcnt(3)
	v_mfma_f32_32x32x16_bf16 v[50:65], v[50:53], v[54:57], 0
	ds_read_b128 v[148:151], v180 offset:4640
	ds_read_b128 v[152:155], v180 offset:9248
	ds_read_b128 v[156:159], v180 offset:13856
	ds_read_b128 v[160:163], v180 offset:18464
	v_lshlrev_b32_e32 v128, 2, v128
	v_cmp_gt_i32_e32 vcc, v128, v99
	v_cmp_lt_i32_e64 s[40:41], v128, v99
	s_waitcnt lgkmcnt(5)
	v_mfma_f32_32x32x16_bf16 v[34:49], v[140:143], v[34:37], 0
	s_waitcnt lgkmcnt(1)
	v_mfma_f32_32x32x16_bf16 v[50:65], v[148:151], v[156:159], v[50:65]
	v_mfma_f32_32x32x16_bf16 v[34:49], v[144:147], v[152:155], v[34:49]
	ds_read_b128 v[148:151], v180 offset:64
	ds_read_b128 v[152:155], v180 offset:4672
	ds_read_b128 v[156:159], v180 offset:9280
	ds_read_b128 v[164:167], v180 offset:13888
	ds_read_b128 v[168:171], v180 offset:18496
	s_waitcnt lgkmcnt(1)
	v_mfma_f32_32x32x16_bf16 v[50:65], v[152:155], v[164:167], v[50:65]
	v_mfma_f32_32x32x16_bf16 v[34:49], v[148:151], v[156:159], v[34:49]
	ds_read_b128 v[152:155], v180 offset:96
	ds_read_b128 v[156:159], v180 offset:4704
	ds_read_b128 v[164:167], v180 offset:9312
	ds_read_b128 v[172:175], v180 offset:13920
	ds_read_b128 v[176:179], v180 offset:18528
	ds_write_b128 v98, v[100:103]
	ds_write_b128 v98, v[104:107] offset:16
	ds_write_b128 v98, v[108:111] offset:32
	ds_write_b128 v98, v[112:115] offset:48
	ds_write_b128 v98, v[116:119] offset:64
	ds_write_b128 v98, v[120:123] offset:80
	ds_write_b128 v98, v[124:127] offset:96
	ds_write_b128 v98, v[132:135] offset:112
	v_add_u32_e32 v102, v129, v131
	v_add_u32_e32 v131, v102, v131
	s_waitcnt lgkmcnt(9)
	v_mfma_f32_32x32x16_bf16 v[50:65], v[156:159], v[172:175], v[50:65]
	v_mfma_f32_32x32x16_bf16 v[34:49], v[152:155], v[164:167], v[34:49]
	s_nop 10
	v_cndmask_b32_e64 v156, v50, 0, vcc
	v_cndmask_b32_e64 v156, v156, v50, s[40:41]
	v_or_b32_e32 v50, 2, v128
	v_cmp_gt_i32_e64 s[42:43], v50, v99
	v_or_b32_e32 v50, 3, v128
	v_cmp_gt_i32_e64 s[44:45], v50, v99
	v_add_u32_e32 v50, 8, v128
	v_cmp_gt_i32_e64 s[46:47], v50, v99
	v_cmp_lt_i32_e64 s[48:49], v50, v99
	v_add_u32_e32 v50, 10, v128
	v_cmp_gt_i32_e64 s[50:51], v50, v99
	v_add_u32_e32 v50, 11, v128
	v_cmp_gt_i32_e64 s[54:55], v50, v99
	v_add_u32_e32 v50, 16, v128
	v_cmp_gt_i32_e64 s[56:57], v50, v99
	v_cmp_lt_i32_e64 s[58:59], v50, v99
	v_add_u32_e32 v50, 18, v128
	v_cmp_gt_i32_e64 s[60:61], v50, v99
	v_add_u32_e32 v50, 19, v128
	v_cmp_gt_i32_e64 s[62:63], v50, v99
	v_add_u32_e32 v50, 24, v128
	v_cndmask_b32_e64 v157, 0, v51, s[40:41]
	v_cndmask_b32_e64 v51, v54, 0, s[46:47]
	v_cmp_gt_i32_e64 s[64:65], v50, v99
	v_cmp_lt_i32_e64 s[66:67], v50, v99
	v_add_u32_e32 v50, 26, v128
	v_cndmask_b32_e64 v164, v51, v54, s[48:49]
	v_cndmask_b32_e64 v51, v58, 0, s[56:57]
	v_cmp_gt_i32_e64 s[68:69], v50, v99
	v_add_u32_e32 v50, 27, v128
	v_cndmask_b32_e64 v172, v51, v58, s[58:59]
	v_cndmask_b32_e64 v51, v62, 0, s[64:65]
	v_cmp_gt_i32_e64 s[70:71], v50, v99
	v_cndmask_b32_e64 v158, v52, 0, s[42:43]
	v_cndmask_b32_e64 v159, v53, 0, s[44:45]
	v_cndmask_b32_e64 v165, 0, v55, s[48:49]
	v_cndmask_b32_e64 v166, v56, 0, s[50:51]
	v_cndmask_b32_e64 v167, v57, 0, s[54:55]
	v_cndmask_b32_e64 v173, 0, v59, s[58:59]
	v_cndmask_b32_e64 v174, v60, 0, s[60:61]
	v_cndmask_b32_e64 v175, v61, 0, s[62:63]
	v_cndmask_b32_e64 v181, v51, v62, s[66:67]
	v_cndmask_b32_e64 v186, 0, v63, s[66:67]
	v_cndmask_b32_e64 v187, v64, 0, s[68:69]
	v_cndmask_b32_e64 v99, v65, 0, s[70:71]
	v_mfma_f32_32x32x16_bf16 v[50:65], v[140:143], v[136:139], 0
	v_cndmask_b32_e64 v98, v34, 0, vcc
	v_cndmask_b32_e64 v34, v98, v34, s[40:41]
	v_cndmask_b32_e64 v98, v38, 0, s[46:47]
	v_cndmask_b32_e64 v38, v98, v38, s[48:49]
	v_cndmask_b32_e64 v98, v42, 0, s[56:57]
	v_cndmask_b32_e64 v35, 0, v35, s[40:41]
	v_cndmask_b32_e64 v36, v36, 0, s[42:43]
	v_mfma_f32_32x32x16_bf16 v[50:65], v[144:147], v[160:163], v[50:65]
	v_cndmask_b32_e64 v37, v37, 0, s[44:45]
	v_cndmask_b32_e64 v39, 0, v39, s[48:49]
	v_cndmask_b32_e64 v40, v40, 0, s[50:51]
	v_cndmask_b32_e64 v41, v41, 0, s[54:55]
	v_cndmask_b32_e64 v42, v98, v42, s[58:59]
	v_cndmask_b32_e64 v98, v46, 0, s[64:65]
	v_cndmask_b32_e64 v43, 0, v43, s[58:59]
	v_mfma_f32_32x32x16_bf16 v[50:65], v[148:151], v[168:171], v[50:65]
	v_cndmask_b32_e64 v44, v44, 0, s[60:61]
	v_cndmask_b32_e64 v45, v45, 0, s[62:63]
	v_cndmask_b32_e64 v46, v98, v46, s[66:67]
	v_cndmask_b32_e64 v47, 0, v47, s[66:67]
	v_cndmask_b32_e64 v48, v48, 0, s[68:69]
	v_cndmask_b32_e64 v49, v49, 0, s[70:71]
	v_cvt_pk_bf16_f32 v34, v34, v35
	s_waitcnt lgkmcnt(8)
	v_mfma_f32_32x32x16_bf16 v[50:65], v[152:155], v[176:179], v[50:65]
	v_cvt_pk_bf16_f32 v35, v36, v37
	v_cvt_pk_bf16_f32 v36, v38, v39
	v_cvt_pk_bf16_f32 v37, v40, v41
	v_cvt_pk_bf16_f32 v136, v42, v43
	v_cvt_pk_bf16_f32 v137, v44, v45
	v_cvt_pk_bf16_f32 v138, v46, v47
	v_cvt_pk_bf16_f32 v139, v48, v49
	s_nop 4
	v_cvt_pk_bf16_f32 v38, v50, v51
	v_cvt_pk_bf16_f32 v39, v52, v53
	v_cvt_pk_bf16_f32 v40, v54, v55
	v_cvt_pk_bf16_f32 v41, v56, v57
	v_cvt_pk_bf16_f32 v143, v187, v99
	ds_read2_b64 v[42:45], v102 offset0:8 offset1:10
	ds_read2_b64 v[46:49], v102 offset1:2
	ds_read2_b64 v[98:101], v102 offset0:4 offset1:6
	v_cvt_pk_bf16_f32 v144, v58, v59
	v_cvt_pk_bf16_f32 v145, v60, v61
	v_cvt_pk_bf16_f32 v146, v62, v63
	v_cvt_pk_bf16_f32 v147, v64, v65
	s_waitcnt lgkmcnt(1)
	v_mfma_f32_32x32x16_bf16 v[50:65], v[38:41], v[46:49], 0
	v_cvt_pk_bf16_f32 v132, v156, v157
	v_cvt_pk_bf16_f32 v133, v158, v159
	v_cvt_pk_bf16_f32 v134, v164, v165
	v_cvt_pk_bf16_f32 v135, v166, v167
	v_cvt_pk_bf16_f32 v140, v172, v173
	v_cvt_pk_bf16_f32 v141, v174, v175
	v_cvt_pk_bf16_f32 v142, v181, v186
	v_mfma_f32_32x32x16_bf16 v[50:65], v[132:135], v[42:45], v[50:65]
	ds_read2_b64 v[42:45], v102 offset0:12 offset1:14
	v_readlane_b32 s42, v254, 31
	v_readlane_b32 s43, v254, 32
	s_mov_b32 s44, s12
	v_readlane_b32 s54, v254, 12
	v_readlane_b32 s55, v254, 13
	v_cmp_gt_u32_e32 vcc, 32, v130
	v_mfma_f32_32x32x16_bf16 v[114:129], v[34:37], v[46:49], 0
	s_waitcnt lgkmcnt(1)
	v_mfma_f32_32x32x16_bf16 v[50:65], v[144:147], v[98:101], v[50:65]
	v_mfma_f32_32x32x16_bf16 v[114:129], v[136:139], v[98:101], v[114:129]
	s_waitcnt lgkmcnt(0)
	v_mfma_f32_32x32x16_bf16 v[50:65], v[140:143], v[42:45], v[50:65]
	ds_read_b128 v[148:151], v180 offset:18432
	ds_read_b128 v[42:45], v131 offset:23040
	ds_read_b128 v[46:49], v131 offset:23072
	ds_read_b128 v[152:155], v180 offset:9216
	ds_read_b128 v[156:159], v180 offset:9248
	ds_read_b128 v[160:163], v180 offset:18464
	s_waitcnt lgkmcnt(2)
	v_mfma_f32_32x32x16_bf16 v[114:129], v[152:155], v[42:45], v[114:129]
	v_mfma_f32_32x32x16_bf16 v[50:65], v[148:151], v[42:45], v[50:65]
	ds_read_b128 v[42:45], v131 offset:23104
	ds_read_b128 v[164:167], v180 offset:9280
	ds_read_b128 v[168:171], v180 offset:18496
	s_waitcnt lgkmcnt(4)
	v_mfma_f32_32x32x16_bf16 v[114:129], v[156:159], v[46:49], v[114:129]
	s_waitcnt lgkmcnt(3)
	v_mfma_f32_32x32x16_bf16 v[50:65], v[160:163], v[46:49], v[50:65]
	s_waitcnt lgkmcnt(1)
	v_mfma_f32_32x32x16_bf16 v[114:129], v[164:167], v[42:45], v[114:129]
	s_waitcnt lgkmcnt(0)
	v_mfma_f32_32x32x16_bf16 v[50:65], v[168:171], v[42:45], v[50:65]
	ds_read_b128 v[42:45], v131 offset:23136
	ds_read_b128 v[172:175], v180 offset:9312
	ds_read_b128 v[176:179], v180 offset:18528
	v_add_u32_e32 v180, 0x1000, v102
	s_waitcnt lgkmcnt(1)
	v_mfma_f32_32x32x16_bf16 v[114:129], v[172:175], v[42:45], v[114:129]
	s_waitcnt lgkmcnt(0)
	v_mfma_f32_32x32x16_bf16 v[50:65], v[176:179], v[42:45], v[50:65]
	ds_read2_b64 v[42:45], v180 offset0:64 offset1:66
	ds_read2_b64 v[192:195], v180 offset0:72 offset1:74
	s_waitcnt lgkmcnt(1)
	v_mfma_f32_32x32x16_bf16 v[98:113], v[34:37], v[42:45], 0
	v_mfma_f32_32x32x16_bf16 v[34:49], v[38:41], v[42:45], 0
	s_waitcnt lgkmcnt(0)
	v_mfma_f32_32x32x16_bf16 v[34:49], v[132:135], v[192:195], v[34:49]
	ds_read2_b64 v[132:135], v180 offset0:68 offset1:70
	ds_read2_b64 v[192:195], v180 offset0:76 offset1:78
	s_waitcnt lgkmcnt(1)
	v_mfma_f32_32x32x16_bf16 v[34:49], v[144:147], v[132:135], v[34:49]
	v_mfma_f32_32x32x16_bf16 v[98:113], v[136:139], v[132:135], v[98:113]
	ds_read_b128 v[132:135], v131 offset:27648
	s_waitcnt lgkmcnt(1)
	v_mfma_f32_32x32x16_bf16 v[34:49], v[140:143], v[192:195], v[34:49]
	s_waitcnt lgkmcnt(0)
	v_mfma_f32_32x32x16_bf16 v[98:113], v[152:155], v[132:135], v[98:113]
	v_mfma_f32_32x32x16_bf16 v[34:49], v[148:151], v[132:135], v[34:49]
	ds_read_b128 v[132:135], v131 offset:27680
	s_waitcnt lgkmcnt(0)
	v_mfma_f32_32x32x16_bf16 v[98:113], v[156:159], v[132:135], v[98:113]
	v_mfma_f32_32x32x16_bf16 v[34:49], v[160:163], v[132:135], v[34:49]
	ds_read_b128 v[132:135], v131 offset:27712
	s_waitcnt lgkmcnt(0)
	v_mfma_f32_32x32x16_bf16 v[98:113], v[164:167], v[132:135], v[98:113]
	v_mfma_f32_32x32x16_bf16 v[34:49], v[168:171], v[132:135], v[34:49]
	ds_read_b128 v[132:135], v131 offset:27744
	s_waitcnt lgkmcnt(0)
	s_load_dwordx2 s[0:1], s[42:43], 0x40
	v_ashrrev_i32_e32 v131, 3, v130
	v_and_b32_e32 v131, -4, v131
	s_waitcnt lgkmcnt(0)
	v_mfma_f32_32x32x16_bf16 v[98:113], v[172:175], v[132:135], v[98:113]
	v_mfma_f32_32x32x16_bf16 v[34:49], v[176:179], v[132:135], v[34:49]
	v_or_b32_e32 v132, s44, v0
	v_ashrrev_i32_e32 v133, 31, v132
	v_lshl_add_u64 v[132:133], v[132:133], 2, s[0:1]
	v_readlane_b32 s0, v254, 21
	global_load_dword v224, v[132:133], off nt
	global_load_dword v189, v[132:133], off offset:128 nt
	v_add_u32_e32 v132, s76, v131
	v_readlane_b32 s1, v254, 22
	s_add_u32 s0, s0, s9
	s_addc_u32 s1, s1, 0
	v_lshlrev_b32_e32 v0, 1, v0
	v_ashrrev_i32_e32 v133, 31, v132
	v_or_b32_e32 v164, 1, v132
	v_lshl_add_u64 v[134:135], s[0:1], 0, v[0:1]
	v_lshlrev_b64 v[136:137], 9, v[132:133]
	v_ashrrev_i32_e32 v165, 31, v164
	v_or_b32_e32 v162, 2, v132
	v_lshl_add_u64 v[170:171], v[134:135], 0, v[136:137]
	v_lshlrev_b64 v[136:137], 9, v[164:165]
	v_ashrrev_i32_e32 v163, 31, v162
	v_or_b32_e32 v160, 3, v132
	v_lshl_add_u64 v[166:167], v[134:135], 0, v[136:137]
	v_lshlrev_b64 v[136:137], 9, v[162:163]
	v_ashrrev_i32_e32 v161, 31, v160
	v_add_u32_e32 v158, 8, v132
	v_lshl_add_u64 v[168:169], v[134:135], 0, v[136:137]
	v_lshlrev_b64 v[136:137], 9, v[160:161]
	v_ashrrev_i32_e32 v159, 31, v158
	v_add_u32_e32 v156, 9, v132
	v_lshl_add_u64 v[172:173], v[134:135], 0, v[136:137]
	v_lshlrev_b64 v[136:137], 9, v[158:159]
	v_ashrrev_i32_e32 v157, 31, v156
	v_add_u32_e32 v154, 10, v132
	v_lshl_add_u64 v[174:175], v[134:135], 0, v[136:137]
	v_lshlrev_b64 v[136:137], 9, v[156:157]
	v_ashrrev_i32_e32 v155, 31, v154
	v_add_u32_e32 v152, 11, v132
	v_lshl_add_u64 v[176:177], v[134:135], 0, v[136:137]
	v_lshlrev_b64 v[136:137], 9, v[154:155]
	v_ashrrev_i32_e32 v153, 31, v152
	v_add_u32_e32 v150, 16, v132
	v_lshl_add_u64 v[178:179], v[134:135], 0, v[136:137]
	v_lshlrev_b64 v[136:137], 9, v[152:153]
	v_ashrrev_i32_e32 v151, 31, v150
	v_add_u32_e32 v148, 17, v132
	v_lshl_add_u64 v[180:181], v[134:135], 0, v[136:137]
	v_lshlrev_b64 v[136:137], 9, v[150:151]
	v_ashrrev_i32_e32 v149, 31, v148
	v_add_u32_e32 v146, 18, v132
	v_lshl_add_u64 v[192:193], v[134:135], 0, v[136:137]
	v_lshlrev_b64 v[136:137], 9, v[148:149]
	v_ashrrev_i32_e32 v147, 31, v146
	v_add_u32_e32 v144, 19, v132
	v_lshl_add_u64 v[194:195], v[134:135], 0, v[136:137]
	v_lshlrev_b64 v[136:137], 9, v[146:147]
	v_ashrrev_i32_e32 v145, 31, v144
	v_add_u32_e32 v142, 24, v132
	v_lshl_add_u64 v[196:197], v[134:135], 0, v[136:137]
	v_lshlrev_b64 v[136:137], 9, v[144:145]
	v_ashrrev_i32_e32 v143, 31, v142
	v_add_u32_e32 v140, 25, v132
	v_lshl_add_u64 v[198:199], v[134:135], 0, v[136:137]
	v_lshlrev_b64 v[136:137], 9, v[142:143]
	v_ashrrev_i32_e32 v141, 31, v140
	v_add_u32_e32 v138, 26, v132
	v_lshl_add_u64 v[200:201], v[134:135], 0, v[136:137]
	v_lshlrev_b64 v[136:137], 9, v[140:141]
	v_ashrrev_i32_e32 v139, 31, v138
	v_lshl_add_u64 v[202:203], v[134:135], 0, v[136:137]
	v_lshlrev_b64 v[136:137], 9, v[138:139]
	v_lshl_add_u64 v[204:205], v[134:135], 0, v[136:137]
	v_add_u32_e32 v136, 27, v132
	v_ashrrev_i32_e32 v137, 31, v136
	s_add_u32 s0, s54, s9
	v_lshlrev_b64 v[186:187], 9, v[136:137]
	s_addc_u32 s1, s55, 0
	v_lshl_add_u64 v[206:207], v[134:135], 0, v[186:187]
	v_mov_b32_e32 v186, v81
	v_lshl_add_u64 v[130:131], s[0:1], 0, v[0:1]
	v_mov_b32_e32 v0, v97
	v_permlane32_swap_b32_e32 v81, v186
	s_nop 0
	v_permlane32_swap_b32_e32 v97, v0
	v_cndmask_b32_e32 v81, v81, v186, vcc
	v_cndmask_b32_e32 v0, v97, v0, vcc
	v_add_f32_e32 v81, v98, v81
	v_add_f32_e32 v0, v114, v0
	v_mul_f32_e32 v97, v81, v81
	v_fmac_f32_e32 v97, v0, v0
	v_lshlrev_b64 v[164:165], 11, v[164:165]
	v_lshl_add_u64 v[164:165], v[130:131], 0, v[164:165]
	v_add_f32_dpp v97, v97, v97 quad_perm:[1,0,3,2] row_mask:0xf bank_mask:0xf bound_ctrl:1
	v_lshlrev_b64 v[162:163], 11, v[162:163]
	v_lshl_add_u64 v[162:163], v[130:131], 0, v[162:163]
	v_add_f32_dpp v97, v97, v97 quad_perm:[2,3,0,1] row_mask:0xf bank_mask:0xf bound_ctrl:1
	s_add_i32 s6, s6, s13
	s_add_i32 s8, s8, s86
	v_add_f32_dpp v97, v97, v97 row_ror:4 row_mask:0xf bank_mask:0xf bound_ctrl:1
	s_cmpk_lt_i32 s6, 0x400
	s_nop 0
	v_add_f32_dpp v97, v97, v97 row_ror:8 row_mask:0xf bank_mask:0xf bound_ctrl:1
	v_mov_b32_e32 v98, v97
	s_nop 1
	v_permlane16_swap_b32_e32 v97, v98
	v_add_f32_e32 v97, v97, v98
	v_fmamk_f32 v97, v97, 0x3c800000, v208
	v_rsq_f32_e32 v97, v97
	global_load_ushort v98, v[170:171], off
	v_mul_f32_e32 v0, v0, v97
	v_mul_f32_e32 v81, v81, v97
	global_load_ushort v97, v[170:171], off offset:64
	s_waitcnt vmcnt(3)
	v_mul_f32_e32 v0, v224, v0
	s_waitcnt vmcnt(2)
	v_mul_f32_e32 v81, v189, v81
	v_lshlrev_b64 v[170:171], 11, v[132:133]
	v_lshl_add_u64 v[186:187], v[130:131], 0, v[170:171]
	s_waitcnt vmcnt(1)
	v_lshlrev_b32_e32 v98, 16, v98
	v_mul_f32_e32 v0, v0, v98
	v_cvt_pk_bf16_f32 v211, v0, s0
	s_waitcnt vmcnt(0)
	v_lshlrev_b32_e32 v97, 16, v97
	v_mul_f32_e32 v210, v81, v97
	global_load_ushort v228, v[166:167], off
	global_load_ushort v229, v[166:167], off offset:64
	global_load_ushort v230, v[168:169], off
	global_load_ushort v231, v[168:169], off offset:64
	global_load_ushort v232, v[172:173], off
	global_load_ushort v233, v[172:173], off offset:64
	global_load_ushort v234, v[174:175], off
	global_load_ushort v235, v[174:175], off offset:64
	global_load_ushort v227, v[176:177], off
	global_load_ushort v226, v[176:177], off offset:64
	global_load_ushort v225, v[178:179], off
	s_nop 0
	global_load_ushort v178, v[178:179], off offset:64
	s_nop 0
	global_load_ushort v177, v[180:181], off
	global_load_ushort v176, v[180:181], off offset:64
	global_load_ushort v175, v[192:193], off
	global_load_ushort v174, v[192:193], off offset:64
	global_load_ushort v173, v[194:195], off
	global_load_ushort v172, v[194:195], off offset:64
	global_load_ushort v171, v[196:197], off
	global_load_ushort v170, v[196:197], off offset:64
	global_load_ushort v169, v[198:199], off
	global_load_ushort v168, v[198:199], off offset:64
	global_load_ushort v167, v[200:201], off
	global_load_ushort v166, v[200:201], off offset:64
	global_load_ushort v133, v[202:203], off
	global_load_ushort v114, v[202:203], off offset:64
	global_load_ushort v98, v[204:205], off
	global_load_ushort v97, v[204:205], off offset:64
	global_load_ushort v81, v[206:207], off
	global_load_ushort v0, v[206:207], off offset:64
	v_cvt_pk_bf16_f32 v179, v210, s0
	v_mov_b32_e32 v180, v80
	global_store_short v[186:187], v179, off offset:64
	v_mov_b32_e32 v179, v96
	v_permlane32_swap_b32_e32 v80, v180
	s_nop 0
	v_permlane32_swap_b32_e32 v96, v179
	v_cndmask_b32_e32 v80, v80, v180, vcc
	v_cndmask_b32_e32 v96, v96, v179, vcc
	v_add_f32_e32 v80, v99, v80
	v_add_f32_e32 v96, v115, v96
	v_mul_f32_e32 v99, v80, v80
	v_fmac_f32_e32 v99, v96, v96
	global_store_short v[186:187], v211, off
	s_waitcnt vmcnt(2)
	v_lshlrev_b32_e32 v0, 16, v0
	v_add_f32_dpp v99, v99, v99 quad_perm:[1,0,3,2] row_mask:0xf bank_mask:0xf bound_ctrl:1
	s_nop 1
	v_add_f32_dpp v99, v99, v99 quad_perm:[2,3,0,1] row_mask:0xf bank_mask:0xf bound_ctrl:1
	s_nop 1
	v_add_f32_dpp v99, v99, v99 row_ror:4 row_mask:0xf bank_mask:0xf bound_ctrl:1
	s_nop 1
	v_add_f32_dpp v99, v99, v99 row_ror:8 row_mask:0xf bank_mask:0xf bound_ctrl:1
	v_mov_b32_e32 v115, v99
	s_nop 1
	v_permlane16_swap_b32_e32 v99, v115
	v_add_f32_e32 v99, v99, v115
	v_fmamk_f32 v99, v99, 0x3c800000, v208
	v_rsq_f32_e32 v99, v99
	v_lshlrev_b32_e32 v115, 16, v228
	v_mul_f32_e32 v96, v96, v99
	v_mul_f32_e32 v96, v224, v96
	v_mul_f32_e32 v80, v80, v99
	v_mul_f32_e32 v96, v96, v115
	v_mul_f32_e32 v80, v189, v80
	v_lshlrev_b32_e32 v99, 16, v229
	v_mul_f32_e32 v80, v80, v99
	v_cvt_pk_bf16_f32 v96, v96, s0
	global_store_short v[164:165], v96, off
	v_cvt_pk_bf16_f32 v80, v80, s0
	v_mov_b32_e32 v96, v79
	global_store_short v[164:165], v80, off offset:64
	v_mov_b32_e32 v80, v95
	v_permlane32_swap_b32_e32 v79, v96
	s_nop 0
	v_permlane32_swap_b32_e32 v95, v80
	v_cndmask_b32_e32 v79, v79, v96, vcc
	v_cndmask_b32_e32 v80, v95, v80, vcc
	v_add_f32_e32 v79, v100, v79
	v_add_f32_e32 v80, v116, v80
	v_mul_f32_e32 v95, v79, v79
	v_fmac_f32_e32 v95, v80, v80
	s_nop 1
	v_add_f32_dpp v95, v95, v95 quad_perm:[1,0,3,2] row_mask:0xf bank_mask:0xf bound_ctrl:1
	s_nop 1
	v_add_f32_dpp v95, v95, v95 quad_perm:[2,3,0,1] row_mask:0xf bank_mask:0xf bound_ctrl:1
	s_nop 1
	v_add_f32_dpp v95, v95, v95 row_ror:4 row_mask:0xf bank_mask:0xf bound_ctrl:1
	s_nop 1
	v_add_f32_dpp v95, v95, v95 row_ror:8 row_mask:0xf bank_mask:0xf bound_ctrl:1
	v_mov_b32_e32 v96, v95
	s_nop 1
	v_permlane16_swap_b32_e32 v95, v96
	v_add_f32_e32 v95, v95, v96
	v_fmamk_f32 v95, v95, 0x3c800000, v208
	v_rsq_f32_e32 v95, v95
	v_lshlrev_b32_e32 v96, 16, v230
	v_mul_f32_e32 v80, v80, v95
	v_mul_f32_e32 v80, v224, v80
	v_mul_f32_e32 v79, v79, v95
	v_mul_f32_e32 v80, v80, v96
	v_mul_f32_e32 v79, v189, v79
	v_lshlrev_b32_e32 v95, 16, v231
	v_mul_f32_e32 v79, v79, v95
	v_cvt_pk_bf16_f32 v80, v80, s0
	global_store_short v[162:163], v80, off
	v_cvt_pk_bf16_f32 v79, v79, s0
	v_mov_b32_e32 v80, v78
	global_store_short v[162:163], v79, off offset:64
	v_mov_b32_e32 v79, v94
	v_permlane32_swap_b32_e32 v78, v80
	s_nop 0
	v_permlane32_swap_b32_e32 v94, v79
	v_cndmask_b32_e32 v78, v78, v80, vcc
	v_cndmask_b32_e32 v79, v94, v79, vcc
	v_add_f32_e32 v78, v101, v78
	v_add_f32_e32 v79, v117, v79
	v_mul_f32_e32 v80, v78, v78
	v_fmac_f32_e32 v80, v79, v79
	v_add_u32_e32 v96, 32, v132
	s_nop 0
	v_add_f32_dpp v80, v80, v80 quad_perm:[1,0,3,2] row_mask:0xf bank_mask:0xf bound_ctrl:1
	s_nop 1
	v_add_f32_dpp v80, v80, v80 quad_perm:[2,3,0,1] row_mask:0xf bank_mask:0xf bound_ctrl:1
	s_nop 1
	v_add_f32_dpp v80, v80, v80 row_ror:4 row_mask:0xf bank_mask:0xf bound_ctrl:1
	s_nop 1
	v_add_f32_dpp v80, v80, v80 row_ror:8 row_mask:0xf bank_mask:0xf bound_ctrl:1
	v_mov_b32_e32 v94, v80
	s_nop 1
	v_permlane16_swap_b32_e32 v80, v94
	v_add_f32_e32 v80, v80, v94
	v_fmamk_f32 v80, v80, 0x3c800000, v208
	v_rsq_f32_e32 v80, v80
	v_lshlrev_b32_e32 v94, 16, v232
	v_mul_f32_e32 v79, v79, v80
	v_mul_f32_e32 v79, v224, v79
	v_mul_f32_e32 v78, v78, v80
	v_mul_f32_e32 v79, v79, v94
	v_mul_f32_e32 v78, v189, v78
	v_lshlrev_b32_e32 v80, 16, v233
	v_mul_f32_e32 v80, v78, v80
	v_cvt_pk_bf16_f32 v94, v79, s0
	v_lshlrev_b64 v[78:79], 11, v[160:161]
	v_lshl_add_u64 v[78:79], v[130:131], 0, v[78:79]
	v_cvt_pk_bf16_f32 v80, v80, s0
	global_store_short v[78:79], v94, off
	global_store_short v[78:79], v80, off offset:64
	v_mov_b32_e32 v79, v77
	v_mov_b32_e32 v78, v93
	s_nop 0
	v_permlane32_swap_b32_e32 v77, v79
	v_permlane32_swap_b32_e32 v93, v78
	v_cndmask_b32_e32 v77, v77, v79, vcc
	v_cndmask_b32_e32 v78, v93, v78, vcc
	v_add_f32_e32 v77, v102, v77
	v_add_f32_e32 v78, v118, v78
	v_mul_f32_e32 v79, v77, v77
	v_fmac_f32_e32 v79, v78, v78
	v_add_u32_e32 v94, 33, v132
	v_ashrrev_i32_e32 v95, 31, v94
	v_add_f32_dpp v79, v79, v79 quad_perm:[1,0,3,2] row_mask:0xf bank_mask:0xf bound_ctrl:1
	s_nop 1
	v_add_f32_dpp v79, v79, v79 quad_perm:[2,3,0,1] row_mask:0xf bank_mask:0xf bound_ctrl:1
	s_nop 1
	v_add_f32_dpp v79, v79, v79 row_ror:4 row_mask:0xf bank_mask:0xf bound_ctrl:1
	s_nop 1
	v_add_f32_dpp v79, v79, v79 row_ror:8 row_mask:0xf bank_mask:0xf bound_ctrl:1
	v_mov_b32_e32 v80, v79
	s_nop 1
	v_permlane16_swap_b32_e32 v79, v80
	v_add_f32_e32 v79, v79, v80
	v_fmamk_f32 v79, v79, 0x3c800000, v208
	v_rsq_f32_e32 v79, v79
	v_lshlrev_b32_e32 v80, 16, v234
	v_mul_f32_e32 v78, v78, v79
	v_mul_f32_e32 v78, v224, v78
	v_mul_f32_e32 v77, v77, v79
	v_mul_f32_e32 v78, v78, v80
	v_mul_f32_e32 v77, v189, v77
	v_lshlrev_b32_e32 v79, 16, v235
	v_mul_f32_e32 v77, v77, v79
	v_cvt_pk_bf16_f32 v80, v78, s0
	v_lshlrev_b64 v[78:79], 11, v[158:159]
	v_lshl_add_u64 v[78:79], v[130:131], 0, v[78:79]
	v_cvt_pk_bf16_f32 v77, v77, s0
	global_store_short v[78:79], v80, off
	global_store_short v[78:79], v77, off offset:64
	v_mov_b32_e32 v78, v76
	v_mov_b32_e32 v77, v92
	s_nop 0
	v_permlane32_swap_b32_e32 v76, v78
	v_permlane32_swap_b32_e32 v92, v77
	v_cndmask_b32_e32 v76, v76, v78, vcc
	v_cndmask_b32_e32 v77, v92, v77, vcc
	v_add_f32_e32 v76, v103, v76
	v_add_f32_e32 v77, v119, v77
	v_mul_f32_e32 v78, v76, v76
	v_fmac_f32_e32 v78, v77, v77
	v_add_u32_e32 v92, 34, v132
	v_ashrrev_i32_e32 v93, 31, v92
	v_add_f32_dpp v78, v78, v78 quad_perm:[1,0,3,2] row_mask:0xf bank_mask:0xf bound_ctrl:1
	v_add_u32_e32 v80, 48, v132
	s_nop 0
	v_add_f32_dpp v78, v78, v78 quad_perm:[2,3,0,1] row_mask:0xf bank_mask:0xf bound_ctrl:1
	s_nop 1
	v_add_f32_dpp v78, v78, v78 row_ror:4 row_mask:0xf bank_mask:0xf bound_ctrl:1
	s_nop 1
	v_add_f32_dpp v78, v78, v78 row_ror:8 row_mask:0xf bank_mask:0xf bound_ctrl:1
	v_mov_b32_e32 v79, v78
	s_nop 1
	v_permlane16_swap_b32_e32 v78, v79
	v_add_f32_e32 v78, v78, v79
	v_fmamk_f32 v78, v78, 0x3c800000, v208
	v_rsq_f32_e32 v78, v78
	v_lshlrev_b32_e32 v79, 16, v227
	v_mul_f32_e32 v77, v77, v78
	v_mul_f32_e32 v77, v224, v77
	v_mul_f32_e32 v76, v76, v78
	v_mul_f32_e32 v77, v77, v79
	v_mul_f32_e32 v76, v189, v76
	v_lshlrev_b32_e32 v78, 16, v226
	v_mul_f32_e32 v78, v76, v78
	v_cvt_pk_bf16_f32 v79, v77, s0
	v_lshlrev_b64 v[76:77], 11, v[156:157]
	v_lshl_add_u64 v[76:77], v[130:131], 0, v[76:77]
	v_cvt_pk_bf16_f32 v78, v78, s0
	global_store_short v[76:77], v79, off
	global_store_short v[76:77], v78, off offset:64
	v_mov_b32_e32 v77, v75
	v_mov_b32_e32 v76, v91
	s_nop 0
	v_permlane32_swap_b32_e32 v75, v77
	v_permlane32_swap_b32_e32 v91, v76
	v_cndmask_b32_e32 v75, v75, v77, vcc
	v_cndmask_b32_e32 v76, v91, v76, vcc
	v_add_f32_e32 v75, v104, v75
	v_add_f32_e32 v76, v120, v76
	v_mul_f32_e32 v77, v75, v75
	v_fmac_f32_e32 v77, v76, v76
	s_nop 1
	v_add_f32_dpp v77, v77, v77 quad_perm:[1,0,3,2] row_mask:0xf bank_mask:0xf bound_ctrl:1
	s_nop 1
	v_add_f32_dpp v77, v77, v77 quad_perm:[2,3,0,1] row_mask:0xf bank_mask:0xf bound_ctrl:1
	s_nop 1
	v_add_f32_dpp v77, v77, v77 row_ror:4 row_mask:0xf bank_mask:0xf bound_ctrl:1
	s_nop 1
	v_add_f32_dpp v77, v77, v77 row_ror:8 row_mask:0xf bank_mask:0xf bound_ctrl:1
	v_mov_b32_e32 v78, v77
	s_nop 1
	v_permlane16_swap_b32_e32 v77, v78
	v_add_f32_e32 v77, v77, v78
	v_fmamk_f32 v77, v77, 0x3c800000, v208
	v_rsq_f32_e32 v77, v77
	v_lshlrev_b32_e32 v78, 16, v225
	v_mul_f32_e32 v76, v76, v77
	v_mul_f32_e32 v76, v224, v76
	v_mul_f32_e32 v75, v75, v77
	v_mul_f32_e32 v76, v76, v78
	v_mul_f32_e32 v75, v189, v75
	v_lshlrev_b32_e32 v77, 16, v178
	v_mul_f32_e32 v75, v75, v77
	v_cvt_pk_bf16_f32 v78, v76, s0
	v_lshlrev_b64 v[76:77], 11, v[154:155]
	v_lshl_add_u64 v[76:77], v[130:131], 0, v[76:77]
	v_cvt_pk_bf16_f32 v75, v75, s0
	global_store_short v[76:77], v78, off
	global_store_short v[76:77], v75, off offset:64
	v_mov_b32_e32 v76, v74
	v_mov_b32_e32 v75, v90
	s_nop 0
	v_permlane32_swap_b32_e32 v74, v76
	v_permlane32_swap_b32_e32 v90, v75
	v_cndmask_b32_e32 v74, v74, v76, vcc
	v_cndmask_b32_e32 v75, v90, v75, vcc
	v_add_f32_e32 v74, v105, v74
	v_add_f32_e32 v75, v121, v75
	v_mul_f32_e32 v76, v74, v74
	v_fmac_f32_e32 v76, v75, v75
	v_add_u32_e32 v90, 35, v132
	v_ashrrev_i32_e32 v91, 31, v90
	v_add_f32_dpp v76, v76, v76 quad_perm:[1,0,3,2] row_mask:0xf bank_mask:0xf bound_ctrl:1
	v_add_u32_e32 v78, 49, v132
	v_ashrrev_i32_e32 v79, 31, v78
	v_add_f32_dpp v76, v76, v76 quad_perm:[2,3,0,1] row_mask:0xf bank_mask:0xf bound_ctrl:1
	s_nop 1
	v_add_f32_dpp v76, v76, v76 row_ror:4 row_mask:0xf bank_mask:0xf bound_ctrl:1
	s_nop 1
	v_add_f32_dpp v76, v76, v76 row_ror:8 row_mask:0xf bank_mask:0xf bound_ctrl:1
	v_mov_b32_e32 v77, v76
	s_nop 1
	v_permlane16_swap_b32_e32 v76, v77
	v_add_f32_e32 v76, v76, v77
	v_fmamk_f32 v76, v76, 0x3c800000, v208
	v_rsq_f32_e32 v76, v76
	v_lshlrev_b32_e32 v77, 16, v177
	v_mul_f32_e32 v75, v75, v76
	v_mul_f32_e32 v75, v224, v75
	v_mul_f32_e32 v74, v74, v76
	v_mul_f32_e32 v75, v75, v77
	v_mul_f32_e32 v74, v189, v74
	v_lshlrev_b32_e32 v76, 16, v176
	v_mul_f32_e32 v76, v74, v76
	v_cvt_pk_bf16_f32 v77, v75, s0
	v_lshlrev_b64 v[74:75], 11, v[152:153]
	v_lshl_add_u64 v[74:75], v[130:131], 0, v[74:75]
	v_cvt_pk_bf16_f32 v76, v76, s0
	global_store_short v[74:75], v77, off
	global_store_short v[74:75], v76, off offset:64
	v_mov_b32_e32 v75, v73
	v_mov_b32_e32 v74, v89
	s_nop 0
	v_permlane32_swap_b32_e32 v73, v75
	v_permlane32_swap_b32_e32 v89, v74
	v_cndmask_b32_e32 v73, v73, v75, vcc
	v_cndmask_b32_e32 v74, v89, v74, vcc
	v_add_f32_e32 v73, v106, v73
	v_add_f32_e32 v74, v122, v74
	v_mul_f32_e32 v75, v73, v73
	v_fmac_f32_e32 v75, v74, v74
	s_nop 1
	v_add_f32_dpp v75, v75, v75 quad_perm:[1,0,3,2] row_mask:0xf bank_mask:0xf bound_ctrl:1
	s_nop 1
	v_add_f32_dpp v75, v75, v75 quad_perm:[2,3,0,1] row_mask:0xf bank_mask:0xf bound_ctrl:1
	s_nop 1
	v_add_f32_dpp v75, v75, v75 row_ror:4 row_mask:0xf bank_mask:0xf bound_ctrl:1
	s_nop 1
	v_add_f32_dpp v75, v75, v75 row_ror:8 row_mask:0xf bank_mask:0xf bound_ctrl:1
	v_mov_b32_e32 v76, v75
	s_nop 1
	v_permlane16_swap_b32_e32 v75, v76
	v_add_f32_e32 v75, v75, v76
	v_fmamk_f32 v75, v75, 0x3c800000, v208
	v_rsq_f32_e32 v75, v75
	v_lshlrev_b32_e32 v76, 16, v175
	v_mul_f32_e32 v74, v74, v75
	v_mul_f32_e32 v74, v224, v74
	v_mul_f32_e32 v73, v73, v75
	v_mul_f32_e32 v74, v74, v76
	v_mul_f32_e32 v73, v189, v73
	v_lshlrev_b32_e32 v75, 16, v174
	v_mul_f32_e32 v73, v73, v75
	v_cvt_pk_bf16_f32 v76, v74, s0
	v_lshlrev_b64 v[74:75], 11, v[150:151]
	v_lshl_add_u64 v[74:75], v[130:131], 0, v[74:75]
	v_cvt_pk_bf16_f32 v73, v73, s0
	global_store_short v[74:75], v76, off
	global_store_short v[74:75], v73, off offset:64
	v_mov_b32_e32 v74, v72
	v_mov_b32_e32 v73, v88
	s_nop 0
	v_permlane32_swap_b32_e32 v72, v74
	v_permlane32_swap_b32_e32 v88, v73
	v_cndmask_b32_e32 v72, v72, v74, vcc
	v_cndmask_b32_e32 v73, v88, v73, vcc
	v_add_f32_e32 v72, v107, v72
	v_add_f32_e32 v73, v123, v73
	v_mul_f32_e32 v74, v72, v72
	v_fmac_f32_e32 v74, v73, v73
	v_add_u32_e32 v88, 40, v132
	v_ashrrev_i32_e32 v89, 31, v88
	v_add_f32_dpp v74, v74, v74 quad_perm:[1,0,3,2] row_mask:0xf bank_mask:0xf bound_ctrl:1
	v_add_u32_e32 v76, 50, v132
	v_ashrrev_i32_e32 v77, 31, v76
	v_add_f32_dpp v74, v74, v74 quad_perm:[2,3,0,1] row_mask:0xf bank_mask:0xf bound_ctrl:1
	s_nop 1
	v_add_f32_dpp v74, v74, v74 row_ror:4 row_mask:0xf bank_mask:0xf bound_ctrl:1
	s_nop 1
	v_add_f32_dpp v74, v74, v74 row_ror:8 row_mask:0xf bank_mask:0xf bound_ctrl:1
	v_mov_b32_e32 v75, v74
	s_nop 1
	v_permlane16_swap_b32_e32 v74, v75
	v_add_f32_e32 v74, v74, v75
	v_fmamk_f32 v74, v74, 0x3c800000, v208
	v_rsq_f32_e32 v74, v74
	v_lshlrev_b32_e32 v75, 16, v173
	v_mul_f32_e32 v73, v73, v74
	v_mul_f32_e32 v73, v224, v73
	v_mul_f32_e32 v72, v72, v74
	v_mul_f32_e32 v73, v73, v75
	v_mul_f32_e32 v72, v189, v72
	v_lshlrev_b32_e32 v74, 16, v172
	v_mul_f32_e32 v74, v72, v74
	v_cvt_pk_bf16_f32 v75, v73, s0
	v_lshlrev_b64 v[72:73], 11, v[148:149]
	v_lshl_add_u64 v[72:73], v[130:131], 0, v[72:73]
	v_cvt_pk_bf16_f32 v74, v74, s0
	global_store_short v[72:73], v75, off
	global_store_short v[72:73], v74, off offset:64
	v_mov_b32_e32 v73, v71
	v_mov_b32_e32 v72, v87
	s_nop 0
	v_permlane32_swap_b32_e32 v71, v73
	v_permlane32_swap_b32_e32 v87, v72
	v_cndmask_b32_e32 v71, v71, v73, vcc
	v_cndmask_b32_e32 v72, v87, v72, vcc
	v_add_f32_e32 v71, v108, v71
	v_add_f32_e32 v72, v124, v72
	v_mul_f32_e32 v73, v71, v71
	v_fmac_f32_e32 v73, v72, v72
	s_nop 1
	v_add_f32_dpp v73, v73, v73 quad_perm:[1,0,3,2] row_mask:0xf bank_mask:0xf bound_ctrl:1
	s_nop 1
	v_add_f32_dpp v73, v73, v73 quad_perm:[2,3,0,1] row_mask:0xf bank_mask:0xf bound_ctrl:1
	s_nop 1
	v_add_f32_dpp v73, v73, v73 row_ror:4 row_mask:0xf bank_mask:0xf bound_ctrl:1
	s_nop 1
	v_add_f32_dpp v73, v73, v73 row_ror:8 row_mask:0xf bank_mask:0xf bound_ctrl:1
	v_mov_b32_e32 v74, v73
	s_nop 1
	v_permlane16_swap_b32_e32 v73, v74
	v_add_f32_e32 v73, v73, v74
	v_fmamk_f32 v73, v73, 0x3c800000, v208
	v_rsq_f32_e32 v73, v73
	v_lshlrev_b32_e32 v74, 16, v171
	v_mul_f32_e32 v72, v72, v73
	v_mul_f32_e32 v72, v224, v72
	v_mul_f32_e32 v71, v71, v73
	v_mul_f32_e32 v72, v72, v74
	v_mul_f32_e32 v71, v189, v71
	v_lshlrev_b32_e32 v73, 16, v170
	v_mul_f32_e32 v71, v71, v73
	v_cvt_pk_bf16_f32 v74, v72, s0
	v_lshlrev_b64 v[72:73], 11, v[146:147]
	v_lshl_add_u64 v[72:73], v[130:131], 0, v[72:73]
	v_cvt_pk_bf16_f32 v71, v71, s0
	global_store_short v[72:73], v74, off
	global_store_short v[72:73], v71, off offset:64
	v_mov_b32_e32 v72, v70
	v_mov_b32_e32 v71, v86
	s_nop 0
	v_permlane32_swap_b32_e32 v70, v72
	v_permlane32_swap_b32_e32 v86, v71
	v_cndmask_b32_e32 v70, v70, v72, vcc
	v_cndmask_b32_e32 v71, v86, v71, vcc
	v_add_f32_e32 v70, v109, v70
	v_add_f32_e32 v71, v125, v71
	v_mul_f32_e32 v72, v70, v70
	v_fmac_f32_e32 v72, v71, v71
	v_add_u32_e32 v86, 41, v132
	v_ashrrev_i32_e32 v87, 31, v86
	v_add_f32_dpp v72, v72, v72 quad_perm:[1,0,3,2] row_mask:0xf bank_mask:0xf bound_ctrl:1
	v_add_u32_e32 v74, 51, v132
	v_ashrrev_i32_e32 v75, 31, v74
	v_add_f32_dpp v72, v72, v72 quad_perm:[2,3,0,1] row_mask:0xf bank_mask:0xf bound_ctrl:1
	s_nop 1
	v_add_f32_dpp v72, v72, v72 row_ror:4 row_mask:0xf bank_mask:0xf bound_ctrl:1
	s_nop 1
	v_add_f32_dpp v72, v72, v72 row_ror:8 row_mask:0xf bank_mask:0xf bound_ctrl:1
	v_mov_b32_e32 v73, v72
	s_nop 1
	v_permlane16_swap_b32_e32 v72, v73
	v_add_f32_e32 v72, v72, v73
	v_fmamk_f32 v72, v72, 0x3c800000, v208
	v_rsq_f32_e32 v72, v72
	v_lshlrev_b32_e32 v73, 16, v169
	v_mul_f32_e32 v71, v71, v72
	v_mul_f32_e32 v71, v224, v71
	v_mul_f32_e32 v70, v70, v72
	v_mul_f32_e32 v71, v71, v73
	v_mul_f32_e32 v70, v189, v70
	v_lshlrev_b32_e32 v72, 16, v168
	v_mul_f32_e32 v72, v70, v72
	v_cvt_pk_bf16_f32 v73, v71, s0
	v_lshlrev_b64 v[70:71], 11, v[144:145]
	v_lshl_add_u64 v[70:71], v[130:131], 0, v[70:71]
	v_cvt_pk_bf16_f32 v72, v72, s0
	global_store_short v[70:71], v73, off
	global_store_short v[70:71], v72, off offset:64
	v_mov_b32_e32 v71, v69
	v_mov_b32_e32 v70, v85
	s_nop 0
	v_permlane32_swap_b32_e32 v69, v71
	v_permlane32_swap_b32_e32 v85, v70
	v_cndmask_b32_e32 v69, v69, v71, vcc
	v_cndmask_b32_e32 v70, v85, v70, vcc
	v_add_f32_e32 v69, v110, v69
	v_add_f32_e32 v70, v126, v70
	v_mul_f32_e32 v71, v69, v69
	v_fmac_f32_e32 v71, v70, v70
	s_nop 1
	v_add_f32_dpp v71, v71, v71 quad_perm:[1,0,3,2] row_mask:0xf bank_mask:0xf bound_ctrl:1
	s_nop 1
	v_add_f32_dpp v71, v71, v71 quad_perm:[2,3,0,1] row_mask:0xf bank_mask:0xf bound_ctrl:1
	s_nop 1
	v_add_f32_dpp v71, v71, v71 row_ror:4 row_mask:0xf bank_mask:0xf bound_ctrl:1
	s_nop 1
	v_add_f32_dpp v71, v71, v71 row_ror:8 row_mask:0xf bank_mask:0xf bound_ctrl:1
	v_mov_b32_e32 v72, v71
	s_nop 1
	v_permlane16_swap_b32_e32 v71, v72
	v_add_f32_e32 v71, v71, v72
	v_fmamk_f32 v71, v71, 0x3c800000, v208
	v_rsq_f32_e32 v71, v71
	v_lshlrev_b32_e32 v72, 16, v167
	v_mul_f32_e32 v70, v70, v71
	v_mul_f32_e32 v70, v224, v70
	v_mul_f32_e32 v69, v69, v71
	v_mul_f32_e32 v70, v70, v72
	v_mul_f32_e32 v69, v189, v69
	v_lshlrev_b32_e32 v71, 16, v166
	v_mul_f32_e32 v69, v69, v71
	v_cvt_pk_bf16_f32 v72, v70, s0
	v_lshlrev_b64 v[70:71], 11, v[142:143]
	v_lshl_add_u64 v[70:71], v[130:131], 0, v[70:71]
	v_cvt_pk_bf16_f32 v69, v69, s0
	global_store_short v[70:71], v72, off
	global_store_short v[70:71], v69, off offset:64
	v_mov_b32_e32 v70, v68
	v_mov_b32_e32 v69, v84
	s_nop 0
	v_permlane32_swap_b32_e32 v68, v70
	v_permlane32_swap_b32_e32 v84, v69
	v_cndmask_b32_e32 v68, v68, v70, vcc
	v_cndmask_b32_e32 v69, v84, v69, vcc
	v_add_f32_e32 v68, v111, v68
	v_add_f32_e32 v69, v127, v69
	v_mul_f32_e32 v70, v68, v68
	v_fmac_f32_e32 v70, v69, v69
	v_add_u32_e32 v84, 42, v132
	v_ashrrev_i32_e32 v85, 31, v84
	v_add_f32_dpp v70, v70, v70 quad_perm:[1,0,3,2] row_mask:0xf bank_mask:0xf bound_ctrl:1
	v_add_u32_e32 v72, 56, v132
	v_ashrrev_i32_e32 v73, 31, v72
	v_add_f32_dpp v70, v70, v70 quad_perm:[2,3,0,1] row_mask:0xf bank_mask:0xf bound_ctrl:1
	s_nop 1
	v_add_f32_dpp v70, v70, v70 row_ror:4 row_mask:0xf bank_mask:0xf bound_ctrl:1
	s_nop 1
	v_add_f32_dpp v70, v70, v70 row_ror:8 row_mask:0xf bank_mask:0xf bound_ctrl:1
	v_mov_b32_e32 v71, v70
	s_nop 1
	v_permlane16_swap_b32_e32 v70, v71
	v_add_f32_e32 v70, v70, v71
	v_fmamk_f32 v70, v70, 0x3c800000, v208
	v_rsq_f32_e32 v70, v70
	v_lshlrev_b32_e32 v71, 16, v133
	v_mul_f32_e32 v69, v69, v70
	v_mul_f32_e32 v69, v224, v69
	v_mul_f32_e32 v68, v68, v70
	v_mul_f32_e32 v69, v69, v71
	v_mul_f32_e32 v68, v189, v68
	v_lshlrev_b32_e32 v70, 16, v114
	v_mul_f32_e32 v70, v68, v70
	v_cvt_pk_bf16_f32 v71, v69, s0
	v_lshlrev_b64 v[68:69], 11, v[140:141]
	v_lshl_add_u64 v[68:69], v[130:131], 0, v[68:69]
	v_cvt_pk_bf16_f32 v70, v70, s0
	global_store_short v[68:69], v71, off
	global_store_short v[68:69], v70, off offset:64
	v_mov_b32_e32 v69, v67
	v_mov_b32_e32 v68, v83
	s_nop 0
	v_permlane32_swap_b32_e32 v67, v69
	v_permlane32_swap_b32_e32 v83, v68
	v_cndmask_b32_e32 v67, v67, v69, vcc
	v_cndmask_b32_e32 v68, v83, v68, vcc
	v_add_f32_e32 v67, v112, v67
	v_add_f32_e32 v68, v128, v68
	v_mul_f32_e32 v69, v67, v67
	v_fmac_f32_e32 v69, v68, v68
	s_nop 1
	v_add_f32_dpp v69, v69, v69 quad_perm:[1,0,3,2] row_mask:0xf bank_mask:0xf bound_ctrl:1
	s_nop 1
	v_add_f32_dpp v69, v69, v69 quad_perm:[2,3,0,1] row_mask:0xf bank_mask:0xf bound_ctrl:1
	s_nop 1
	v_add_f32_dpp v69, v69, v69 row_ror:4 row_mask:0xf bank_mask:0xf bound_ctrl:1
	s_nop 1
	v_add_f32_dpp v69, v69, v69 row_ror:8 row_mask:0xf bank_mask:0xf bound_ctrl:1
	v_mov_b32_e32 v70, v69
	s_nop 1
	v_permlane16_swap_b32_e32 v69, v70
	v_add_f32_e32 v69, v69, v70
	v_fmamk_f32 v69, v69, 0x3c800000, v208
	v_rsq_f32_e32 v69, v69
	v_lshlrev_b32_e32 v70, 16, v98
	v_mul_f32_e32 v68, v68, v69
	v_mul_f32_e32 v68, v224, v68
	v_mul_f32_e32 v67, v67, v69
	v_mul_f32_e32 v68, v68, v70
	v_mul_f32_e32 v67, v189, v67
	v_lshlrev_b32_e32 v69, 16, v97
	v_mul_f32_e32 v67, v67, v69
	v_cvt_pk_bf16_f32 v70, v68, s0
	v_lshlrev_b64 v[68:69], 11, v[138:139]
	v_lshl_add_u64 v[68:69], v[130:131], 0, v[68:69]
	v_cvt_pk_bf16_f32 v67, v67, s0
	global_store_short v[68:69], v70, off
	global_store_short v[68:69], v67, off offset:64
	v_mov_b32_e32 v68, v66
	v_mov_b32_e32 v67, v82
	s_nop 0
	v_permlane32_swap_b32_e32 v66, v68
	v_permlane32_swap_b32_e32 v82, v67
	v_cndmask_b32_e32 v66, v66, v68, vcc
	v_cndmask_b32_e32 v67, v82, v67, vcc
	v_add_f32_e32 v66, v113, v66
	v_add_f32_e32 v67, v129, v67
	v_mul_f32_e32 v68, v66, v66
	v_fmac_f32_e32 v68, v67, v67
	v_ashrrev_i32_e32 v97, 31, v96
	v_add_u32_e32 v82, 43, v132
	v_add_f32_dpp v68, v68, v68 quad_perm:[1,0,3,2] row_mask:0xf bank_mask:0xf bound_ctrl:1
	v_ashrrev_i32_e32 v83, 31, v82
	v_add_u32_e32 v70, 57, v132
	v_add_f32_dpp v68, v68, v68 quad_perm:[2,3,0,1] row_mask:0xf bank_mask:0xf bound_ctrl:1
	v_ashrrev_i32_e32 v71, 31, v70
	s_nop 0
	v_add_f32_dpp v68, v68, v68 row_ror:4 row_mask:0xf bank_mask:0xf bound_ctrl:1
	s_nop 1
	v_add_f32_dpp v68, v68, v68 row_ror:8 row_mask:0xf bank_mask:0xf bound_ctrl:1
	v_mov_b32_e32 v69, v68
	s_nop 1
	v_permlane16_swap_b32_e32 v68, v69
	v_add_f32_e32 v68, v68, v69
	v_fmamk_f32 v68, v68, 0x3c800000, v208
	v_rsq_f32_e32 v68, v68
	v_lshlrev_b32_e32 v69, 16, v81
	v_ashrrev_i32_e32 v81, 31, v80
	v_mul_f32_e32 v67, v67, v68
	v_mul_f32_e32 v67, v224, v67
	v_mul_f32_e32 v66, v66, v68
	v_mul_f32_e32 v67, v67, v69
	v_mul_f32_e32 v66, v189, v66
	v_mul_f32_e32 v0, v66, v0
	v_cvt_pk_bf16_f32 v68, v67, s0
	v_lshlrev_b64 v[66:67], 11, v[136:137]
	v_lshl_add_u64 v[66:67], v[130:131], 0, v[66:67]
	v_cvt_pk_bf16_f32 v0, v0, s0
	global_store_short v[66:67], v68, off
	global_store_short v[66:67], v0, off offset:64
	v_lshlrev_b64 v[66:67], 9, v[96:97]
	v_lshl_add_u64 v[102:103], v[134:135], 0, v[66:67]
	v_lshlrev_b64 v[66:67], 9, v[94:95]
	v_lshl_add_u64 v[98:99], v[134:135], 0, v[66:67]
	v_lshlrev_b64 v[66:67], 9, v[92:93]
	v_lshl_add_u64 v[100:101], v[134:135], 0, v[66:67]
	v_lshlrev_b64 v[66:67], 9, v[90:91]
	v_lshl_add_u64 v[104:105], v[134:135], 0, v[66:67]
	v_lshlrev_b64 v[66:67], 9, v[88:89]
	v_lshl_add_u64 v[106:107], v[134:135], 0, v[66:67]
	v_lshlrev_b64 v[66:67], 9, v[86:87]
	v_lshl_add_u64 v[108:109], v[134:135], 0, v[66:67]
	v_lshlrev_b64 v[66:67], 9, v[84:85]
	v_lshl_add_u64 v[110:111], v[134:135], 0, v[66:67]
	v_lshlrev_b64 v[66:67], 9, v[82:83]
	v_lshl_add_u64 v[112:113], v[134:135], 0, v[66:67]
	v_lshlrev_b64 v[66:67], 9, v[80:81]
	v_lshl_add_u64 v[114:115], v[134:135], 0, v[66:67]
	v_lshlrev_b64 v[66:67], 9, v[78:79]
	v_lshl_add_u64 v[116:117], v[134:135], 0, v[66:67]
	v_lshlrev_b64 v[66:67], 9, v[76:77]
	v_lshl_add_u64 v[118:119], v[134:135], 0, v[66:67]
	v_lshlrev_b64 v[66:67], 9, v[74:75]
	v_lshl_add_u64 v[120:121], v[134:135], 0, v[66:67]
	v_lshlrev_b64 v[66:67], 9, v[72:73]
	v_add_u32_e32 v68, 58, v132
	v_lshl_add_u64 v[122:123], v[134:135], 0, v[66:67]
	v_lshlrev_b64 v[66:67], 9, v[70:71]
	v_ashrrev_i32_e32 v69, 31, v68
	v_lshl_add_u64 v[124:125], v[134:135], 0, v[66:67]
	v_lshlrev_b64 v[66:67], 9, v[68:69]
	v_lshl_add_u64 v[126:127], v[134:135], 0, v[66:67]
	v_add_u32_e32 v66, 59, v132
	v_mov_b32_e32 v132, v17
	v_mov_b32_e32 v0, v33
	s_nop 0
	v_permlane32_swap_b32_e32 v17, v132
	v_permlane32_swap_b32_e32 v33, v0
	v_cndmask_b32_e32 v17, v17, v132, vcc
	v_cndmask_b32_e32 v0, v33, v0, vcc
	v_add_f32_e32 v17, v34, v17
	v_add_f32_e32 v0, v50, v0
	v_mul_f32_e32 v33, v17, v17
	v_fmac_f32_e32 v33, v0, v0
	v_ashrrev_i32_e32 v67, 31, v66
	v_lshlrev_b64 v[128:129], 9, v[66:67]
	v_add_f32_dpp v33, v33, v33 quad_perm:[1,0,3,2] row_mask:0xf bank_mask:0xf bound_ctrl:1
	v_lshlrev_b64 v[96:97], 11, v[96:97]
	v_lshl_add_u64 v[128:129], v[134:135], 0, v[128:129]
	v_add_f32_dpp v33, v33, v33 quad_perm:[2,3,0,1] row_mask:0xf bank_mask:0xf bound_ctrl:1
	v_lshl_add_u64 v[140:141], v[130:131], 0, v[96:97]
	v_lshlrev_b64 v[94:95], 11, v[94:95]
	v_add_f32_dpp v33, v33, v33 row_ror:4 row_mask:0xf bank_mask:0xf bound_ctrl:1
	v_lshl_add_u64 v[94:95], v[130:131], 0, v[94:95]
	v_lshlrev_b64 v[92:93], 11, v[92:93]
	v_add_f32_dpp v33, v33, v33 row_ror:8 row_mask:0xf bank_mask:0xf bound_ctrl:1
	v_mov_b32_e32 v34, v33
	s_nop 1
	v_permlane16_swap_b32_e32 v33, v34
	v_add_f32_e32 v33, v33, v34
	v_fmamk_f32 v33, v33, 0x3c800000, v208
	v_rsq_f32_e32 v33, v33
	global_load_ushort v34, v[102:103], off
	v_lshl_add_u64 v[92:93], v[130:131], 0, v[92:93]
	v_mul_f32_e32 v0, v0, v33
	v_mul_f32_e32 v17, v17, v33
	global_load_ushort v33, v[102:103], off offset:64
	v_mul_f32_e32 v0, v224, v0
	v_mul_f32_e32 v17, v189, v17
	s_waitcnt vmcnt(1)
	v_lshlrev_b32_e32 v34, 16, v34
	v_mul_f32_e32 v0, v0, v34
	v_cvt_pk_bf16_f32 v142, v0, s0
	s_waitcnt vmcnt(0)
	v_lshlrev_b32_e32 v33, 16, v33
	v_mul_f32_e32 v139, v17, v33
	global_load_ushort v143, v[98:99], off
	global_load_ushort v144, v[98:99], off offset:64
	global_load_ushort v145, v[100:101], off
	global_load_ushort v146, v[100:101], off offset:64
	global_load_ushort v138, v[104:105], off
	global_load_ushort v137, v[104:105], off offset:64
	global_load_ushort v136, v[106:107], off
	global_load_ushort v135, v[106:107], off offset:64
	global_load_ushort v134, v[108:109], off
	global_load_ushort v133, v[108:109], off offset:64
	global_load_ushort v132, v[110:111], off
	s_nop 0
	global_load_ushort v109, v[110:111], off offset:64
	global_load_ushort v108, v[112:113], off
	global_load_ushort v107, v[112:113], off offset:64
	global_load_ushort v106, v[114:115], off
	global_load_ushort v105, v[114:115], off offset:64
	global_load_ushort v104, v[116:117], off
	global_load_ushort v103, v[116:117], off offset:64
	global_load_ushort v102, v[118:119], off
	global_load_ushort v101, v[118:119], off offset:64
	global_load_ushort v100, v[120:121], off
	global_load_ushort v99, v[120:121], off offset:64
	global_load_ushort v98, v[122:123], off
	global_load_ushort v97, v[122:123], off offset:64
	global_load_ushort v96, v[124:125], off
	global_load_ushort v50, v[124:125], off offset:64
	global_load_ushort v34, v[126:127], off
	global_load_ushort v33, v[126:127], off offset:64
	global_load_ushort v17, v[128:129], off
	global_load_ushort v0, v[128:129], off offset:64
	v_cvt_pk_bf16_f32 v110, v139, s0
	v_mov_b32_e32 v111, v16
	global_store_short v[140:141], v110, off offset:64
	v_mov_b32_e32 v110, v32
	v_permlane32_swap_b32_e32 v16, v111
	s_nop 0
	v_permlane32_swap_b32_e32 v32, v110
	v_cndmask_b32_e32 v16, v16, v111, vcc
	v_cndmask_b32_e32 v32, v32, v110, vcc
	v_add_f32_e32 v16, v35, v16
	v_add_f32_e32 v32, v51, v32
	v_mul_f32_e32 v35, v16, v16
	v_fmac_f32_e32 v35, v32, v32
	global_store_short v[140:141], v142, off
	s_waitcnt vmcnt(2)
	v_lshlrev_b32_e32 v0, 16, v0
	v_add_f32_dpp v35, v35, v35 quad_perm:[1,0,3,2] row_mask:0xf bank_mask:0xf bound_ctrl:1
	s_nop 1
	v_add_f32_dpp v35, v35, v35 quad_perm:[2,3,0,1] row_mask:0xf bank_mask:0xf bound_ctrl:1
	s_nop 1
	v_add_f32_dpp v35, v35, v35 row_ror:4 row_mask:0xf bank_mask:0xf bound_ctrl:1
	s_nop 1
	v_add_f32_dpp v35, v35, v35 row_ror:8 row_mask:0xf bank_mask:0xf bound_ctrl:1
	v_mov_b32_e32 v51, v35
	s_nop 1
	v_permlane16_swap_b32_e32 v35, v51
	v_add_f32_e32 v35, v35, v51
	v_fmamk_f32 v35, v35, 0x3c800000, v208
	v_rsq_f32_e32 v35, v35
	v_lshlrev_b32_e32 v51, 16, v143
	v_mul_f32_e32 v32, v32, v35
	v_mul_f32_e32 v32, v224, v32
	v_mul_f32_e32 v16, v16, v35
	v_mul_f32_e32 v32, v32, v51
	v_mul_f32_e32 v16, v189, v16
	v_lshlrev_b32_e32 v35, 16, v144
	v_mul_f32_e32 v16, v16, v35
	v_cvt_pk_bf16_f32 v32, v32, s0
	global_store_short v[94:95], v32, off
	v_cvt_pk_bf16_f32 v16, v16, s0
	v_mov_b32_e32 v32, v15
	global_store_short v[94:95], v16, off offset:64
	v_mov_b32_e32 v16, v31
	v_permlane32_swap_b32_e32 v15, v32
	s_nop 0
	v_permlane32_swap_b32_e32 v31, v16
	v_cndmask_b32_e32 v15, v15, v32, vcc
	v_cndmask_b32_e32 v16, v31, v16, vcc
	v_add_f32_e32 v15, v36, v15
	v_add_f32_e32 v16, v52, v16
	v_mul_f32_e32 v31, v15, v15
	v_fmac_f32_e32 v31, v16, v16
	s_nop 1
	v_add_f32_dpp v31, v31, v31 quad_perm:[1,0,3,2] row_mask:0xf bank_mask:0xf bound_ctrl:1
	s_nop 1
	v_add_f32_dpp v31, v31, v31 quad_perm:[2,3,0,1] row_mask:0xf bank_mask:0xf bound_ctrl:1
	s_nop 1
	v_add_f32_dpp v31, v31, v31 row_ror:4 row_mask:0xf bank_mask:0xf bound_ctrl:1
	s_nop 1
	v_add_f32_dpp v31, v31, v31 row_ror:8 row_mask:0xf bank_mask:0xf bound_ctrl:1
	v_mov_b32_e32 v32, v31
	s_nop 1
	v_permlane16_swap_b32_e32 v31, v32
	v_add_f32_e32 v31, v31, v32
	v_fmamk_f32 v31, v31, 0x3c800000, v208
	v_rsq_f32_e32 v31, v31
	v_lshlrev_b32_e32 v32, 16, v145
	v_mul_f32_e32 v16, v16, v31
	v_mul_f32_e32 v16, v224, v16
	v_mul_f32_e32 v15, v15, v31
	v_mul_f32_e32 v16, v16, v32
	v_mul_f32_e32 v15, v189, v15
	v_lshlrev_b32_e32 v31, 16, v146
	v_mul_f32_e32 v15, v15, v31
	v_cvt_pk_bf16_f32 v16, v16, s0
	global_store_short v[92:93], v16, off
	v_cvt_pk_bf16_f32 v15, v15, s0
	v_mov_b32_e32 v16, v14
	global_store_short v[92:93], v15, off offset:64
	v_mov_b32_e32 v15, v30
	v_permlane32_swap_b32_e32 v14, v16
	s_nop 0
	v_permlane32_swap_b32_e32 v30, v15
	v_cndmask_b32_e32 v14, v14, v16, vcc
	v_cndmask_b32_e32 v15, v30, v15, vcc
	v_add_f32_e32 v14, v37, v14
	v_add_f32_e32 v15, v53, v15
	v_mul_f32_e32 v16, v14, v14
	v_fmac_f32_e32 v16, v15, v15
	s_nop 1
	v_add_f32_dpp v16, v16, v16 quad_perm:[1,0,3,2] row_mask:0xf bank_mask:0xf bound_ctrl:1
	s_nop 1
	v_add_f32_dpp v16, v16, v16 quad_perm:[2,3,0,1] row_mask:0xf bank_mask:0xf bound_ctrl:1
	s_nop 1
	v_add_f32_dpp v16, v16, v16 row_ror:4 row_mask:0xf bank_mask:0xf bound_ctrl:1
	s_nop 1
	v_add_f32_dpp v16, v16, v16 row_ror:8 row_mask:0xf bank_mask:0xf bound_ctrl:1
	v_mov_b32_e32 v30, v16
	s_nop 1
	v_permlane16_swap_b32_e32 v16, v30
	v_add_f32_e32 v16, v16, v30
	v_fmamk_f32 v16, v16, 0x3c800000, v208
	v_rsq_f32_e32 v16, v16
	v_lshlrev_b32_e32 v30, 16, v138
	v_mul_f32_e32 v15, v15, v16
	v_mul_f32_e32 v15, v224, v15
	v_mul_f32_e32 v14, v14, v16
	v_mul_f32_e32 v15, v15, v30
	v_mul_f32_e32 v14, v189, v14
	v_lshlrev_b32_e32 v16, 16, v137
	v_mul_f32_e32 v16, v14, v16
	v_cvt_pk_bf16_f32 v30, v15, s0
	v_lshlrev_b64 v[14:15], 11, v[90:91]
	v_lshl_add_u64 v[14:15], v[130:131], 0, v[14:15]
	v_cvt_pk_bf16_f32 v16, v16, s0
	global_store_short v[14:15], v30, off
	global_store_short v[14:15], v16, off offset:64
	v_mov_b32_e32 v15, v13
	v_mov_b32_e32 v14, v29
	s_nop 0
	v_permlane32_swap_b32_e32 v13, v15
	v_permlane32_swap_b32_e32 v29, v14
	v_cndmask_b32_e32 v13, v13, v15, vcc
	v_cndmask_b32_e32 v14, v29, v14, vcc
	v_add_f32_e32 v13, v38, v13
	v_add_f32_e32 v14, v54, v14
	v_mul_f32_e32 v15, v13, v13
	v_fmac_f32_e32 v15, v14, v14
	s_nop 1
	v_add_f32_dpp v15, v15, v15 quad_perm:[1,0,3,2] row_mask:0xf bank_mask:0xf bound_ctrl:1
	s_nop 1
	v_add_f32_dpp v15, v15, v15 quad_perm:[2,3,0,1] row_mask:0xf bank_mask:0xf bound_ctrl:1
	s_nop 1
	v_add_f32_dpp v15, v15, v15 row_ror:4 row_mask:0xf bank_mask:0xf bound_ctrl:1
	s_nop 1
	v_add_f32_dpp v15, v15, v15 row_ror:8 row_mask:0xf bank_mask:0xf bound_ctrl:1
	v_mov_b32_e32 v16, v15
	s_nop 1
	v_permlane16_swap_b32_e32 v15, v16
	v_add_f32_e32 v15, v15, v16
	v_fmamk_f32 v15, v15, 0x3c800000, v208
	v_rsq_f32_e32 v15, v15
	v_lshlrev_b32_e32 v16, 16, v136
	v_mul_f32_e32 v14, v14, v15
	v_mul_f32_e32 v14, v224, v14
	v_mul_f32_e32 v13, v13, v15
	v_mul_f32_e32 v14, v14, v16
	v_mul_f32_e32 v13, v189, v13
	v_lshlrev_b32_e32 v15, 16, v135
	v_mul_f32_e32 v13, v13, v15
	v_cvt_pk_bf16_f32 v16, v14, s0
	v_lshlrev_b64 v[14:15], 11, v[88:89]
	v_lshl_add_u64 v[14:15], v[130:131], 0, v[14:15]
	v_cvt_pk_bf16_f32 v13, v13, s0
	global_store_short v[14:15], v16, off
	global_store_short v[14:15], v13, off offset:64
	v_mov_b32_e32 v14, v12
	v_mov_b32_e32 v13, v28
	s_nop 0
	v_permlane32_swap_b32_e32 v12, v14
	v_permlane32_swap_b32_e32 v28, v13
	v_cndmask_b32_e32 v12, v12, v14, vcc
	v_cndmask_b32_e32 v13, v28, v13, vcc
	v_add_f32_e32 v12, v39, v12
	v_add_f32_e32 v13, v55, v13
	v_mul_f32_e32 v14, v12, v12
	v_fmac_f32_e32 v14, v13, v13
	s_nop 1
	v_add_f32_dpp v14, v14, v14 quad_perm:[1,0,3,2] row_mask:0xf bank_mask:0xf bound_ctrl:1
	s_nop 1
	v_add_f32_dpp v14, v14, v14 quad_perm:[2,3,0,1] row_mask:0xf bank_mask:0xf bound_ctrl:1
	s_nop 1
	v_add_f32_dpp v14, v14, v14 row_ror:4 row_mask:0xf bank_mask:0xf bound_ctrl:1
	s_nop 1
	v_add_f32_dpp v14, v14, v14 row_ror:8 row_mask:0xf bank_mask:0xf bound_ctrl:1
	v_mov_b32_e32 v15, v14
	s_nop 1
	v_permlane16_swap_b32_e32 v14, v15
	v_add_f32_e32 v14, v14, v15
	v_fmamk_f32 v14, v14, 0x3c800000, v208
	v_rsq_f32_e32 v14, v14
	v_lshlrev_b32_e32 v15, 16, v134
	v_mul_f32_e32 v13, v13, v14
	v_mul_f32_e32 v13, v224, v13
	v_mul_f32_e32 v12, v12, v14
	v_mul_f32_e32 v13, v13, v15
	v_mul_f32_e32 v12, v189, v12
	v_lshlrev_b32_e32 v14, 16, v133
	v_mul_f32_e32 v14, v12, v14
	v_cvt_pk_bf16_f32 v15, v13, s0
	v_lshlrev_b64 v[12:13], 11, v[86:87]
	v_lshl_add_u64 v[12:13], v[130:131], 0, v[12:13]
	v_cvt_pk_bf16_f32 v14, v14, s0
	global_store_short v[12:13], v15, off
	global_store_short v[12:13], v14, off offset:64
	v_mov_b32_e32 v13, v11
	v_mov_b32_e32 v12, v27
	s_nop 0
	v_permlane32_swap_b32_e32 v11, v13
	v_permlane32_swap_b32_e32 v27, v12
	v_cndmask_b32_e32 v11, v11, v13, vcc
	v_cndmask_b32_e32 v12, v27, v12, vcc
	v_add_f32_e32 v11, v40, v11
	v_add_f32_e32 v12, v56, v12
	v_mul_f32_e32 v13, v11, v11
	v_fmac_f32_e32 v13, v12, v12
	s_nop 1
	v_add_f32_dpp v13, v13, v13 quad_perm:[1,0,3,2] row_mask:0xf bank_mask:0xf bound_ctrl:1
	s_nop 1
	v_add_f32_dpp v13, v13, v13 quad_perm:[2,3,0,1] row_mask:0xf bank_mask:0xf bound_ctrl:1
	s_nop 1
	v_add_f32_dpp v13, v13, v13 row_ror:4 row_mask:0xf bank_mask:0xf bound_ctrl:1
	s_nop 1
	v_add_f32_dpp v13, v13, v13 row_ror:8 row_mask:0xf bank_mask:0xf bound_ctrl:1
	v_mov_b32_e32 v14, v13
	s_nop 1
	v_permlane16_swap_b32_e32 v13, v14
	v_add_f32_e32 v13, v13, v14
	v_fmamk_f32 v13, v13, 0x3c800000, v208
	v_rsq_f32_e32 v13, v13
	v_lshlrev_b32_e32 v14, 16, v132
	v_mul_f32_e32 v12, v12, v13
	v_mul_f32_e32 v12, v224, v12
	v_mul_f32_e32 v11, v11, v13
	v_mul_f32_e32 v12, v12, v14
	v_mul_f32_e32 v11, v189, v11
	v_lshlrev_b32_e32 v13, 16, v109
	v_mul_f32_e32 v11, v11, v13
	v_cvt_pk_bf16_f32 v14, v12, s0
	v_lshlrev_b64 v[12:13], 11, v[84:85]
	v_lshl_add_u64 v[12:13], v[130:131], 0, v[12:13]
	v_cvt_pk_bf16_f32 v11, v11, s0
	global_store_short v[12:13], v14, off
	global_store_short v[12:13], v11, off offset:64
	v_mov_b32_e32 v12, v10
	v_mov_b32_e32 v11, v26
	s_nop 0
	v_permlane32_swap_b32_e32 v10, v12
	v_permlane32_swap_b32_e32 v26, v11
	v_cndmask_b32_e32 v10, v10, v12, vcc
	v_cndmask_b32_e32 v11, v26, v11, vcc
	v_add_f32_e32 v10, v41, v10
	v_add_f32_e32 v11, v57, v11
	v_mul_f32_e32 v12, v10, v10
	v_fmac_f32_e32 v12, v11, v11
	s_nop 1
	v_add_f32_dpp v12, v12, v12 quad_perm:[1,0,3,2] row_mask:0xf bank_mask:0xf bound_ctrl:1
	s_nop 1
	v_add_f32_dpp v12, v12, v12 quad_perm:[2,3,0,1] row_mask:0xf bank_mask:0xf bound_ctrl:1
	s_nop 1
	v_add_f32_dpp v12, v12, v12 row_ror:4 row_mask:0xf bank_mask:0xf bound_ctrl:1
	s_nop 1
	v_add_f32_dpp v12, v12, v12 row_ror:8 row_mask:0xf bank_mask:0xf bound_ctrl:1
	v_mov_b32_e32 v13, v12
	s_nop 1
	v_permlane16_swap_b32_e32 v12, v13
	v_add_f32_e32 v12, v12, v13
	v_fmamk_f32 v12, v12, 0x3c800000, v208
	v_rsq_f32_e32 v12, v12
	v_lshlrev_b32_e32 v13, 16, v108
	v_mul_f32_e32 v11, v11, v12
	v_mul_f32_e32 v11, v224, v11
	v_mul_f32_e32 v10, v10, v12
	v_mul_f32_e32 v11, v11, v13
	v_mul_f32_e32 v10, v189, v10
	v_lshlrev_b32_e32 v12, 16, v107
	v_mul_f32_e32 v12, v10, v12
	v_cvt_pk_bf16_f32 v13, v11, s0
	v_lshlrev_b64 v[10:11], 11, v[82:83]
	v_lshl_add_u64 v[10:11], v[130:131], 0, v[10:11]
	v_cvt_pk_bf16_f32 v12, v12, s0
	global_store_short v[10:11], v13, off
	global_store_short v[10:11], v12, off offset:64
	v_mov_b32_e32 v11, v9
	v_mov_b32_e32 v10, v25
	s_nop 0
	v_permlane32_swap_b32_e32 v9, v11
	v_permlane32_swap_b32_e32 v25, v10
	v_cndmask_b32_e32 v9, v9, v11, vcc
	v_cndmask_b32_e32 v10, v25, v10, vcc
	v_add_f32_e32 v9, v42, v9
	v_add_f32_e32 v10, v58, v10
	v_mul_f32_e32 v11, v9, v9
	v_fmac_f32_e32 v11, v10, v10
	s_nop 1
	v_add_f32_dpp v11, v11, v11 quad_perm:[1,0,3,2] row_mask:0xf bank_mask:0xf bound_ctrl:1
	s_nop 1
	v_add_f32_dpp v11, v11, v11 quad_perm:[2,3,0,1] row_mask:0xf bank_mask:0xf bound_ctrl:1
	s_nop 1
	v_add_f32_dpp v11, v11, v11 row_ror:4 row_mask:0xf bank_mask:0xf bound_ctrl:1
	s_nop 1
	v_add_f32_dpp v11, v11, v11 row_ror:8 row_mask:0xf bank_mask:0xf bound_ctrl:1
	v_mov_b32_e32 v12, v11
	s_nop 1
	v_permlane16_swap_b32_e32 v11, v12
	v_add_f32_e32 v11, v11, v12
	v_fmamk_f32 v11, v11, 0x3c800000, v208
	v_rsq_f32_e32 v11, v11
	v_lshlrev_b32_e32 v12, 16, v106
	v_mul_f32_e32 v10, v10, v11
	v_mul_f32_e32 v10, v224, v10
	v_mul_f32_e32 v9, v9, v11
	v_mul_f32_e32 v10, v10, v12
	v_mul_f32_e32 v9, v189, v9
	v_lshlrev_b32_e32 v11, 16, v105
	v_mul_f32_e32 v9, v9, v11
	v_cvt_pk_bf16_f32 v12, v10, s0
	v_lshlrev_b64 v[10:11], 11, v[80:81]
	v_lshl_add_u64 v[10:11], v[130:131], 0, v[10:11]
	v_cvt_pk_bf16_f32 v9, v9, s0
	global_store_short v[10:11], v12, off
	global_store_short v[10:11], v9, off offset:64
	v_mov_b32_e32 v10, v8
	v_mov_b32_e32 v9, v24
	s_nop 0
	v_permlane32_swap_b32_e32 v8, v10
	v_permlane32_swap_b32_e32 v24, v9
	v_cndmask_b32_e32 v8, v8, v10, vcc
	v_cndmask_b32_e32 v9, v24, v9, vcc
	v_add_f32_e32 v8, v43, v8
	v_add_f32_e32 v9, v59, v9
	v_mul_f32_e32 v10, v8, v8
	v_fmac_f32_e32 v10, v9, v9
	s_nop 1
	v_add_f32_dpp v10, v10, v10 quad_perm:[1,0,3,2] row_mask:0xf bank_mask:0xf bound_ctrl:1
	s_nop 1
	v_add_f32_dpp v10, v10, v10 quad_perm:[2,3,0,1] row_mask:0xf bank_mask:0xf bound_ctrl:1
	s_nop 1
	v_add_f32_dpp v10, v10, v10 row_ror:4 row_mask:0xf bank_mask:0xf bound_ctrl:1
	s_nop 1
	v_add_f32_dpp v10, v10, v10 row_ror:8 row_mask:0xf bank_mask:0xf bound_ctrl:1
	v_mov_b32_e32 v11, v10
	s_nop 1
	v_permlane16_swap_b32_e32 v10, v11
	v_add_f32_e32 v10, v10, v11
	v_fmamk_f32 v10, v10, 0x3c800000, v208
	v_rsq_f32_e32 v10, v10
	v_lshlrev_b32_e32 v11, 16, v104
	v_mul_f32_e32 v9, v9, v10
	v_mul_f32_e32 v9, v224, v9
	v_mul_f32_e32 v8, v8, v10
	v_mul_f32_e32 v9, v9, v11
	v_mul_f32_e32 v8, v189, v8
	v_lshlrev_b32_e32 v10, 16, v103
	v_mul_f32_e32 v10, v8, v10
	v_cvt_pk_bf16_f32 v11, v9, s0
	v_lshlrev_b64 v[8:9], 11, v[78:79]
	v_lshl_add_u64 v[8:9], v[130:131], 0, v[8:9]
	v_cvt_pk_bf16_f32 v10, v10, s0
	global_store_short v[8:9], v11, off
	global_store_short v[8:9], v10, off offset:64
	v_mov_b32_e32 v9, v7
	v_mov_b32_e32 v8, v23
	s_nop 0
	v_permlane32_swap_b32_e32 v7, v9
	v_permlane32_swap_b32_e32 v23, v8
	v_cndmask_b32_e32 v7, v7, v9, vcc
	v_cndmask_b32_e32 v8, v23, v8, vcc
	v_add_f32_e32 v7, v44, v7
	v_add_f32_e32 v8, v60, v8
	v_mul_f32_e32 v9, v7, v7
	v_fmac_f32_e32 v9, v8, v8
	s_nop 1
	v_add_f32_dpp v9, v9, v9 quad_perm:[1,0,3,2] row_mask:0xf bank_mask:0xf bound_ctrl:1
	s_nop 1
	v_add_f32_dpp v9, v9, v9 quad_perm:[2,3,0,1] row_mask:0xf bank_mask:0xf bound_ctrl:1
	s_nop 1
	v_add_f32_dpp v9, v9, v9 row_ror:4 row_mask:0xf bank_mask:0xf bound_ctrl:1
	s_nop 1
	v_add_f32_dpp v9, v9, v9 row_ror:8 row_mask:0xf bank_mask:0xf bound_ctrl:1
	v_mov_b32_e32 v10, v9
	s_nop 1
	v_permlane16_swap_b32_e32 v9, v10
	v_add_f32_e32 v9, v9, v10
	v_fmamk_f32 v9, v9, 0x3c800000, v208
	v_rsq_f32_e32 v9, v9
	v_lshlrev_b32_e32 v10, 16, v102
	v_mul_f32_e32 v8, v8, v9
	v_mul_f32_e32 v8, v224, v8
	v_mul_f32_e32 v7, v7, v9
	v_mul_f32_e32 v8, v8, v10
	v_mul_f32_e32 v7, v189, v7
	v_lshlrev_b32_e32 v9, 16, v101
	v_mul_f32_e32 v7, v7, v9
	v_cvt_pk_bf16_f32 v10, v8, s0
	v_lshlrev_b64 v[8:9], 11, v[76:77]
	v_lshl_add_u64 v[8:9], v[130:131], 0, v[8:9]
	v_cvt_pk_bf16_f32 v7, v7, s0
	global_store_short v[8:9], v10, off
	global_store_short v[8:9], v7, off offset:64
	v_mov_b32_e32 v8, v6
	v_mov_b32_e32 v7, v22
	s_nop 0
	v_permlane32_swap_b32_e32 v6, v8
	v_permlane32_swap_b32_e32 v22, v7
	v_cndmask_b32_e32 v6, v6, v8, vcc
	v_cndmask_b32_e32 v7, v22, v7, vcc
	v_add_f32_e32 v6, v45, v6
	v_add_f32_e32 v7, v61, v7
	v_mul_f32_e32 v8, v6, v6
	v_fmac_f32_e32 v8, v7, v7
	s_nop 1
	v_add_f32_dpp v8, v8, v8 quad_perm:[1,0,3,2] row_mask:0xf bank_mask:0xf bound_ctrl:1
	s_nop 1
	v_add_f32_dpp v8, v8, v8 quad_perm:[2,3,0,1] row_mask:0xf bank_mask:0xf bound_ctrl:1
	s_nop 1
	v_add_f32_dpp v8, v8, v8 row_ror:4 row_mask:0xf bank_mask:0xf bound_ctrl:1
	s_nop 1
	v_add_f32_dpp v8, v8, v8 row_ror:8 row_mask:0xf bank_mask:0xf bound_ctrl:1
	v_mov_b32_e32 v9, v8
	s_nop 1
	v_permlane16_swap_b32_e32 v8, v9
	v_add_f32_e32 v8, v8, v9
	v_fmamk_f32 v8, v8, 0x3c800000, v208
	v_rsq_f32_e32 v8, v8
	v_lshlrev_b32_e32 v9, 16, v100
	v_mul_f32_e32 v7, v7, v8
	v_mul_f32_e32 v7, v224, v7
	v_mul_f32_e32 v6, v6, v8
	v_mul_f32_e32 v7, v7, v9
	v_mul_f32_e32 v6, v189, v6
	v_lshlrev_b32_e32 v8, 16, v99
	v_mul_f32_e32 v8, v6, v8
	v_cvt_pk_bf16_f32 v9, v7, s0
	v_lshlrev_b64 v[6:7], 11, v[74:75]
	v_lshl_add_u64 v[6:7], v[130:131], 0, v[6:7]
	v_cvt_pk_bf16_f32 v8, v8, s0
	global_store_short v[6:7], v9, off
	global_store_short v[6:7], v8, off offset:64
	v_mov_b32_e32 v7, v5
	v_mov_b32_e32 v6, v21
	s_nop 0
	v_permlane32_swap_b32_e32 v5, v7
	v_permlane32_swap_b32_e32 v21, v6
	v_cndmask_b32_e32 v5, v5, v7, vcc
	v_cndmask_b32_e32 v6, v21, v6, vcc
	v_add_f32_e32 v5, v46, v5
	v_add_f32_e32 v6, v62, v6
	v_mul_f32_e32 v7, v5, v5
	v_fmac_f32_e32 v7, v6, v6
	s_nop 1
	v_add_f32_dpp v7, v7, v7 quad_perm:[1,0,3,2] row_mask:0xf bank_mask:0xf bound_ctrl:1
	s_nop 1
	v_add_f32_dpp v7, v7, v7 quad_perm:[2,3,0,1] row_mask:0xf bank_mask:0xf bound_ctrl:1
	s_nop 1
	v_add_f32_dpp v7, v7, v7 row_ror:4 row_mask:0xf bank_mask:0xf bound_ctrl:1
	s_nop 1
	v_add_f32_dpp v7, v7, v7 row_ror:8 row_mask:0xf bank_mask:0xf bound_ctrl:1
	v_mov_b32_e32 v8, v7
	s_nop 1
	v_permlane16_swap_b32_e32 v7, v8
	v_add_f32_e32 v7, v7, v8
	v_fmamk_f32 v7, v7, 0x3c800000, v208
	v_rsq_f32_e32 v7, v7
	v_lshlrev_b32_e32 v8, 16, v98
	v_mul_f32_e32 v6, v6, v7
	v_mul_f32_e32 v6, v224, v6
	v_mul_f32_e32 v5, v5, v7
	v_mul_f32_e32 v6, v6, v8
	v_mul_f32_e32 v5, v189, v5
	v_lshlrev_b32_e32 v7, 16, v97
	v_mul_f32_e32 v5, v5, v7
	v_cvt_pk_bf16_f32 v8, v6, s0
	v_lshlrev_b64 v[6:7], 11, v[72:73]
	v_lshl_add_u64 v[6:7], v[130:131], 0, v[6:7]
	v_cvt_pk_bf16_f32 v5, v5, s0
	global_store_short v[6:7], v8, off
	global_store_short v[6:7], v5, off offset:64
	v_mov_b32_e32 v6, v4
	v_mov_b32_e32 v5, v20
	s_nop 0
	v_permlane32_swap_b32_e32 v4, v6
	v_permlane32_swap_b32_e32 v20, v5
	v_cndmask_b32_e32 v4, v4, v6, vcc
	v_cndmask_b32_e32 v5, v20, v5, vcc
	v_add_f32_e32 v4, v47, v4
	v_add_f32_e32 v5, v63, v5
	v_mul_f32_e32 v6, v4, v4
	v_fmac_f32_e32 v6, v5, v5
	s_nop 1
	v_add_f32_dpp v6, v6, v6 quad_perm:[1,0,3,2] row_mask:0xf bank_mask:0xf bound_ctrl:1
	s_nop 1
	v_add_f32_dpp v6, v6, v6 quad_perm:[2,3,0,1] row_mask:0xf bank_mask:0xf bound_ctrl:1
	s_nop 1
	v_add_f32_dpp v6, v6, v6 row_ror:4 row_mask:0xf bank_mask:0xf bound_ctrl:1
	s_nop 1
	v_add_f32_dpp v6, v6, v6 row_ror:8 row_mask:0xf bank_mask:0xf bound_ctrl:1
	v_mov_b32_e32 v7, v6
	s_nop 1
	v_permlane16_swap_b32_e32 v6, v7
	v_add_f32_e32 v6, v6, v7
	v_fmamk_f32 v6, v6, 0x3c800000, v208
	v_rsq_f32_e32 v6, v6
	v_lshlrev_b32_e32 v7, 16, v96
	v_mul_f32_e32 v5, v5, v6
	v_mul_f32_e32 v5, v224, v5
	v_mul_f32_e32 v4, v4, v6
	v_mul_f32_e32 v5, v5, v7
	v_mul_f32_e32 v4, v189, v4
	v_lshlrev_b32_e32 v6, 16, v50
	v_mul_f32_e32 v6, v4, v6
	v_cvt_pk_bf16_f32 v7, v5, s0
	v_lshlrev_b64 v[4:5], 11, v[70:71]
	v_lshl_add_u64 v[4:5], v[130:131], 0, v[4:5]
	v_cvt_pk_bf16_f32 v6, v6, s0
	global_store_short v[4:5], v7, off
	global_store_short v[4:5], v6, off offset:64
	v_mov_b32_e32 v5, v3
	v_mov_b32_e32 v4, v19
	s_nop 0
	v_permlane32_swap_b32_e32 v3, v5
	v_permlane32_swap_b32_e32 v19, v4
	v_cndmask_b32_e32 v3, v3, v5, vcc
	v_cndmask_b32_e32 v4, v19, v4, vcc
	v_add_f32_e32 v3, v48, v3
	v_add_f32_e32 v4, v64, v4
	v_mul_f32_e32 v5, v3, v3
	v_fmac_f32_e32 v5, v4, v4
	s_nop 1
	v_add_f32_dpp v5, v5, v5 quad_perm:[1,0,3,2] row_mask:0xf bank_mask:0xf bound_ctrl:1
	s_nop 1
	v_add_f32_dpp v5, v5, v5 quad_perm:[2,3,0,1] row_mask:0xf bank_mask:0xf bound_ctrl:1
	s_nop 1
	v_add_f32_dpp v5, v5, v5 row_ror:4 row_mask:0xf bank_mask:0xf bound_ctrl:1
	s_nop 1
	v_add_f32_dpp v5, v5, v5 row_ror:8 row_mask:0xf bank_mask:0xf bound_ctrl:1
	v_mov_b32_e32 v6, v5
	s_nop 1
	v_permlane16_swap_b32_e32 v5, v6
	v_add_f32_e32 v5, v5, v6
	v_fmamk_f32 v5, v5, 0x3c800000, v208
	v_rsq_f32_e32 v5, v5
	v_lshlrev_b32_e32 v6, 16, v34
	v_mul_f32_e32 v4, v4, v5
	v_mul_f32_e32 v4, v224, v4
	v_mul_f32_e32 v3, v3, v5
	v_mul_f32_e32 v4, v4, v6
	v_mul_f32_e32 v3, v189, v3
	v_lshlrev_b32_e32 v5, 16, v33
	v_mul_f32_e32 v3, v3, v5
	v_cvt_pk_bf16_f32 v6, v4, s0
	v_lshlrev_b64 v[4:5], 11, v[68:69]
	v_lshl_add_u64 v[4:5], v[130:131], 0, v[4:5]
	v_cvt_pk_bf16_f32 v3, v3, s0
	global_store_short v[4:5], v3, off offset:64
	v_mov_b32_e32 v3, v2
	global_store_short v[4:5], v6, off
	v_mov_b32_e32 v4, v18
	v_permlane32_swap_b32_e32 v2, v3
	s_nop 0
	v_permlane32_swap_b32_e32 v18, v4
	v_cndmask_b32_e32 v2, v2, v3, vcc
	v_cndmask_b32_e32 v4, v18, v4, vcc
	v_add_f32_e32 v2, v49, v2
	v_add_f32_e32 v4, v65, v4
	v_mul_f32_e32 v3, v2, v2
	v_fmac_f32_e32 v3, v4, v4
	s_nop 1
	v_add_f32_dpp v3, v3, v3 quad_perm:[1,0,3,2] row_mask:0xf bank_mask:0xf bound_ctrl:1
	s_nop 1
	v_add_f32_dpp v3, v3, v3 quad_perm:[2,3,0,1] row_mask:0xf bank_mask:0xf bound_ctrl:1
	s_nop 1
	v_add_f32_dpp v3, v3, v3 row_ror:4 row_mask:0xf bank_mask:0xf bound_ctrl:1
	s_nop 1
	v_add_f32_dpp v3, v3, v3 row_ror:8 row_mask:0xf bank_mask:0xf bound_ctrl:1
	v_mov_b32_e32 v5, v3
	s_nop 1
	v_permlane16_swap_b32_e32 v3, v5
	v_add_f32_e32 v3, v3, v5
	v_fmamk_f32 v3, v3, 0x3c800000, v208
	v_rsq_f32_e32 v3, v3
	v_lshlrev_b32_e32 v5, 16, v17
	v_mul_f32_e32 v4, v4, v3
	v_mul_f32_e32 v4, v224, v4
	v_mul_f32_e32 v2, v2, v3
	v_mul_f32_e32 v4, v4, v5
	v_mul_f32_e32 v2, v189, v2
	v_mul_f32_e32 v0, v2, v0
	v_cvt_pk_bf16_f32 v2, v4, s0
	v_lshlrev_b64 v[4:5], 11, v[66:67]
	v_lshl_add_u64 v[4:5], v[130:131], 0, v[4:5]
	v_cvt_pk_bf16_f32 v0, v0, s0
	global_store_short v[4:5], v2, off
	global_store_short v[4:5], v0, off offset:64
	s_cbranch_scc1 .LBB0_590
	s_mov_b32 s76, 0x5a000
	s_movk_i32 s46, 0xffd0
	s_movk_i32 s50, 0xffc0
	s_mov_b32 s51, 0x41000000
	s_mov_b64 s[48:49], 0xca00100
	v_readlane_b32 s88, v254, 50
	v_readlane_b32 s89, v254, 51
